# one static s_setprio 1 for waves 4-7 (the lagging half) per K-loop instead of hipcc's per-phase priority flips; on top of v64
# baseline (speedup 1.0000x reference)
; #define PG8_STAGE(bufoff, gbase, voff) do { _Pragma("unroll") for (int _i = 0; _i < 2; ++_i) \
;         __builtin_amdgcn_global_load_lds((const unsigned*)((const char*)(gbase) + (voff)[_i]), (PG8_LAS unsigned*)(lds + (bufoff) + ldsw + _i * 8192), 16, 0, 0); } while (0)
; #define PG8_LDA(dst, b, h) do { _Pragma("unroll") for (int m = 0; m < 4; ++m) _Pragma("unroll") for (int k = 0; k < 2; ++k) dst[m][k] = *(const PG8_LAS bf16x8*)(lds + PG8_SA(b, h) + aoff + m * 2048 + k * 1024); } while (0)
; #define PG8_LDB(dst, b, h) do { _Pragma("unroll") for (int n = 0; n < 2; ++n) _Pragma("unroll") for (int k = 0; k < 2; ++k) dst[n][k] = *(const PG8_LAS bf16x8*)(lds + PG8_SB(b, h) + boff + n * 2048 + k * 1024); } while (0)
; #define PG8_WAIT_V(n) asm volatile("s_waitcnt vmcnt(" #n ")" ::: "memory")
; #define PG8_WAIT_L(n) asm volatile("s_waitcnt lgkmcnt(" #n ")" ::: "memory")
; #define PG8_BAR __builtin_amdgcn_s_barrier()
; template <class Epi, bool ALIGN_EPI, bool ABLK = false>
; __device__ __forceinline__ void gemm_phase(PG8_LAS unsigned char* lds, const Gemm g, const StaticOrder& S, const Epi& E) {
;     ...
;         const bool has_next = S.next(ui + 1, nxt);
;         const char* nA = has_next ? PG8_ABASE(nxt) : cA; const char* nB = has_next ? PG8_BBASE(nxt) : cB;
;         for (int t = 0; t < nt; t += 2) {
;             const bool last = (t == nt - 2);
;             const char* a1 = cA + (size_t)(t + 1) * kstepA;
;             const char* a2 = last ? nA : cA + (size_t)(t + 2) * kstepA; const char* b2 = last ? nB : cB + (size_t)(t + 2) * kstepB;
;             const char* a3 = a2 + kstepA; const char* b3 = b2 + kstepB;
;             PG8_LDB(B0, 0, 0); PG8_LDB(B1, 0, 1); PG8_SCHED; PG8_LDA(At, 0, 0); PG8_STAGE(PG8_SA(1, 1), a1 + hstepA, voffA);
;             PG8_WAIT_V(8); PG8_WAIT_L(0); PG8_BAR; PG8_MMA(0, 0, At, B0); PG8_MMA(0, 1, At, B1); PG8_BAR; PG8_SCHED;
;             PG8_LDA(At, 0, 1); PG8_STAGE(PG8_SB(0, 0), b2, voffB); PG8_STAGE(PG8_SB(0, 1), b2 + hstepB, voffB); PG8_STAGE(PG8_SA(0, 0), a2, voffA);
;             PG8_WAIT_V(8); PG8_WAIT_L(0); PG8_BAR; PG8_MMA(1, 0, At, B0); PG8_MMA(1, 1, At, B1); PG8_BAR; PG8_SCHED;
;             PG8_LDB(B0, 1, 0); PG8_LDB(B1, 1, 1); PG8_SCHED; PG8_LDA(At, 1, 0); PG8_STAGE(PG8_SA(0, 1), a2 + hstepA, voffA);
;             PG8_WAIT_V(8); PG8_WAIT_L(0); PG8_BAR; PG8_MMA(0, 0, At, B0); PG8_MMA(0, 1, At, B1); PG8_BAR; PG8_SCHED;
.LBB0_401:
	s_ashr_i32 s41, s40, 31
	s_lshl_b64 s[42:43], s[40:41], 19
	s_add_u32 s42, s11, s42
	s_addc_u32 s43, s54, s43
	s_and_b64 s[44:45], s[6:7], exec
	s_cselect_b32 s41, s43, s25
	s_cselect_b32 s66, s42, s24
	s_ashr_i32 s39, s38, 31
	s_lshl_b64 s[44:45], s[38:39], 19
	s_add_u32 s44, s12, s44
	s_addc_u32 s45, s13, s45
	s_and_b64 s[46:47], s[6:7], exec
	s_cselect_b32 s39, s45, s23
	s_cselect_b32 s67, s44, s22
	s_add_u32 s68, s22, 0x100
	s_addc_u32 s69, s23, 0
	s_mov_b32 s70, -2
	s_mov_b64 s[46:47], 0x10000
	s_mov_b64 s[82:83], s[24:25]
	s_setprio 0
	v_readfirstlane_b32 s101, v0
	s_nop 3
	s_bfe_u32 s101, s101, 0x40006
	s_cmp_ge_u32 s101, 4
	s_cbranch_scc0 .Lprio_402
	s_setprio 1
.Lprio_402:
.LBB0_402:
	ds_read_b128 v[132:135], v251
	ds_read_b128 v[136:139], v251 offset:1024
	ds_read_b128 v[140:143], v251 offset:2048
	ds_read_b128 v[186:189], v251 offset:3072
	ds_read_b128 v[190:193], v251 offset:16384
	ds_read_b128 v[194:197], v251 offset:17408
	ds_read_b128 v[198:201], v251 offset:18432
	ds_read_b128 v[202:205], v251 offset:19456
	s_add_u32 s48, s24, s46
	s_addc_u32 s49, s25, s47
	s_cmp_eq_u32 s70, 12
	s_cselect_b32 s85, s41, s49
	s_cselect_b32 s84, s66, s48
	s_cselect_b32 s49, s39, s69
	s_cselect_b32 s48, s67, s68
	s_mov_b64 s[74:75], 0xc000
	s_add_i32 m0, s55, 0xc000
	s_mov_b64 s[74:75], 0xe000
	ds_read_b128 v[206:209], v183
	ds_read_b128 v[210:213], v183 offset:1024
	ds_read_b128 v[214:217], v183 offset:2048
	ds_read_b128 v[218:221], v183 offset:3072
	ds_read_b128 v[222:225], v183 offset:4096
	ds_read_b128 v[226:229], v183 offset:5120
	ds_read_b128 v[230:233], v183 offset:6144
	ds_read_b128 v[234:237], v183 offset:7168
	global_load_lds_dwordx4 v249, s[82:83]
	s_add_i32 m0, s55, 0xe000
	s_nop 0
	global_load_lds_dwordx4 v250, s[82:83]
	s_waitcnt vmcnt(8)
	s_waitcnt lgkmcnt(0)
	s_barrier
	s_waitcnt lgkmcnt(0)
	v_mfma_f32_16x16x32_bf16 v[126:129], v[132:135], v[206:209], v[126:129]
	v_mfma_f32_16x16x32_bf16 v[122:125], v[140:143], v[206:209], v[122:125]
	v_mfma_f32_16x16x32_bf16 v[118:121], v[132:135], v[214:217], v[118:121]
	v_mfma_f32_16x16x32_bf16 v[114:117], v[140:143], v[214:217], v[114:117]
	v_mfma_f32_16x16x32_bf16 v[110:113], v[132:135], v[222:225], v[110:113]
	v_mfma_f32_16x16x32_bf16 v[106:109], v[140:143], v[222:225], v[106:109]
	v_mfma_f32_16x16x32_bf16 v[102:105], v[132:135], v[230:233], v[102:105]
	v_mfma_f32_16x16x32_bf16 v[98:101], v[140:143], v[230:233], v[98:101]
	v_mfma_f32_16x16x32_bf16 v[126:129], v[136:139], v[210:213], v[126:129]
	v_mfma_f32_16x16x32_bf16 v[122:125], v[186:189], v[210:213], v[122:125]
	v_mfma_f32_16x16x32_bf16 v[118:121], v[136:139], v[218:221], v[118:121]
	v_mfma_f32_16x16x32_bf16 v[114:117], v[186:189], v[218:221], v[114:117]
	v_mfma_f32_16x16x32_bf16 v[110:113], v[136:139], v[226:229], v[110:113]
	v_mfma_f32_16x16x32_bf16 v[106:109], v[186:189], v[226:229], v[106:109]
	v_mfma_f32_16x16x32_bf16 v[102:105], v[136:139], v[234:237], v[102:105]
	v_mfma_f32_16x16x32_bf16 v[98:101], v[186:189], v[234:237], v[98:101]
	v_mfma_f32_16x16x32_bf16 v[94:97], v[190:193], v[206:209], v[94:97]
	s_add_i32 s71, s64, s9
	v_mfma_f32_16x16x32_bf16 v[90:93], v[198:201], v[206:209], v[90:93]
	s_mov_b32 m0, s71
	v_mfma_f32_16x16x32_bf16 v[86:89], v[190:193], v[214:217], v[86:89]
	v_mfma_f32_16x16x32_bf16 v[82:85], v[198:201], v[214:217], v[82:85]
	v_mfma_f32_16x16x32_bf16 v[78:81], v[190:193], v[222:225], v[78:81]
	v_mfma_f32_16x16x32_bf16 v[74:77], v[198:201], v[222:225], v[74:77]
	v_mfma_f32_16x16x32_bf16 v[70:73], v[190:193], v[230:233], v[70:73]
	v_mfma_f32_16x16x32_bf16 v[66:69], v[198:201], v[230:233], v[66:69]
	v_mfma_f32_16x16x32_bf16 v[94:97], v[194:197], v[210:213], v[94:97]
	v_mfma_f32_16x16x32_bf16 v[90:93], v[202:205], v[210:213], v[90:93]
	v_mfma_f32_16x16x32_bf16 v[86:89], v[194:197], v[218:221], v[86:89]
	v_mfma_f32_16x16x32_bf16 v[82:85], v[202:205], v[218:221], v[82:85]
	v_mfma_f32_16x16x32_bf16 v[78:81], v[194:197], v[226:229], v[78:81]
	v_mfma_f32_16x16x32_bf16 v[74:77], v[202:205], v[226:229], v[74:77]
	v_mfma_f32_16x16x32_bf16 v[70:73], v[194:197], v[234:237], v[70:73]
	v_mfma_f32_16x16x32_bf16 v[66:69], v[202:205], v[234:237], v[66:69]
	s_barrier
	ds_read_b128 v[206:209], v183 offset:16384
	ds_read_b128 v[210:213], v183 offset:17408
	ds_read_b128 v[214:217], v183 offset:18432
	ds_read_b128 v[218:221], v183 offset:19456
	ds_read_b128 v[222:225], v183 offset:20480
	ds_read_b128 v[226:229], v183 offset:21504
	ds_read_b128 v[230:233], v183 offset:22528
	ds_read_b128 v[234:237], v183 offset:23552
	global_load_lds_dwordx4 v148, s[48:49]
	s_add_i32 m0, s71, 0x2000
	s_add_u32 s74, s48, 0x40000
	s_addc_u32 s75, s49, 0
	s_add_i32 s71, s65, s9
	global_load_lds_dwordx4 v150, s[48:49]
	s_mov_b32 m0, s71
	s_nop 0
	global_load_lds_dwordx4 v148, s[74:75]
	s_add_i32 m0, s71, 0x2000
	s_nop 0
	global_load_lds_dwordx4 v150, s[74:75]
	s_mov_b32 m0, s55
	s_mov_b64 s[72:73], 0x2000
	global_load_lds_dwordx4 v146, s[84:85]
	s_mov_b32 m0, s56
	s_nop 0
	global_load_lds_dwordx4 v244, s[84:85]
	s_waitcnt vmcnt(8)
	s_waitcnt lgkmcnt(0)
	s_barrier
; #define PG8_STAGE(bufoff, gbase, voff) do { _Pragma("unroll") for (int _i = 0; _i < 2; ++_i) \
;         __builtin_amdgcn_global_load_lds((const unsigned*)((const char*)(gbase) + (voff)[_i]), (PG8_LAS unsigned*)(lds + (bufoff) + ldsw + _i * 8192), 16, 0, 0); } while (0)
; #define PG8_LDA(dst, b, h) do { _Pragma("unroll") for (int m = 0; m < 4; ++m) _Pragma("unroll") for (int k = 0; k < 2; ++k) dst[m][k] = *(const PG8_LAS bf16x8*)(lds + PG8_SA(b, h) + aoff + m * 2048 + k * 1024); } while (0)
; #define PG8_LDB(dst, b, h) do { _Pragma("unroll") for (int n = 0; n < 2; ++n) _Pragma("unroll") for (int k = 0; k < 2; ++k) dst[n][k] = *(const PG8_LAS bf16x8*)(lds + PG8_SB(b, h) + boff + n * 2048 + k * 1024); } while (0)
; #define PG8_MMA(ai, bj, At, Bt) do { __builtin_amdgcn_s_setprio(1); _Pragma("unroll") for (int m = 0; m < 4; ++m) _Pragma("unroll") for (int n = 0; n < 2; ++n) _Pragma("unroll") for (int k = 0; k < 2; ++k) \
;         acc[ai][bj][m][n] = __builtin_amdgcn_mfma_f32_16x16x32_bf16(Bt[n][k], At[m][k], acc[ai][bj][m][n], 0, 0, 0); __builtin_amdgcn_s_setprio(0); } while (0)
; #define PG8_WAIT_V(n) asm volatile("s_waitcnt vmcnt(" #n ")" ::: "memory")
; #define PG8_WAIT_L(n) asm volatile("s_waitcnt lgkmcnt(" #n ")" ::: "memory")
; #define PG8_BAR __builtin_amdgcn_s_barrier()
; #define PG8_SCHED __builtin_amdgcn_sched_barrier(0)
; template <class Epi, bool ALIGN_EPI, bool ABLK = false>
; __device__ __forceinline__ void gemm_phase(PG8_LAS unsigned char* lds, const Gemm g, const StaticOrder& S, const Epi& E) {
;     ...
;             PG8_WAIT_V(8); PG8_WAIT_L(0); PG8_BAR; PG8_MMA(1, 0, At, B0); PG8_MMA(1, 1, At, B1); PG8_BAR; PG8_SCHED;
;             PG8_LDB(B0, 1, 0); PG8_LDB(B1, 1, 1); PG8_SCHED; PG8_LDA(At, 1, 0); PG8_STAGE(PG8_SA(0, 1), a2 + hstepA, voffA);
;             PG8_WAIT_V(8); PG8_WAIT_L(0); PG8_BAR; PG8_MMA(0, 0, At, B0); PG8_MMA(0, 1, At, B1); PG8_BAR; PG8_SCHED;
	s_waitcnt lgkmcnt(0)
	v_mfma_f32_16x16x32_bf16 v[62:65], v[132:135], v[206:209], v[62:65]
	v_mfma_f32_16x16x32_bf16 v[58:61], v[140:143], v[206:209], v[58:61]
	v_mfma_f32_16x16x32_bf16 v[54:57], v[132:135], v[214:217], v[54:57]
	v_mfma_f32_16x16x32_bf16 v[50:53], v[140:143], v[214:217], v[50:53]
	v_mfma_f32_16x16x32_bf16 v[46:49], v[132:135], v[222:225], v[46:49]
	v_mfma_f32_16x16x32_bf16 v[42:45], v[140:143], v[222:225], v[42:45]
	v_mfma_f32_16x16x32_bf16 v[38:41], v[132:135], v[230:233], v[38:41]
	v_mfma_f32_16x16x32_bf16 v[34:37], v[140:143], v[230:233], v[34:37]
	v_mfma_f32_16x16x32_bf16 v[62:65], v[136:139], v[210:213], v[62:65]
	v_mfma_f32_16x16x32_bf16 v[58:61], v[186:189], v[210:213], v[58:61]
	v_mfma_f32_16x16x32_bf16 v[54:57], v[136:139], v[218:221], v[54:57]
	v_mfma_f32_16x16x32_bf16 v[50:53], v[186:189], v[218:221], v[50:53]
	v_mfma_f32_16x16x32_bf16 v[46:49], v[136:139], v[226:229], v[46:49]
	v_mfma_f32_16x16x32_bf16 v[42:45], v[186:189], v[226:229], v[42:45]
	v_mfma_f32_16x16x32_bf16 v[38:41], v[136:139], v[234:237], v[38:41]
	v_mfma_f32_16x16x32_bf16 v[34:37], v[186:189], v[234:237], v[34:37]
	v_mfma_f32_16x16x32_bf16 v[30:33], v[190:193], v[206:209], v[30:33]
	s_add_i32 s71, 0, 0x18000
	v_mfma_f32_16x16x32_bf16 v[26:29], v[198:201], v[206:209], v[26:29]
	s_add_i32 s74, 0, 0x1c000
	v_mfma_f32_16x16x32_bf16 v[22:25], v[190:193], v[214:217], v[22:25]
	v_mfma_f32_16x16x32_bf16 v[18:21], v[198:201], v[214:217], v[18:21]
	v_mfma_f32_16x16x32_bf16 v[14:17], v[190:193], v[222:225], v[14:17]
	v_mfma_f32_16x16x32_bf16 v[10:13], v[198:201], v[222:225], v[10:13]
	v_mfma_f32_16x16x32_bf16 v[6:9], v[190:193], v[230:233], v[6:9]
	v_mfma_f32_16x16x32_bf16 v[2:5], v[198:201], v[230:233], v[2:5]
	v_mfma_f32_16x16x32_bf16 v[30:33], v[194:197], v[210:213], v[30:33]
	v_mfma_f32_16x16x32_bf16 v[26:29], v[202:205], v[210:213], v[26:29]
	v_mfma_f32_16x16x32_bf16 v[22:25], v[194:197], v[218:221], v[22:25]
	v_mfma_f32_16x16x32_bf16 v[18:21], v[202:205], v[218:221], v[18:21]
	v_mfma_f32_16x16x32_bf16 v[14:17], v[194:197], v[226:229], v[14:17]
	v_mfma_f32_16x16x32_bf16 v[10:13], v[202:205], v[226:229], v[10:13]
	v_mfma_f32_16x16x32_bf16 v[6:9], v[194:197], v[234:237], v[6:9]
	v_mfma_f32_16x16x32_bf16 v[2:5], v[202:205], v[234:237], v[2:5]
	s_barrier
	ds_read_b128 v[132:135], v251 offset:32768
	ds_read_b128 v[136:139], v251 offset:33792
	ds_read_b128 v[140:143], v251 offset:34816
	ds_read_b128 v[186:189], v251 offset:35840
	ds_read_b128 v[190:193], v251 offset:49152
	ds_read_b128 v[194:197], v251 offset:50176
	ds_read_b128 v[198:201], v251 offset:51200
	ds_read_b128 v[202:205], v251 offset:52224
	s_mov_b64 s[72:73], 0x4000
	s_mov_b32 m0, s57
	s_mov_b64 s[72:73], 0x6000
	ds_read_b128 v[206:209], v183 offset:32768
	ds_read_b128 v[210:213], v183 offset:33792
	ds_read_b128 v[214:217], v183 offset:34816
	ds_read_b128 v[218:221], v183 offset:35840
	ds_read_b128 v[222:225], v183 offset:36864
	ds_read_b128 v[226:229], v183 offset:37888
	ds_read_b128 v[230:233], v183 offset:38912
	ds_read_b128 v[234:237], v183 offset:39936
	global_load_lds_dwordx4 v245, s[84:85]
	s_mov_b32 m0, s58
	s_nop 0
	global_load_lds_dwordx4 v246, s[84:85]
	s_waitcnt vmcnt(8)
	s_waitcnt lgkmcnt(0)
	s_barrier
	s_waitcnt lgkmcnt(0)
	v_mfma_f32_16x16x32_bf16 v[126:129], v[132:135], v[206:209], v[126:129]
	v_mfma_f32_16x16x32_bf16 v[122:125], v[140:143], v[206:209], v[122:125]
	v_mfma_f32_16x16x32_bf16 v[118:121], v[132:135], v[214:217], v[118:121]
	v_mfma_f32_16x16x32_bf16 v[114:117], v[140:143], v[214:217], v[114:117]
	v_mfma_f32_16x16x32_bf16 v[110:113], v[132:135], v[222:225], v[110:113]
	v_mfma_f32_16x16x32_bf16 v[106:109], v[140:143], v[222:225], v[106:109]
	v_mfma_f32_16x16x32_bf16 v[102:105], v[132:135], v[230:233], v[102:105]
	v_mfma_f32_16x16x32_bf16 v[98:101], v[140:143], v[230:233], v[98:101]
	v_mfma_f32_16x16x32_bf16 v[126:129], v[136:139], v[210:213], v[126:129]
	v_mfma_f32_16x16x32_bf16 v[122:125], v[186:189], v[210:213], v[122:125]
	v_mfma_f32_16x16x32_bf16 v[118:121], v[136:139], v[218:221], v[118:121]
	v_mfma_f32_16x16x32_bf16 v[114:117], v[186:189], v[218:221], v[114:117]
	v_mfma_f32_16x16x32_bf16 v[110:113], v[136:139], v[226:229], v[110:113]
	v_mfma_f32_16x16x32_bf16 v[106:109], v[186:189], v[226:229], v[106:109]
	v_mfma_f32_16x16x32_bf16 v[102:105], v[136:139], v[234:237], v[102:105]
	v_mfma_f32_16x16x32_bf16 v[98:101], v[186:189], v[234:237], v[98:101]
	v_mfma_f32_16x16x32_bf16 v[94:97], v[190:193], v[206:209], v[94:97]
	s_add_i32 s71, s71, s9
	v_mfma_f32_16x16x32_bf16 v[90:93], v[198:201], v[206:209], v[90:93]
	s_add_u32 s86, s48, s28
	v_mfma_f32_16x16x32_bf16 v[86:89], v[190:193], v[214:217], v[86:89]
	s_addc_u32 s87, s49, s29
	v_mfma_f32_16x16x32_bf16 v[82:85], v[198:201], v[214:217], v[82:85]
	s_mov_b32 m0, s71
	v_mfma_f32_16x16x32_bf16 v[78:81], v[190:193], v[222:225], v[78:81]
	v_mfma_f32_16x16x32_bf16 v[74:77], v[198:201], v[222:225], v[74:77]
	v_mfma_f32_16x16x32_bf16 v[70:73], v[190:193], v[230:233], v[70:73]
	v_mfma_f32_16x16x32_bf16 v[66:69], v[198:201], v[230:233], v[66:69]
	v_mfma_f32_16x16x32_bf16 v[94:97], v[194:197], v[210:213], v[94:97]
	v_mfma_f32_16x16x32_bf16 v[90:93], v[202:205], v[210:213], v[90:93]
	v_mfma_f32_16x16x32_bf16 v[86:89], v[194:197], v[218:221], v[86:89]
	v_mfma_f32_16x16x32_bf16 v[82:85], v[202:205], v[218:221], v[82:85]
	v_mfma_f32_16x16x32_bf16 v[78:81], v[194:197], v[226:229], v[78:81]
	v_mfma_f32_16x16x32_bf16 v[74:77], v[202:205], v[226:229], v[74:77]
	v_mfma_f32_16x16x32_bf16 v[70:73], v[194:197], v[234:237], v[70:73]
	v_mfma_f32_16x16x32_bf16 v[66:69], v[202:205], v[234:237], v[66:69]
	s_barrier
; #define PG8_STAGE(bufoff, gbase, voff) do { _Pragma("unroll") for (int _i = 0; _i < 2; ++_i) \
;         __builtin_amdgcn_global_load_lds((const unsigned*)((const char*)(gbase) + (voff)[_i]), (PG8_LAS unsigned*)(lds + (bufoff) + ldsw + _i * 8192), 16, 0, 0); } while (0)
; #define PG8_LDA(dst, b, h) do { _Pragma("unroll") for (int m = 0; m < 4; ++m) _Pragma("unroll") for (int k = 0; k < 2; ++k) dst[m][k] = *(const PG8_LAS bf16x8*)(lds + PG8_SA(b, h) + aoff + m * 2048 + k * 1024); } while (0)
; #define PG8_MMA(ai, bj, At, Bt) do { __builtin_amdgcn_s_setprio(1); _Pragma("unroll") for (int m = 0; m < 4; ++m) _Pragma("unroll") for (int n = 0; n < 2; ++n) _Pragma("unroll") for (int k = 0; k < 2; ++k) \
;         acc[ai][bj][m][n] = __builtin_amdgcn_mfma_f32_16x16x32_bf16(Bt[n][k], At[m][k], acc[ai][bj][m][n], 0, 0, 0); __builtin_amdgcn_s_setprio(0); } while (0)
; #define PG8_WAIT_V(n) asm volatile("s_waitcnt vmcnt(" #n ")" ::: "memory")
; #define PG8_WAIT_L(n) asm volatile("s_waitcnt lgkmcnt(" #n ")" ::: "memory")
; #define PG8_BAR __builtin_amdgcn_s_barrier()
; #define PG8_SCHED __builtin_amdgcn_sched_barrier(0)
; template <class Epi, bool ALIGN_EPI, bool ABLK = false>
; __device__ __forceinline__ void gemm_phase(PG8_LAS unsigned char* lds, const Gemm g, const StaticOrder& S, const Epi& E) {
;     ...
;             PG8_LDA(At, 1, 1); PG8_STAGE(PG8_SB(1, 0), b3, voffB); PG8_STAGE(PG8_SB(1, 1), b3 + hstepB, voffB); PG8_STAGE(PG8_SA(1, 0), a3, voffA);
;             PG8_WAIT_V(8); PG8_WAIT_L(0); PG8_BAR; PG8_MMA(1, 0, At, B0); PG8_MMA(1, 1, At, B1); PG8_BAR; PG8_SCHED;
;         }
;         if constexpr (ALIGN_EPI) { if (wr == 0) PG8_BAR; }
	ds_read_b128 v[206:209], v183 offset:49152
	ds_read_b128 v[210:213], v183 offset:50176
	ds_read_b128 v[214:217], v183 offset:51200
	ds_read_b128 v[218:221], v183 offset:52224
	ds_read_b128 v[222:225], v183 offset:53248
	ds_read_b128 v[226:229], v183 offset:54272
	ds_read_b128 v[230:233], v183 offset:55296
	ds_read_b128 v[234:237], v183 offset:56320
	global_load_lds_dwordx4 v148, s[86:87]
	s_add_i32 m0, s71, 0x2000
	s_add_u32 s48, s48, 0x40080
	s_addc_u32 s49, s49, 0
	s_add_i32 s71, s74, s9
	global_load_lds_dwordx4 v150, s[86:87]
	s_mov_b32 m0, s71
	s_nop 0
	global_load_lds_dwordx4 v148, s[48:49]
	s_add_i32 m0, s71, 0x2000
	s_nop 0
	global_load_lds_dwordx4 v150, s[48:49]
	s_mov_b32 m0, s59
	s_nop 0
	global_load_lds_dwordx4 v247, s[84:85]
	s_mov_b32 m0, s61
	s_nop 0
	global_load_lds_dwordx4 v248, s[84:85]
	s_waitcnt vmcnt(8)
	s_waitcnt lgkmcnt(0)
	s_barrier
	s_waitcnt lgkmcnt(0)
	v_mfma_f32_16x16x32_bf16 v[62:65], v[132:135], v[206:209], v[62:65]
	v_mfma_f32_16x16x32_bf16 v[58:61], v[140:143], v[206:209], v[58:61]
	v_mfma_f32_16x16x32_bf16 v[54:57], v[132:135], v[214:217], v[54:57]
	v_mfma_f32_16x16x32_bf16 v[50:53], v[140:143], v[214:217], v[50:53]
	v_mfma_f32_16x16x32_bf16 v[46:49], v[132:135], v[222:225], v[46:49]
	v_mfma_f32_16x16x32_bf16 v[42:45], v[140:143], v[222:225], v[42:45]
	v_mfma_f32_16x16x32_bf16 v[38:41], v[132:135], v[230:233], v[38:41]
	v_mfma_f32_16x16x32_bf16 v[34:37], v[140:143], v[230:233], v[34:37]
	v_mfma_f32_16x16x32_bf16 v[62:65], v[136:139], v[210:213], v[62:65]
	v_mfma_f32_16x16x32_bf16 v[58:61], v[186:189], v[210:213], v[58:61]
	v_mfma_f32_16x16x32_bf16 v[54:57], v[136:139], v[218:221], v[54:57]
	v_mfma_f32_16x16x32_bf16 v[50:53], v[186:189], v[218:221], v[50:53]
	v_mfma_f32_16x16x32_bf16 v[46:49], v[136:139], v[226:229], v[46:49]
	v_mfma_f32_16x16x32_bf16 v[42:45], v[186:189], v[226:229], v[42:45]
	v_mfma_f32_16x16x32_bf16 v[38:41], v[136:139], v[234:237], v[38:41]
	v_mfma_f32_16x16x32_bf16 v[34:37], v[186:189], v[234:237], v[34:37]
	v_mfma_f32_16x16x32_bf16 v[30:33], v[190:193], v[206:209], v[30:33]
	s_add_i32 s70, s70, 2
	v_mfma_f32_16x16x32_bf16 v[26:29], v[198:201], v[206:209], v[26:29]
	s_add_u32 s68, s68, 0x100
	v_mfma_f32_16x16x32_bf16 v[22:25], v[190:193], v[214:217], v[22:25]
	s_addc_u32 s69, s69, 0
	v_mfma_f32_16x16x32_bf16 v[18:21], v[198:201], v[214:217], v[18:21]
	s_add_u32 s46, s46, 0x10000
	v_mfma_f32_16x16x32_bf16 v[14:17], v[190:193], v[222:225], v[14:17]
	s_addc_u32 s47, s47, 0
	v_mfma_f32_16x16x32_bf16 v[10:13], v[198:201], v[222:225], v[10:13]
	s_add_u32 s82, s82, 0x10000
	v_mfma_f32_16x16x32_bf16 v[6:9], v[190:193], v[230:233], v[6:9]
	s_addc_u32 s83, s83, 0
	v_mfma_f32_16x16x32_bf16 v[2:5], v[198:201], v[230:233], v[2:5]
	s_mov_b64 s[48:49], 0x10000
	v_mfma_f32_16x16x32_bf16 v[30:33], v[194:197], v[210:213], v[30:33]
	s_cmp_gt_u32 s70, 13
	v_mfma_f32_16x16x32_bf16 v[26:29], v[202:205], v[210:213], v[26:29]
	v_mfma_f32_16x16x32_bf16 v[22:25], v[194:197], v[218:221], v[22:25]
	v_mfma_f32_16x16x32_bf16 v[18:21], v[202:205], v[218:221], v[18:21]
	v_mfma_f32_16x16x32_bf16 v[14:17], v[194:197], v[226:229], v[14:17]
	v_mfma_f32_16x16x32_bf16 v[10:13], v[202:205], v[226:229], v[10:13]
	v_mfma_f32_16x16x32_bf16 v[6:9], v[194:197], v[234:237], v[6:9]
	v_mfma_f32_16x16x32_bf16 v[2:5], v[202:205], v[234:237], v[2:5]
	s_barrier
	s_cbranch_scc0 .LBB0_402
	s_setprio 0
	s_and_b64 vcc, exec, s[36:37]
	s_cbranch_vccz .LBB0_405
	s_barrier

; #define PG8_STAGE(bufoff, gbase, voff) do { _Pragma("unroll") for (int _i = 0; _i < 2; ++_i) \
;         __builtin_amdgcn_global_load_lds((const unsigned*)((const char*)(gbase) + (voff)[_i]), (PG8_LAS unsigned*)(lds + (bufoff) + ldsw + _i * 8192), 16, 0, 0); } while (0)
; #define PG8_LDA(dst, b, h) do { _Pragma("unroll") for (int m = 0; m < 4; ++m) _Pragma("unroll") for (int k = 0; k < 2; ++k) dst[m][k] = *(const PG8_LAS bf16x8*)(lds + PG8_SA(b, h) + aoff + m * 2048 + k * 1024); } while (0)
; #define PG8_LDB(dst, b, h) do { _Pragma("unroll") for (int n = 0; n < 2; ++n) _Pragma("unroll") for (int k = 0; k < 2; ++k) dst[n][k] = *(const PG8_LAS bf16x8*)(lds + PG8_SB(b, h) + boff + n * 2048 + k * 1024); } while (0)
; #define PG8_WAIT_V(n) asm volatile("s_waitcnt vmcnt(" #n ")" ::: "memory")
; #define PG8_WAIT_L(n) asm volatile("s_waitcnt lgkmcnt(" #n ")" ::: "memory")
; #define PG8_BAR __builtin_amdgcn_s_barrier()
; #define PG8_SCHED __builtin_amdgcn_sched_barrier(0)
; #define S xcd_barrier(bar);
; template <class Epi, bool ALIGN_EPI, bool ABLK = false>
; __device__ __forceinline__ void gemm_phase(PG8_LAS unsigned char* lds, const Gemm g, const StaticOrder& S, const Epi& E) {
;     ...
;         const bool has_next = S.next(ui + 1, nxt);
;         const char* nA = has_next ? PG8_ABASE(nxt) : cA; const char* nB = has_next ? PG8_BBASE(nxt) : cB;
;         for (int t = 0; t < nt; t += 2) {
;             const bool last = (t == nt - 2);
;             const char* a1 = cA + (size_t)(t + 1) * kstepA;
;             const char* a2 = last ? nA : cA + (size_t)(t + 2) * kstepA; const char* b2 = last ? nB : cB + (size_t)(t + 2) * kstepB;
;             const char* a3 = a2 + kstepA; const char* b3 = b2 + kstepB;
;             PG8_LDB(B0, 0, 0); PG8_LDB(B1, 0, 1); PG8_SCHED; PG8_LDA(At, 0, 0); PG8_STAGE(PG8_SA(1, 1), a1 + hstepA, voffA);
;             PG8_WAIT_V(8); PG8_WAIT_L(0); PG8_BAR; PG8_MMA(0, 0, At, B0); PG8_MMA(0, 1, At, B1); PG8_BAR; PG8_SCHED;
;     ...
;         if (!E.keep(cur)) {
; #pragma unroll
;             for (int a = 0; a < 2; ++a)
; #pragma unroll
;                 for (int b = 0; b < 2; ++b)
; #pragma unroll
;                     for (int m = 0; m < 4; ++m)
; #pragma unroll
;                         for (int n = 0; n < 2; ++n) acc[a][b][m][n] = (f32x4){0.f, 0.f, 0.f, 0.f};
;         }
;         cur = nxt; cA = nA; cB = nB; ++ui;
.LBB0_539:
	s_add_u32 s54, s50, 0x100
	s_addc_u32 s55, s51, 0
	s_add_u32 s50, s52, 0x10000
	v_mov_b32_e32 v2, 0
	s_addc_u32 s51, s53, 0
	s_mov_b32 s78, -2
	s_waitcnt lgkmcnt(0)
	v_mov_b32_e32 v3, v2
	v_mov_b32_e32 v4, v2
	v_mov_b32_e32 v5, v2
	v_mov_b32_e32 v6, v2
	v_mov_b32_e32 v7, v2
	v_mov_b32_e32 v8, v2
	v_mov_b32_e32 v9, v2
	v_mov_b32_e32 v18, v2
	v_mov_b32_e32 v19, v2
	v_mov_b32_e32 v20, v2
	v_mov_b32_e32 v21, v2
	v_mov_b32_e32 v22, v2
	v_mov_b32_e32 v23, v2
	v_mov_b32_e32 v24, v2
	v_mov_b32_e32 v25, v2
	v_mov_b32_e32 v34, v2
	v_mov_b32_e32 v35, v2
	v_mov_b32_e32 v36, v2
	v_mov_b32_e32 v37, v2
	v_mov_b32_e32 v38, v2
	v_mov_b32_e32 v39, v2
	v_mov_b32_e32 v40, v2
	v_mov_b32_e32 v41, v2
	v_mov_b32_e32 v50, v2
	v_mov_b32_e32 v51, v2
	v_mov_b32_e32 v52, v2
	v_mov_b32_e32 v53, v2
	v_mov_b32_e32 v54, v2
	v_mov_b32_e32 v55, v2
	v_mov_b32_e32 v56, v2
	v_mov_b32_e32 v57, v2
	v_mov_b32_e32 v10, v2
	v_mov_b32_e32 v11, v2
	v_mov_b32_e32 v12, v2
	v_mov_b32_e32 v13, v2
	v_mov_b32_e32 v14, v2
	v_mov_b32_e32 v15, v2
	v_mov_b32_e32 v16, v2
	v_mov_b32_e32 v17, v2
	v_mov_b32_e32 v26, v2
	v_mov_b32_e32 v27, v2
	v_mov_b32_e32 v28, v2
	v_mov_b32_e32 v29, v2
	v_mov_b32_e32 v30, v2
	v_mov_b32_e32 v31, v2
	v_mov_b32_e32 v32, v2
	v_mov_b32_e32 v33, v2
	v_mov_b32_e32 v42, v2
	v_mov_b32_e32 v43, v2
	v_mov_b32_e32 v44, v2
	v_mov_b32_e32 v45, v2
	v_mov_b32_e32 v46, v2
	v_mov_b32_e32 v47, v2
	v_mov_b32_e32 v48, v2
	v_mov_b32_e32 v49, v2
	v_mov_b32_e32 v58, v2
	v_mov_b32_e32 v59, v2
	v_mov_b32_e32 v60, v2
	v_mov_b32_e32 v61, v2
	v_mov_b32_e32 v62, v2
	v_mov_b32_e32 v63, v2
	v_mov_b32_e32 v64, v2
	v_mov_b32_e32 v65, v2
	v_mov_b32_e32 v66, v2
	v_mov_b32_e32 v67, v2
	v_mov_b32_e32 v68, v2
	v_mov_b32_e32 v69, v2
	v_mov_b32_e32 v70, v2
	v_mov_b32_e32 v71, v2
	v_mov_b32_e32 v72, v2
	v_mov_b32_e32 v73, v2
	v_mov_b32_e32 v82, v2
	v_mov_b32_e32 v83, v2
	v_mov_b32_e32 v84, v2
	v_mov_b32_e32 v85, v2
	v_mov_b32_e32 v86, v2
	v_mov_b32_e32 v87, v2
	v_mov_b32_e32 v88, v2
	v_mov_b32_e32 v89, v2
	v_mov_b32_e32 v102, v2
	v_mov_b32_e32 v103, v2
	v_mov_b32_e32 v104, v2
	v_mov_b32_e32 v105, v2
	v_mov_b32_e32 v106, v2
	v_mov_b32_e32 v107, v2
	v_mov_b32_e32 v108, v2
	v_mov_b32_e32 v109, v2
	v_mov_b32_e32 v130, v2
	v_mov_b32_e32 v131, v2
	v_mov_b32_e32 v132, v2
	v_mov_b32_e32 v133, v2
	v_mov_b32_e32 v138, v2
	v_mov_b32_e32 v139, v2
	v_mov_b32_e32 v140, v2
	v_mov_b32_e32 v141, v2
	v_mov_b32_e32 v74, v2
	v_mov_b32_e32 v75, v2
	v_mov_b32_e32 v76, v2
	v_mov_b32_e32 v77, v2
	v_mov_b32_e32 v78, v2
	v_mov_b32_e32 v79, v2
	v_mov_b32_e32 v80, v2
	v_mov_b32_e32 v81, v2
	v_mov_b32_e32 v90, v2
	v_mov_b32_e32 v91, v2
	v_mov_b32_e32 v92, v2
	v_mov_b32_e32 v93, v2
	v_mov_b32_e32 v94, v2
	v_mov_b32_e32 v95, v2
	v_mov_b32_e32 v96, v2
	v_mov_b32_e32 v97, v2
	v_mov_b32_e32 v114, v2
	v_mov_b32_e32 v115, v2
	v_mov_b32_e32 v116, v2
	v_mov_b32_e32 v117, v2
	v_mov_b32_e32 v118, v2
	v_mov_b32_e32 v119, v2
	v_mov_b32_e32 v120, v2
	v_mov_b32_e32 v121, v2
	v_mov_b32_e32 v158, v2
	v_mov_b32_e32 v159, v2
	v_mov_b32_e32 v160, v2
	v_mov_b32_e32 v161, v2
	v_mov_b32_e32 v162, v2
	v_mov_b32_e32 v163, v2
	v_mov_b32_e32 v164, v2
	v_mov_b32_e32 v165, v2
	s_setprio 0
	v_readfirstlane_b32 s101, v0
	s_nop 3
	s_bfe_u32 s101, s101, 0x40006
	s_cmp_ge_u32 s101, 4
	s_cbranch_scc0 .Lprio_540
	s_setprio 1
.Lprio_540:
.LBB0_540:
	ds_read_b128 v[98:101], v238
	ds_read_b128 v[110:113], v238 offset:1024
	ds_read_b128 v[122:125], v238 offset:2048
	ds_read_b128 v[126:129], v238 offset:3072
	ds_read_b128 v[134:137], v239
	ds_read_b128 v[142:145], v239 offset:1024
	ds_read_b128 v[146:149], v239 offset:2048
	ds_read_b128 v[150:153], v239 offset:3072
	s_cmp_eq_u32 s78, 40
	s_cselect_b32 s81, s9, s51
	s_cselect_b32 s80, s8, s50
	s_cselect_b32 s53, s49, s55
	s_cselect_b32 s52, s48, s54
	s_movk_i32 s82, 0xc000
	v_lshl_add_u64 v[242:243], s[50:51], 0, v[194:195]
	s_mov_b32 s83, -1
	v_lshl_add_u64 v[244:245], v[242:243], 0, s[82:83]
	s_movk_i32 s82, 0xe000
	s_add_i32 m0, s61, 0xc000
	s_mov_b32 s83, -1
	ds_read_b128 v[154:157], v240
	ds_read_b128 v[166:169], v240 offset:1024
	ds_read_b128 v[170:173], v240 offset:2048
	ds_read_b128 v[174:177], v240 offset:3072
	ds_read_b128 v[178:181], v240 offset:4096
	ds_read_b128 v[182:185], v240 offset:5120
	ds_read_b128 v[186:189], v240 offset:6144
	ds_read_b128 v[190:193], v240 offset:7168
	global_load_lds_dwordx4 v[244:245], off
	v_lshl_add_u64 v[242:243], v[242:243], 0, s[82:83]
	s_add_i32 m0, s61, 0xe000
	s_nop 0
	global_load_lds_dwordx4 v[242:243], off
	s_waitcnt vmcnt(8)
	s_waitcnt lgkmcnt(0)
	s_barrier
; #define PG8_STAGE(bufoff, gbase, voff) do { _Pragma("unroll") for (int _i = 0; _i < 2; ++_i) \
;         __builtin_amdgcn_global_load_lds((const unsigned*)((const char*)(gbase) + (voff)[_i]), (PG8_LAS unsigned*)(lds + (bufoff) + ldsw + _i * 8192), 16, 0, 0); } while (0)
; #define PG8_LDA(dst, b, h) do { _Pragma("unroll") for (int m = 0; m < 4; ++m) _Pragma("unroll") for (int k = 0; k < 2; ++k) dst[m][k] = *(const PG8_LAS bf16x8*)(lds + PG8_SA(b, h) + aoff + m * 2048 + k * 1024); } while (0)
; #define PG8_LDB(dst, b, h) do { _Pragma("unroll") for (int n = 0; n < 2; ++n) _Pragma("unroll") for (int k = 0; k < 2; ++k) dst[n][k] = *(const PG8_LAS bf16x8*)(lds + PG8_SB(b, h) + boff + n * 2048 + k * 1024); } while (0)
; #define PG8_MMA(ai, bj, At, Bt) do { __builtin_amdgcn_s_setprio(1); _Pragma("unroll") for (int m = 0; m < 4; ++m) _Pragma("unroll") for (int n = 0; n < 2; ++n) _Pragma("unroll") for (int k = 0; k < 2; ++k) \
;         acc[ai][bj][m][n] = __builtin_amdgcn_mfma_f32_16x16x32_bf16(Bt[n][k], At[m][k], acc[ai][bj][m][n], 0, 0, 0); __builtin_amdgcn_s_setprio(0); } while (0)
; #define PG8_WAIT_V(n) asm volatile("s_waitcnt vmcnt(" #n ")" ::: "memory")
; #define PG8_WAIT_L(n) asm volatile("s_waitcnt lgkmcnt(" #n ")" ::: "memory")
; #define PG8_BAR __builtin_amdgcn_s_barrier()
; #define PG8_SCHED __builtin_amdgcn_sched_barrier(0)
; template <class Epi, bool ALIGN_EPI, bool ABLK = false>
; __device__ __forceinline__ void gemm_phase(PG8_LAS unsigned char* lds, const Gemm g, const StaticOrder& S, const Epi& E) {
;     ...
;             PG8_WAIT_V(8); PG8_WAIT_L(0); PG8_BAR; PG8_MMA(0, 0, At, B0); PG8_MMA(0, 1, At, B1); PG8_BAR; PG8_SCHED;
;             PG8_LDA(At, 0, 1); PG8_STAGE(PG8_SB(0, 0), b2, voffB); PG8_STAGE(PG8_SB(0, 1), b2 + hstepB, voffB); PG8_STAGE(PG8_SA(0, 0), a2, voffA);
;             PG8_WAIT_V(8); PG8_WAIT_L(0); PG8_BAR; PG8_MMA(1, 0, At, B0); PG8_MMA(1, 1, At, B1); PG8_BAR; PG8_SCHED;
;             PG8_LDB(B0, 1, 0); PG8_LDB(B1, 1, 1); PG8_SCHED; PG8_LDA(At, 1, 0); PG8_STAGE(PG8_SA(0, 1), a2 + hstepA, voffA);
;             PG8_WAIT_V(8); PG8_WAIT_L(0); PG8_BAR; PG8_MMA(0, 0, At, B0); PG8_MMA(0, 1, At, B1); PG8_BAR; PG8_SCHED;
	s_waitcnt lgkmcnt(0)
	v_mfma_f32_16x16x32_bf16 v[162:165], v[98:101], v[154:157], v[162:165]
	v_mfma_f32_16x16x32_bf16 v[158:161], v[122:125], v[154:157], v[158:161]
	v_mfma_f32_16x16x32_bf16 v[118:121], v[98:101], v[170:173], v[118:121]
	v_mfma_f32_16x16x32_bf16 v[114:117], v[122:125], v[170:173], v[114:117]
	v_mfma_f32_16x16x32_bf16 v[94:97], v[98:101], v[178:181], v[94:97]
	v_mfma_f32_16x16x32_bf16 v[90:93], v[122:125], v[178:181], v[90:93]
	v_mfma_f32_16x16x32_bf16 v[78:81], v[98:101], v[186:189], v[78:81]
	v_mfma_f32_16x16x32_bf16 v[74:77], v[122:125], v[186:189], v[74:77]
	v_mfma_f32_16x16x32_bf16 v[162:165], v[110:113], v[166:169], v[162:165]
	v_mfma_f32_16x16x32_bf16 v[158:161], v[126:129], v[166:169], v[158:161]
	v_mfma_f32_16x16x32_bf16 v[118:121], v[110:113], v[174:177], v[118:121]
	v_mfma_f32_16x16x32_bf16 v[114:117], v[126:129], v[174:177], v[114:117]
	v_mfma_f32_16x16x32_bf16 v[94:97], v[110:113], v[182:185], v[94:97]
	v_mfma_f32_16x16x32_bf16 v[90:93], v[126:129], v[182:185], v[90:93]
	v_mfma_f32_16x16x32_bf16 v[78:81], v[110:113], v[190:193], v[78:81]
	v_mfma_f32_16x16x32_bf16 v[74:77], v[126:129], v[190:193], v[74:77]
	v_mfma_f32_16x16x32_bf16 v[138:141], v[134:137], v[154:157], v[138:141]
	s_add_i32 s79, s73, s59
	v_mfma_f32_16x16x32_bf16 v[130:133], v[146:149], v[154:157], v[130:133]
	s_mov_b32 m0, s79
	v_mfma_f32_16x16x32_bf16 v[106:109], v[134:137], v[170:173], v[106:109]
	v_mfma_f32_16x16x32_bf16 v[102:105], v[146:149], v[170:173], v[102:105]
	v_mfma_f32_16x16x32_bf16 v[86:89], v[134:137], v[178:181], v[86:89]
	v_mfma_f32_16x16x32_bf16 v[82:85], v[146:149], v[178:181], v[82:85]
	v_mfma_f32_16x16x32_bf16 v[70:73], v[134:137], v[186:189], v[70:73]
	v_mfma_f32_16x16x32_bf16 v[66:69], v[146:149], v[186:189], v[66:69]
	v_mfma_f32_16x16x32_bf16 v[138:141], v[142:145], v[166:169], v[138:141]
	v_mfma_f32_16x16x32_bf16 v[130:133], v[150:153], v[166:169], v[130:133]
	v_mfma_f32_16x16x32_bf16 v[106:109], v[142:145], v[174:177], v[106:109]
	v_mfma_f32_16x16x32_bf16 v[102:105], v[150:153], v[174:177], v[102:105]
	v_mfma_f32_16x16x32_bf16 v[86:89], v[142:145], v[182:185], v[86:89]
	v_mfma_f32_16x16x32_bf16 v[82:85], v[150:153], v[182:185], v[82:85]
	v_mfma_f32_16x16x32_bf16 v[70:73], v[142:145], v[190:193], v[70:73]
	v_mfma_f32_16x16x32_bf16 v[66:69], v[150:153], v[190:193], v[66:69]
	s_barrier
	v_lshl_add_u64 v[242:243], s[52:53], 0, v[196:197]
	ds_read_b128 v[154:157], v240 offset:16384
	ds_read_b128 v[166:169], v240 offset:17408
	ds_read_b128 v[170:173], v240 offset:18432
	ds_read_b128 v[174:177], v240 offset:19456
	ds_read_b128 v[178:181], v240 offset:20480
	ds_read_b128 v[182:185], v240 offset:21504
	ds_read_b128 v[186:189], v240 offset:22528
	ds_read_b128 v[190:193], v240 offset:23552
	global_load_lds_dwordx4 v[242:243], off
	s_add_i32 m0, s79, 0x2000
	s_add_u32 s82, s52, 0xb0000
	v_lshl_add_u64 v[244:245], s[52:53], 0, v[198:199]
	s_addc_u32 s83, s53, 0
	s_add_i32 s79, s74, s59
	global_load_lds_dwordx4 v[244:245], off
	v_lshl_add_u64 v[246:247], s[82:83], 0, v[196:197]
	s_mov_b32 m0, s79
	s_nop 0
	global_load_lds_dwordx4 v[246:247], off
	v_lshl_add_u64 v[246:247], s[82:83], 0, v[198:199]
	s_add_i32 m0, s79, 0x2000
	s_nop 0
	global_load_lds_dwordx4 v[246:247], off
	v_lshl_add_u64 v[246:247], s[80:81], 0, v[194:195]
	s_mov_b32 m0, s61
	v_lshl_add_u64 v[248:249], v[246:247], 0, s[10:11]
	global_load_lds_dwordx4 v[246:247], off
	s_mov_b32 m0, s62
	s_nop 0
	global_load_lds_dwordx4 v[248:249], off
	s_waitcnt vmcnt(8)
	s_waitcnt lgkmcnt(0)
	s_barrier
	s_waitcnt lgkmcnt(0)
	v_mfma_f32_16x16x32_bf16 v[62:65], v[98:101], v[154:157], v[62:65]
	v_mfma_f32_16x16x32_bf16 v[58:61], v[122:125], v[154:157], v[58:61]
	v_mfma_f32_16x16x32_bf16 v[46:49], v[98:101], v[170:173], v[46:49]
	v_mfma_f32_16x16x32_bf16 v[42:45], v[122:125], v[170:173], v[42:45]
	v_mfma_f32_16x16x32_bf16 v[30:33], v[98:101], v[178:181], v[30:33]
	v_mfma_f32_16x16x32_bf16 v[26:29], v[122:125], v[178:181], v[26:29]
	v_mfma_f32_16x16x32_bf16 v[14:17], v[98:101], v[186:189], v[14:17]
	v_mfma_f32_16x16x32_bf16 v[10:13], v[122:125], v[186:189], v[10:13]
	v_mfma_f32_16x16x32_bf16 v[62:65], v[110:113], v[166:169], v[62:65]
	v_mfma_f32_16x16x32_bf16 v[58:61], v[126:129], v[166:169], v[58:61]
	v_mfma_f32_16x16x32_bf16 v[46:49], v[110:113], v[174:177], v[46:49]
	v_mfma_f32_16x16x32_bf16 v[42:45], v[126:129], v[174:177], v[42:45]
	v_mfma_f32_16x16x32_bf16 v[30:33], v[110:113], v[182:185], v[30:33]
	v_mfma_f32_16x16x32_bf16 v[26:29], v[126:129], v[182:185], v[26:29]
	v_mfma_f32_16x16x32_bf16 v[14:17], v[110:113], v[190:193], v[14:17]
	v_mfma_f32_16x16x32_bf16 v[10:13], v[126:129], v[190:193], v[10:13]
	v_mfma_f32_16x16x32_bf16 v[54:57], v[134:137], v[154:157], v[54:57]
	s_add_i32 s79, 0, 0x18000
	v_mfma_f32_16x16x32_bf16 v[50:53], v[146:149], v[154:157], v[50:53]
	s_add_i32 s80, 0, 0x1c000
	v_mfma_f32_16x16x32_bf16 v[38:41], v[134:137], v[170:173], v[38:41]
	v_mfma_f32_16x16x32_bf16 v[34:37], v[146:149], v[170:173], v[34:37]
	v_mfma_f32_16x16x32_bf16 v[22:25], v[134:137], v[178:181], v[22:25]
	v_mfma_f32_16x16x32_bf16 v[18:21], v[146:149], v[178:181], v[18:21]
	v_mfma_f32_16x16x32_bf16 v[6:9], v[134:137], v[186:189], v[6:9]
	v_mfma_f32_16x16x32_bf16 v[2:5], v[146:149], v[186:189], v[2:5]
	v_mfma_f32_16x16x32_bf16 v[54:57], v[142:145], v[166:169], v[54:57]
	v_mfma_f32_16x16x32_bf16 v[50:53], v[150:153], v[166:169], v[50:53]
	v_mfma_f32_16x16x32_bf16 v[38:41], v[142:145], v[174:177], v[38:41]
	v_mfma_f32_16x16x32_bf16 v[34:37], v[150:153], v[174:177], v[34:37]
	v_mfma_f32_16x16x32_bf16 v[22:25], v[142:145], v[182:185], v[22:25]
	v_mfma_f32_16x16x32_bf16 v[18:21], v[150:153], v[182:185], v[18:21]
	v_mfma_f32_16x16x32_bf16 v[6:9], v[142:145], v[190:193], v[6:9]
	v_mfma_f32_16x16x32_bf16 v[2:5], v[150:153], v[190:193], v[2:5]
	s_barrier
; #define PG8_STAGE(bufoff, gbase, voff) do { _Pragma("unroll") for (int _i = 0; _i < 2; ++_i) \
;         __builtin_amdgcn_global_load_lds((const unsigned*)((const char*)(gbase) + (voff)[_i]), (PG8_LAS unsigned*)(lds + (bufoff) + ldsw + _i * 8192), 16, 0, 0); } while (0)
; #define PG8_LDA(dst, b, h) do { _Pragma("unroll") for (int m = 0; m < 4; ++m) _Pragma("unroll") for (int k = 0; k < 2; ++k) dst[m][k] = *(const PG8_LAS bf16x8*)(lds + PG8_SA(b, h) + aoff + m * 2048 + k * 1024); } while (0)
; #define PG8_LDB(dst, b, h) do { _Pragma("unroll") for (int n = 0; n < 2; ++n) _Pragma("unroll") for (int k = 0; k < 2; ++k) dst[n][k] = *(const PG8_LAS bf16x8*)(lds + PG8_SB(b, h) + boff + n * 2048 + k * 1024); } while (0)
; #define PG8_MMA(ai, bj, At, Bt) do { __builtin_amdgcn_s_setprio(1); _Pragma("unroll") for (int m = 0; m < 4; ++m) _Pragma("unroll") for (int n = 0; n < 2; ++n) _Pragma("unroll") for (int k = 0; k < 2; ++k) \
;         acc[ai][bj][m][n] = __builtin_amdgcn_mfma_f32_16x16x32_bf16(Bt[n][k], At[m][k], acc[ai][bj][m][n], 0, 0, 0); __builtin_amdgcn_s_setprio(0); } while (0)
; #define PG8_WAIT_V(n) asm volatile("s_waitcnt vmcnt(" #n ")" ::: "memory")
; #define PG8_WAIT_L(n) asm volatile("s_waitcnt lgkmcnt(" #n ")" ::: "memory")
; #define PG8_BAR __builtin_amdgcn_s_barrier()
; #define PG8_SCHED __builtin_amdgcn_sched_barrier(0)
; template <class Epi, bool ALIGN_EPI, bool ABLK = false>
; __device__ __forceinline__ void gemm_phase(PG8_LAS unsigned char* lds, const Gemm g, const StaticOrder& S, const Epi& E) {
;     ...
;             PG8_LDB(B0, 1, 0); PG8_LDB(B1, 1, 1); PG8_SCHED; PG8_LDA(At, 1, 0); PG8_STAGE(PG8_SA(0, 1), a2 + hstepA, voffA);
;             PG8_WAIT_V(8); PG8_WAIT_L(0); PG8_BAR; PG8_MMA(0, 0, At, B0); PG8_MMA(0, 1, At, B1); PG8_BAR; PG8_SCHED;
;             PG8_LDA(At, 1, 1); PG8_STAGE(PG8_SB(1, 0), b3, voffB); PG8_STAGE(PG8_SB(1, 1), b3 + hstepB, voffB); PG8_STAGE(PG8_SA(1, 0), a3, voffA);
;             PG8_WAIT_V(8); PG8_WAIT_L(0); PG8_BAR; PG8_MMA(1, 0, At, B0); PG8_MMA(1, 1, At, B1); PG8_BAR; PG8_SCHED;
;         }
;         if constexpr (ALIGN_EPI) { if (wr == 0) PG8_BAR; }
	v_add_u32_e32 v126, s79, v230
	v_add_u32_e32 v150, s80, v230
	ds_read_b128 v[98:101], v126
	ds_read_b128 v[110:113], v126 offset:1024
	ds_read_b128 v[122:125], v126 offset:2048
	ds_read_b128 v[126:129], v126 offset:3072
	ds_read_b128 v[134:137], v150
	ds_read_b128 v[142:145], v150 offset:1024
	ds_read_b128 v[146:149], v150 offset:2048
	ds_read_b128 v[150:153], v150 offset:3072
	s_mov_b32 m0, s63
	v_lshl_add_u64 v[248:249], v[246:247], 0, s[12:13]
	ds_read_b128 v[154:157], v240 offset:32768
	ds_read_b128 v[166:169], v240 offset:33792
	ds_read_b128 v[170:173], v240 offset:34816
	ds_read_b128 v[174:177], v240 offset:35840
	ds_read_b128 v[178:181], v240 offset:36864
	ds_read_b128 v[182:185], v240 offset:37888
	ds_read_b128 v[186:189], v240 offset:38912
	ds_read_b128 v[190:193], v240 offset:39936
	global_load_lds_dwordx4 v[248:249], off
	v_lshl_add_u64 v[248:249], v[246:247], 0, s[24:25]
	s_mov_b32 m0, s64
	s_nop 0
	global_load_lds_dwordx4 v[248:249], off
	s_waitcnt vmcnt(8)
	s_waitcnt lgkmcnt(0)
	s_barrier
	s_waitcnt lgkmcnt(0)
	v_mfma_f32_16x16x32_bf16 v[162:165], v[98:101], v[154:157], v[162:165]
	v_mfma_f32_16x16x32_bf16 v[158:161], v[122:125], v[154:157], v[158:161]
	v_mfma_f32_16x16x32_bf16 v[118:121], v[98:101], v[170:173], v[118:121]
	v_mfma_f32_16x16x32_bf16 v[114:117], v[122:125], v[170:173], v[114:117]
	v_mfma_f32_16x16x32_bf16 v[94:97], v[98:101], v[178:181], v[94:97]
	v_mfma_f32_16x16x32_bf16 v[90:93], v[122:125], v[178:181], v[90:93]
	v_mfma_f32_16x16x32_bf16 v[78:81], v[98:101], v[186:189], v[78:81]
	v_mfma_f32_16x16x32_bf16 v[74:77], v[122:125], v[186:189], v[74:77]
	v_mfma_f32_16x16x32_bf16 v[162:165], v[110:113], v[166:169], v[162:165]
	v_mfma_f32_16x16x32_bf16 v[158:161], v[126:129], v[166:169], v[158:161]
	v_mfma_f32_16x16x32_bf16 v[118:121], v[110:113], v[174:177], v[118:121]
	v_mfma_f32_16x16x32_bf16 v[114:117], v[126:129], v[174:177], v[114:117]
	v_mfma_f32_16x16x32_bf16 v[94:97], v[110:113], v[182:185], v[94:97]
	v_mfma_f32_16x16x32_bf16 v[90:93], v[126:129], v[182:185], v[90:93]
	v_mfma_f32_16x16x32_bf16 v[78:81], v[110:113], v[190:193], v[78:81]
	v_mfma_f32_16x16x32_bf16 v[74:77], v[126:129], v[190:193], v[74:77]
	v_mfma_f32_16x16x32_bf16 v[138:141], v[134:137], v[154:157], v[138:141]
	s_add_i32 s79, s79, s59
	v_mfma_f32_16x16x32_bf16 v[130:133], v[146:149], v[154:157], v[130:133]
	s_mov_b32 m0, s79
	v_mfma_f32_16x16x32_bf16 v[106:109], v[134:137], v[170:173], v[106:109]
	v_mfma_f32_16x16x32_bf16 v[102:105], v[146:149], v[170:173], v[102:105]
	v_mfma_f32_16x16x32_bf16 v[86:89], v[134:137], v[178:181], v[86:89]
	v_mfma_f32_16x16x32_bf16 v[82:85], v[146:149], v[178:181], v[82:85]
	v_mfma_f32_16x16x32_bf16 v[70:73], v[134:137], v[186:189], v[70:73]
	v_mfma_f32_16x16x32_bf16 v[66:69], v[146:149], v[186:189], v[66:69]
	v_mfma_f32_16x16x32_bf16 v[138:141], v[142:145], v[166:169], v[138:141]
	v_mfma_f32_16x16x32_bf16 v[130:133], v[150:153], v[166:169], v[130:133]
	v_mfma_f32_16x16x32_bf16 v[106:109], v[142:145], v[174:177], v[106:109]
	v_mfma_f32_16x16x32_bf16 v[102:105], v[150:153], v[174:177], v[102:105]
	v_mfma_f32_16x16x32_bf16 v[86:89], v[142:145], v[182:185], v[86:89]
	v_mfma_f32_16x16x32_bf16 v[82:85], v[150:153], v[182:185], v[82:85]
	v_mfma_f32_16x16x32_bf16 v[70:73], v[142:145], v[190:193], v[70:73]
	v_mfma_f32_16x16x32_bf16 v[66:69], v[150:153], v[190:193], v[66:69]
	s_barrier
	v_lshl_add_u64 v[242:243], v[242:243], 0, s[34:35]
	ds_read_b128 v[154:157], v240 offset:49152
	ds_read_b128 v[166:169], v240 offset:50176
	ds_read_b128 v[170:173], v240 offset:51200
	ds_read_b128 v[174:177], v240 offset:52224
	ds_read_b128 v[178:181], v240 offset:53248
	ds_read_b128 v[182:185], v240 offset:54272
	ds_read_b128 v[186:189], v240 offset:55296
	ds_read_b128 v[190:193], v240 offset:56320
	global_load_lds_dwordx4 v[242:243], off
	s_add_i32 m0, s79, 0x2000
	s_add_u32 s52, s52, 0xb0080
	v_lshl_add_u64 v[242:243], v[244:245], 0, s[34:35]
	s_addc_u32 s53, s53, 0
	s_add_i32 s79, s80, s59
	global_load_lds_dwordx4 v[242:243], off
	v_lshl_add_u64 v[242:243], s[52:53], 0, v[196:197]
	s_mov_b32 m0, s79
	s_nop 0
	global_load_lds_dwordx4 v[242:243], off
	v_lshl_add_u64 v[242:243], s[52:53], 0, v[198:199]
	s_add_i32 m0, s79, 0x2000
	s_nop 0
	global_load_lds_dwordx4 v[242:243], off
	v_lshl_add_u64 v[242:243], v[246:247], 0, s[36:37]
	s_mov_b32 m0, s67
	s_nop 0
	global_load_lds_dwordx4 v[242:243], off
	v_lshl_add_u64 v[242:243], v[246:247], 0, s[38:39]
	s_mov_b32 m0, s68
	s_nop 0
	global_load_lds_dwordx4 v[242:243], off
	s_waitcnt vmcnt(8)
	s_waitcnt lgkmcnt(0)
	s_barrier
	s_waitcnt lgkmcnt(0)
	v_mfma_f32_16x16x32_bf16 v[62:65], v[98:101], v[154:157], v[62:65]
	v_mfma_f32_16x16x32_bf16 v[58:61], v[122:125], v[154:157], v[58:61]
	v_mfma_f32_16x16x32_bf16 v[46:49], v[98:101], v[170:173], v[46:49]
	v_mfma_f32_16x16x32_bf16 v[42:45], v[122:125], v[170:173], v[42:45]
	v_mfma_f32_16x16x32_bf16 v[30:33], v[98:101], v[178:181], v[30:33]
	v_mfma_f32_16x16x32_bf16 v[26:29], v[122:125], v[178:181], v[26:29]
	v_mfma_f32_16x16x32_bf16 v[14:17], v[98:101], v[186:189], v[14:17]
	v_mfma_f32_16x16x32_bf16 v[10:13], v[122:125], v[186:189], v[10:13]
	v_mfma_f32_16x16x32_bf16 v[62:65], v[110:113], v[166:169], v[62:65]
	v_mfma_f32_16x16x32_bf16 v[58:61], v[126:129], v[166:169], v[58:61]
	v_mfma_f32_16x16x32_bf16 v[46:49], v[110:113], v[174:177], v[46:49]
	v_mfma_f32_16x16x32_bf16 v[42:45], v[126:129], v[174:177], v[42:45]
	v_mfma_f32_16x16x32_bf16 v[30:33], v[110:113], v[182:185], v[30:33]
	v_mfma_f32_16x16x32_bf16 v[26:29], v[126:129], v[182:185], v[26:29]
	v_mfma_f32_16x16x32_bf16 v[14:17], v[110:113], v[190:193], v[14:17]
	v_mfma_f32_16x16x32_bf16 v[10:13], v[126:129], v[190:193], v[10:13]
	v_mfma_f32_16x16x32_bf16 v[54:57], v[134:137], v[154:157], v[54:57]
	s_add_i32 s78, s78, 2
	v_mfma_f32_16x16x32_bf16 v[50:53], v[146:149], v[154:157], v[50:53]
	s_add_u32 s54, s54, 0x100
	v_mfma_f32_16x16x32_bf16 v[38:41], v[134:137], v[170:173], v[38:41]
	s_addc_u32 s55, s55, 0
	v_mfma_f32_16x16x32_bf16 v[34:37], v[146:149], v[170:173], v[34:37]
	s_add_u32 s50, s50, 0x10000
	v_mfma_f32_16x16x32_bf16 v[22:25], v[134:137], v[178:181], v[22:25]
	s_addc_u32 s51, s51, 0
	v_mfma_f32_16x16x32_bf16 v[18:21], v[146:149], v[178:181], v[18:21]
	s_cmp_gt_u32 s78, 41
	v_mfma_f32_16x16x32_bf16 v[6:9], v[134:137], v[186:189], v[6:9]
	v_mfma_f32_16x16x32_bf16 v[2:5], v[146:149], v[186:189], v[2:5]
	v_mfma_f32_16x16x32_bf16 v[54:57], v[142:145], v[166:169], v[54:57]
	v_mfma_f32_16x16x32_bf16 v[50:53], v[150:153], v[166:169], v[50:53]
	v_mfma_f32_16x16x32_bf16 v[38:41], v[142:145], v[174:177], v[38:41]
	v_mfma_f32_16x16x32_bf16 v[34:37], v[150:153], v[174:177], v[34:37]
	v_mfma_f32_16x16x32_bf16 v[22:25], v[142:145], v[182:185], v[22:25]
	v_mfma_f32_16x16x32_bf16 v[18:21], v[150:153], v[182:185], v[18:21]
	v_mfma_f32_16x16x32_bf16 v[6:9], v[142:145], v[190:193], v[6:9]
	v_mfma_f32_16x16x32_bf16 v[2:5], v[150:153], v[190:193], v[2:5]
	s_barrier
	s_cbranch_scc0 .LBB0_540
	s_setprio 0
	s_and_b64 vcc, exec, s[40:41]
	s_cbranch_vccz .LBB0_543
	s_barrier

; #define PG8_STAGE(bufoff, gbase, voff) do { _Pragma("unroll") for (int _i = 0; _i < 2; ++_i) \
;         __builtin_amdgcn_global_load_lds((const unsigned*)((const char*)(gbase) + (voff)[_i]), (PG8_LAS unsigned*)(lds + (bufoff) + ldsw + _i * 8192), 16, 0, 0); } while (0)
; #define PG8_LDA(dst, b, h) do { _Pragma("unroll") for (int m = 0; m < 4; ++m) _Pragma("unroll") for (int k = 0; k < 2; ++k) dst[m][k] = *(const PG8_LAS bf16x8*)(lds + PG8_SA(b, h) + aoff + m * 2048 + k * 1024); } while (0)
; #define PG8_LDB(dst, b, h) do { _Pragma("unroll") for (int n = 0; n < 2; ++n) _Pragma("unroll") for (int k = 0; k < 2; ++k) dst[n][k] = *(const PG8_LAS bf16x8*)(lds + PG8_SB(b, h) + boff + n * 2048 + k * 1024); } while (0)
; #define PG8_WAIT_V(n) asm volatile("s_waitcnt vmcnt(" #n ")" ::: "memory")
; #define PG8_WAIT_L(n) asm volatile("s_waitcnt lgkmcnt(" #n ")" ::: "memory")
; #define PG8_BAR __builtin_amdgcn_s_barrier()
; template <class Epi, bool ALIGN_EPI, bool ABLK = false>
; __device__ __forceinline__ void gemm_phase(PG8_LAS unsigned char* lds, const Gemm g, const StaticOrder& S, const Epi& E) {
;     ...
;         const bool has_next = S.next(ui + 1, nxt);
;         const char* nA = has_next ? PG8_ABASE(nxt) : cA; const char* nB = has_next ? PG8_BBASE(nxt) : cB;
;         for (int t = 0; t < nt; t += 2) {
;             const bool last = (t == nt - 2);
;             const char* a1 = cA + (size_t)(t + 1) * kstepA;
;             const char* a2 = last ? nA : cA + (size_t)(t + 2) * kstepA; const char* b2 = last ? nB : cB + (size_t)(t + 2) * kstepB;
;             const char* a3 = a2 + kstepA; const char* b3 = b2 + kstepB;
;             PG8_LDB(B0, 0, 0); PG8_LDB(B1, 0, 1); PG8_SCHED; PG8_LDA(At, 0, 0); PG8_STAGE(PG8_SA(1, 1), a1 + hstepA, voffA);
;             PG8_WAIT_V(8); PG8_WAIT_L(0); PG8_BAR; PG8_MMA(0, 0, At, B0); PG8_MMA(0, 1, At, B1); PG8_BAR; PG8_SCHED;
;             PG8_LDA(At, 0, 1); PG8_STAGE(PG8_SB(0, 0), b2, voffB); PG8_STAGE(PG8_SB(0, 1), b2 + hstepB, voffB); PG8_STAGE(PG8_SA(0, 0), a2, voffA);
;             PG8_WAIT_V(8); PG8_WAIT_L(0); PG8_BAR; PG8_MMA(1, 0, At, B0); PG8_MMA(1, 1, At, B1); PG8_BAR; PG8_SCHED;
;             PG8_LDB(B0, 1, 0); PG8_LDB(B1, 1, 1); PG8_SCHED; PG8_LDA(At, 1, 0); PG8_STAGE(PG8_SA(0, 1), a2 + hstepA, voffA);
;             PG8_WAIT_V(8); PG8_WAIT_L(0); PG8_BAR; PG8_MMA(0, 0, At, B0); PG8_MMA(0, 1, At, B1); PG8_BAR; PG8_SCHED;
.LBB0_817:
	s_ashr_i32 s57, s56, 31
	s_lshl_b64 s[10:11], s[56:57], 19
	s_add_u32 s58, s74, s10
	s_addc_u32 s59, s75, s11
	s_and_b64 s[10:11], s[8:9], exec
	s_cselect_b32 s33, s59, s39
	s_cselect_b32 s57, s58, s38
	s_ashr_i32 s55, s54, 31
	s_lshl_b64 s[10:11], s[54:55], 19
	s_add_u32 s60, s14, s10
	s_addc_u32 s61, s15, s11
	s_and_b64 s[10:11], s[8:9], exec
	s_cselect_b32 s55, s61, s37
	s_cselect_b32 s62, s60, s36
	s_add_u32 s63, s36, 0x100
	s_addc_u32 s64, s37, 0
	s_mov_b32 s65, -2
	s_mov_b64 s[10:11], 0x10000
	v_add_u32_e32 v248, 0x2000, v154
	v_add_u32_e32 v249, 0x4000, v154
	v_add_u32_e32 v250, 0x6000, v154
	v_add_u32_e32 v251, 0x8000, v154
	v_add_u32_e32 v252, 0xa000, v154
	v_add_u32_e32 v253, 0xc000, v154
	v_add_u32_e32 v152, 0xe000, v154
	v_add_u32_e32 v153, 0x10000, v197
	s_setprio 0
	v_readfirstlane_b32 s101, v0
	s_nop 3
	s_bfe_u32 s101, s101, 0x40006
	s_cmp_ge_u32 s101, 4
	s_cbranch_scc0 .Lprio_818
	s_setprio 1
.Lprio_818:
.LBB0_818:
	ds_read_b128 v[132:135], v153
	ds_read_b128 v[136:139], v153 offset:1024
	ds_read_b128 v[140:143], v153 offset:2048
	ds_read_b128 v[144:147], v153 offset:3072
	ds_read_b128 v[148:151], v153 offset:16384
	ds_read_b128 v[178:181], v153 offset:17408
	ds_read_b128 v[182:185], v153 offset:18432
	ds_read_b128 v[212:215], v153 offset:19456
	s_add_u32 s12, s38, s10
	s_addc_u32 s13, s39, s11
	s_sub_u32 s98, s12, 0x10000
	s_subb_u32 s99, s13, 0
	s_cmp_eq_u32 s65, 12
	s_cselect_b32 s101, s33, s13
	s_cselect_b32 s100, s57, s12
	s_cselect_b32 s13, s55, s64
	s_cselect_b32 s12, s62, s63
	s_mov_b64 s[68:69], 0xc000
	s_add_i32 m0, s35, 0xc000
	s_mov_b64 s[68:69], 0xe000
	ds_read_b128 v[216:219], v205
	ds_read_b128 v[220:223], v205 offset:1024
	ds_read_b128 v[224:227], v205 offset:2048
	ds_read_b128 v[228:231], v205 offset:3072
	ds_read_b128 v[232:235], v205 offset:4096
	ds_read_b128 v[236:239], v205 offset:5120
	ds_read_b128 v[240:243], v205 offset:6144
	ds_read_b128 v[244:247], v205 offset:7168
	global_load_lds_dwordx4 v253, s[98:99]
	s_add_i32 m0, s35, 0xe000
	s_nop 0
	global_load_lds_dwordx4 v152, s[98:99]
	s_waitcnt vmcnt(8)
	s_waitcnt lgkmcnt(0)
	s_barrier
	s_waitcnt lgkmcnt(0)
	v_mfma_f32_16x16x32_bf16 v[126:129], v[132:135], v[216:219], v[126:129]
	v_mfma_f32_16x16x32_bf16 v[122:125], v[140:143], v[216:219], v[122:125]
	v_mfma_f32_16x16x32_bf16 v[118:121], v[132:135], v[224:227], v[118:121]
	v_mfma_f32_16x16x32_bf16 v[114:117], v[140:143], v[224:227], v[114:117]
	v_mfma_f32_16x16x32_bf16 v[110:113], v[132:135], v[232:235], v[110:113]
	v_mfma_f32_16x16x32_bf16 v[106:109], v[140:143], v[232:235], v[106:109]
	v_mfma_f32_16x16x32_bf16 v[102:105], v[132:135], v[240:243], v[102:105]
	v_mfma_f32_16x16x32_bf16 v[98:101], v[140:143], v[240:243], v[98:101]
	v_mfma_f32_16x16x32_bf16 v[126:129], v[136:139], v[220:223], v[126:129]
	v_mfma_f32_16x16x32_bf16 v[122:125], v[144:147], v[220:223], v[122:125]
	v_mfma_f32_16x16x32_bf16 v[118:121], v[136:139], v[228:231], v[118:121]
	v_mfma_f32_16x16x32_bf16 v[114:117], v[144:147], v[228:231], v[114:117]
	v_mfma_f32_16x16x32_bf16 v[110:113], v[136:139], v[236:239], v[110:113]
	v_mfma_f32_16x16x32_bf16 v[106:109], v[144:147], v[236:239], v[106:109]
	v_mfma_f32_16x16x32_bf16 v[102:105], v[136:139], v[244:247], v[102:105]
	v_mfma_f32_16x16x32_bf16 v[98:101], v[144:147], v[244:247], v[98:101]
	v_mfma_f32_16x16x32_bf16 v[94:97], v[148:151], v[216:219], v[94:97]
	s_add_i32 s68, s42, s31
	v_mfma_f32_16x16x32_bf16 v[90:93], v[182:185], v[216:219], v[90:93]
	s_mov_b32 m0, s68
	v_mfma_f32_16x16x32_bf16 v[86:89], v[148:151], v[224:227], v[86:89]
	v_mfma_f32_16x16x32_bf16 v[82:85], v[182:185], v[224:227], v[82:85]
	v_mfma_f32_16x16x32_bf16 v[78:81], v[148:151], v[232:235], v[78:81]
	v_mfma_f32_16x16x32_bf16 v[74:77], v[182:185], v[232:235], v[74:77]
	v_mfma_f32_16x16x32_bf16 v[70:73], v[148:151], v[240:243], v[70:73]
	v_mfma_f32_16x16x32_bf16 v[66:69], v[182:185], v[240:243], v[66:69]
	v_mfma_f32_16x16x32_bf16 v[94:97], v[178:181], v[220:223], v[94:97]
	v_mfma_f32_16x16x32_bf16 v[90:93], v[212:215], v[220:223], v[90:93]
	v_mfma_f32_16x16x32_bf16 v[86:89], v[178:181], v[228:231], v[86:89]
	v_mfma_f32_16x16x32_bf16 v[82:85], v[212:215], v[228:231], v[82:85]
	v_mfma_f32_16x16x32_bf16 v[78:81], v[178:181], v[236:239], v[78:81]
	v_mfma_f32_16x16x32_bf16 v[74:77], v[212:215], v[236:239], v[74:77]
	v_mfma_f32_16x16x32_bf16 v[70:73], v[178:181], v[244:247], v[70:73]
	v_mfma_f32_16x16x32_bf16 v[66:69], v[212:215], v[244:247], v[66:69]
	s_barrier
	ds_read_b128 v[216:219], v205 offset:16384
	ds_read_b128 v[220:223], v205 offset:17408
	ds_read_b128 v[224:227], v205 offset:18432
	ds_read_b128 v[228:231], v205 offset:19456
	ds_read_b128 v[232:235], v205 offset:20480
	ds_read_b128 v[236:239], v205 offset:21504
	ds_read_b128 v[240:243], v205 offset:22528
	ds_read_b128 v[244:247], v205 offset:23552
	global_load_lds_dwordx4 v156, s[12:13]
	s_add_i32 m0, s68, 0x2000
	s_add_u32 s68, s12, 0x40000
	s_addc_u32 s69, s13, 0
	s_add_i32 s70, s43, s31
	global_load_lds_dwordx4 v158, s[12:13]
	s_mov_b32 m0, s70
	s_nop 0
	global_load_lds_dwordx4 v156, s[68:69]
	s_add_i32 m0, s70, 0x2000
	s_nop 0
	global_load_lds_dwordx4 v158, s[68:69]
	s_mov_b32 m0, s35
	s_mov_b64 s[66:67], 0x2000
	global_load_lds_dwordx4 v154, s[100:101]
	s_mov_b32 m0, s18
	s_nop 0
	global_load_lds_dwordx4 v248, s[100:101]
	s_waitcnt vmcnt(8)
	s_waitcnt lgkmcnt(0)
	s_barrier
; #define PG8_STAGE(bufoff, gbase, voff) do { _Pragma("unroll") for (int _i = 0; _i < 2; ++_i) \
;         __builtin_amdgcn_global_load_lds((const unsigned*)((const char*)(gbase) + (voff)[_i]), (PG8_LAS unsigned*)(lds + (bufoff) + ldsw + _i * 8192), 16, 0, 0); } while (0)
; #define PG8_LDA(dst, b, h) do { _Pragma("unroll") for (int m = 0; m < 4; ++m) _Pragma("unroll") for (int k = 0; k < 2; ++k) dst[m][k] = *(const PG8_LAS bf16x8*)(lds + PG8_SA(b, h) + aoff + m * 2048 + k * 1024); } while (0)
; #define PG8_LDB(dst, b, h) do { _Pragma("unroll") for (int n = 0; n < 2; ++n) _Pragma("unroll") for (int k = 0; k < 2; ++k) dst[n][k] = *(const PG8_LAS bf16x8*)(lds + PG8_SB(b, h) + boff + n * 2048 + k * 1024); } while (0)
; #define PG8_MMA(ai, bj, At, Bt) do { __builtin_amdgcn_s_setprio(1); _Pragma("unroll") for (int m = 0; m < 4; ++m) _Pragma("unroll") for (int n = 0; n < 2; ++n) _Pragma("unroll") for (int k = 0; k < 2; ++k) \
;         acc[ai][bj][m][n] = __builtin_amdgcn_mfma_f32_16x16x32_bf16(Bt[n][k], At[m][k], acc[ai][bj][m][n], 0, 0, 0); __builtin_amdgcn_s_setprio(0); } while (0)
; #define PG8_WAIT_V(n) asm volatile("s_waitcnt vmcnt(" #n ")" ::: "memory")
; #define PG8_WAIT_L(n) asm volatile("s_waitcnt lgkmcnt(" #n ")" ::: "memory")
; #define PG8_BAR __builtin_amdgcn_s_barrier()
; #define PG8_SCHED __builtin_amdgcn_sched_barrier(0)
; template <class Epi, bool ALIGN_EPI, bool ABLK = false>
; __device__ __forceinline__ void gemm_phase(PG8_LAS unsigned char* lds, const Gemm g, const StaticOrder& S, const Epi& E) {
;     ...
;             PG8_WAIT_V(8); PG8_WAIT_L(0); PG8_BAR; PG8_MMA(1, 0, At, B0); PG8_MMA(1, 1, At, B1); PG8_BAR; PG8_SCHED;
;             PG8_LDB(B0, 1, 0); PG8_LDB(B1, 1, 1); PG8_SCHED; PG8_LDA(At, 1, 0); PG8_STAGE(PG8_SA(0, 1), a2 + hstepA, voffA);
;             PG8_WAIT_V(8); PG8_WAIT_L(0); PG8_BAR; PG8_MMA(0, 0, At, B0); PG8_MMA(0, 1, At, B1); PG8_BAR; PG8_SCHED;
	s_waitcnt lgkmcnt(0)
	v_mfma_f32_16x16x32_bf16 v[62:65], v[132:135], v[216:219], v[62:65]
	v_mfma_f32_16x16x32_bf16 v[58:61], v[140:143], v[216:219], v[58:61]
	v_mfma_f32_16x16x32_bf16 v[54:57], v[132:135], v[224:227], v[54:57]
	v_mfma_f32_16x16x32_bf16 v[50:53], v[140:143], v[224:227], v[50:53]
	v_mfma_f32_16x16x32_bf16 v[46:49], v[132:135], v[232:235], v[46:49]
	v_mfma_f32_16x16x32_bf16 v[42:45], v[140:143], v[232:235], v[42:45]
	v_mfma_f32_16x16x32_bf16 v[38:41], v[132:135], v[240:243], v[38:41]
	v_mfma_f32_16x16x32_bf16 v[34:37], v[140:143], v[240:243], v[34:37]
	v_mfma_f32_16x16x32_bf16 v[62:65], v[136:139], v[220:223], v[62:65]
	v_mfma_f32_16x16x32_bf16 v[58:61], v[144:147], v[220:223], v[58:61]
	v_mfma_f32_16x16x32_bf16 v[54:57], v[136:139], v[228:231], v[54:57]
	v_mfma_f32_16x16x32_bf16 v[50:53], v[144:147], v[228:231], v[50:53]
	v_mfma_f32_16x16x32_bf16 v[46:49], v[136:139], v[236:239], v[46:49]
	v_mfma_f32_16x16x32_bf16 v[42:45], v[144:147], v[236:239], v[42:45]
	v_mfma_f32_16x16x32_bf16 v[38:41], v[136:139], v[244:247], v[38:41]
	v_mfma_f32_16x16x32_bf16 v[34:37], v[144:147], v[244:247], v[34:37]
	v_mfma_f32_16x16x32_bf16 v[30:33], v[148:151], v[216:219], v[30:33]
	s_add_i32 s68, 0, 0x18000
	v_mfma_f32_16x16x32_bf16 v[26:29], v[182:185], v[216:219], v[26:29]
	s_add_i32 s69, 0, 0x1c000
	v_mfma_f32_16x16x32_bf16 v[22:25], v[148:151], v[224:227], v[22:25]
	v_mfma_f32_16x16x32_bf16 v[18:21], v[182:185], v[224:227], v[18:21]
	v_mfma_f32_16x16x32_bf16 v[14:17], v[148:151], v[232:235], v[14:17]
	v_mfma_f32_16x16x32_bf16 v[10:13], v[182:185], v[232:235], v[10:13]
	v_mfma_f32_16x16x32_bf16 v[6:9], v[148:151], v[240:243], v[6:9]
	v_mfma_f32_16x16x32_bf16 v[2:5], v[182:185], v[240:243], v[2:5]
	v_mfma_f32_16x16x32_bf16 v[30:33], v[178:181], v[220:223], v[30:33]
	v_mfma_f32_16x16x32_bf16 v[26:29], v[212:215], v[220:223], v[26:29]
	v_mfma_f32_16x16x32_bf16 v[22:25], v[178:181], v[228:231], v[22:25]
	v_mfma_f32_16x16x32_bf16 v[18:21], v[212:215], v[228:231], v[18:21]
	v_mfma_f32_16x16x32_bf16 v[14:17], v[178:181], v[236:239], v[14:17]
	v_mfma_f32_16x16x32_bf16 v[10:13], v[212:215], v[236:239], v[10:13]
	v_mfma_f32_16x16x32_bf16 v[6:9], v[178:181], v[244:247], v[6:9]
	v_mfma_f32_16x16x32_bf16 v[2:5], v[212:215], v[244:247], v[2:5]
	s_barrier
	ds_read_b128 v[132:135], v153 offset:32768
	ds_read_b128 v[136:139], v153 offset:33792
	ds_read_b128 v[140:143], v153 offset:34816
	ds_read_b128 v[144:147], v153 offset:35840
	ds_read_b128 v[148:151], v153 offset:49152
	ds_read_b128 v[178:181], v153 offset:50176
	ds_read_b128 v[182:185], v153 offset:51200
	ds_read_b128 v[212:215], v153 offset:52224
	s_mov_b64 s[66:67], 0x4000
	s_mov_b32 m0, s28
	s_mov_b64 s[66:67], 0x6000
	ds_read_b128 v[216:219], v205 offset:32768
	ds_read_b128 v[220:223], v205 offset:33792
	ds_read_b128 v[224:227], v205 offset:34816
	ds_read_b128 v[228:231], v205 offset:35840
	ds_read_b128 v[232:235], v205 offset:36864
	ds_read_b128 v[236:239], v205 offset:37888
	ds_read_b128 v[240:243], v205 offset:38912
	ds_read_b128 v[244:247], v205 offset:39936
	global_load_lds_dwordx4 v249, s[100:101]
	s_mov_b32 m0, s29
	s_nop 0
	global_load_lds_dwordx4 v250, s[100:101]
	s_waitcnt vmcnt(8)
	s_waitcnt lgkmcnt(0)
	s_barrier
	s_waitcnt lgkmcnt(0)
	v_mfma_f32_16x16x32_bf16 v[126:129], v[132:135], v[216:219], v[126:129]
	v_mfma_f32_16x16x32_bf16 v[122:125], v[140:143], v[216:219], v[122:125]
	v_mfma_f32_16x16x32_bf16 v[118:121], v[132:135], v[224:227], v[118:121]
	v_mfma_f32_16x16x32_bf16 v[114:117], v[140:143], v[224:227], v[114:117]
	v_mfma_f32_16x16x32_bf16 v[110:113], v[132:135], v[232:235], v[110:113]
	v_mfma_f32_16x16x32_bf16 v[106:109], v[140:143], v[232:235], v[106:109]
	v_mfma_f32_16x16x32_bf16 v[102:105], v[132:135], v[240:243], v[102:105]
	v_mfma_f32_16x16x32_bf16 v[98:101], v[140:143], v[240:243], v[98:101]
	v_mfma_f32_16x16x32_bf16 v[126:129], v[136:139], v[220:223], v[126:129]
	v_mfma_f32_16x16x32_bf16 v[122:125], v[144:147], v[220:223], v[122:125]
	v_mfma_f32_16x16x32_bf16 v[118:121], v[136:139], v[228:231], v[118:121]
	v_mfma_f32_16x16x32_bf16 v[114:117], v[144:147], v[228:231], v[114:117]
	v_mfma_f32_16x16x32_bf16 v[110:113], v[136:139], v[236:239], v[110:113]
	v_mfma_f32_16x16x32_bf16 v[106:109], v[144:147], v[236:239], v[106:109]
	v_mfma_f32_16x16x32_bf16 v[102:105], v[136:139], v[244:247], v[102:105]
	v_mfma_f32_16x16x32_bf16 v[98:101], v[144:147], v[244:247], v[98:101]
	v_mfma_f32_16x16x32_bf16 v[94:97], v[148:151], v[216:219], v[94:97]
	s_add_i32 s66, s68, s31
	v_mfma_f32_16x16x32_bf16 v[90:93], v[182:185], v[216:219], v[90:93]
	s_add_u32 s12, s12, s46
	v_mfma_f32_16x16x32_bf16 v[86:89], v[148:151], v[224:227], v[86:89]
	s_addc_u32 s13, s13, s47
	v_mfma_f32_16x16x32_bf16 v[82:85], v[182:185], v[224:227], v[82:85]
	s_mov_b32 m0, s66
	v_mfma_f32_16x16x32_bf16 v[78:81], v[148:151], v[232:235], v[78:81]
	v_mfma_f32_16x16x32_bf16 v[74:77], v[182:185], v[232:235], v[74:77]
	v_mfma_f32_16x16x32_bf16 v[70:73], v[148:151], v[240:243], v[70:73]
	v_mfma_f32_16x16x32_bf16 v[66:69], v[182:185], v[240:243], v[66:69]
	v_mfma_f32_16x16x32_bf16 v[94:97], v[178:181], v[220:223], v[94:97]
	v_mfma_f32_16x16x32_bf16 v[90:93], v[212:215], v[220:223], v[90:93]
	v_mfma_f32_16x16x32_bf16 v[86:89], v[178:181], v[228:231], v[86:89]
	v_mfma_f32_16x16x32_bf16 v[82:85], v[212:215], v[228:231], v[82:85]
	v_mfma_f32_16x16x32_bf16 v[78:81], v[178:181], v[236:239], v[78:81]
	v_mfma_f32_16x16x32_bf16 v[74:77], v[212:215], v[236:239], v[74:77]
	v_mfma_f32_16x16x32_bf16 v[70:73], v[178:181], v[244:247], v[70:73]
	v_mfma_f32_16x16x32_bf16 v[66:69], v[212:215], v[244:247], v[66:69]
	s_barrier
; #define PG8_STAGE(bufoff, gbase, voff) do { _Pragma("unroll") for (int _i = 0; _i < 2; ++_i) \
;         __builtin_amdgcn_global_load_lds((const unsigned*)((const char*)(gbase) + (voff)[_i]), (PG8_LAS unsigned*)(lds + (bufoff) + ldsw + _i * 8192), 16, 0, 0); } while (0)
; #define PG8_LDA(dst, b, h) do { _Pragma("unroll") for (int m = 0; m < 4; ++m) _Pragma("unroll") for (int k = 0; k < 2; ++k) dst[m][k] = *(const PG8_LAS bf16x8*)(lds + PG8_SA(b, h) + aoff + m * 2048 + k * 1024); } while (0)
; #define PG8_MMA(ai, bj, At, Bt) do { __builtin_amdgcn_s_setprio(1); _Pragma("unroll") for (int m = 0; m < 4; ++m) _Pragma("unroll") for (int n = 0; n < 2; ++n) _Pragma("unroll") for (int k = 0; k < 2; ++k) \
;         acc[ai][bj][m][n] = __builtin_amdgcn_mfma_f32_16x16x32_bf16(Bt[n][k], At[m][k], acc[ai][bj][m][n], 0, 0, 0); __builtin_amdgcn_s_setprio(0); } while (0)
; #define PG8_WAIT_V(n) asm volatile("s_waitcnt vmcnt(" #n ")" ::: "memory")
; #define PG8_WAIT_L(n) asm volatile("s_waitcnt lgkmcnt(" #n ")" ::: "memory")
; #define PG8_BAR __builtin_amdgcn_s_barrier()
; #define PG8_SCHED __builtin_amdgcn_sched_barrier(0)
; template <class Epi, bool ALIGN_EPI, bool ABLK = false>
; __device__ __forceinline__ void gemm_phase(PG8_LAS unsigned char* lds, const Gemm g, const StaticOrder& S, const Epi& E) {
;     ...
;             PG8_LDA(At, 1, 1); PG8_STAGE(PG8_SB(1, 0), b3, voffB); PG8_STAGE(PG8_SB(1, 1), b3 + hstepB, voffB); PG8_STAGE(PG8_SA(1, 0), a3, voffA);
;             PG8_WAIT_V(8); PG8_WAIT_L(0); PG8_BAR; PG8_MMA(1, 0, At, B0); PG8_MMA(1, 1, At, B1); PG8_BAR; PG8_SCHED;
;         }
;         if constexpr (ALIGN_EPI) { if (wr == 0) PG8_BAR; }
	ds_read_b128 v[216:219], v205 offset:49152
	ds_read_b128 v[220:223], v205 offset:50176
	ds_read_b128 v[224:227], v205 offset:51200
	ds_read_b128 v[228:231], v205 offset:52224
	ds_read_b128 v[232:235], v205 offset:53248
	ds_read_b128 v[236:239], v205 offset:54272
	ds_read_b128 v[240:243], v205 offset:55296
	ds_read_b128 v[244:247], v205 offset:56320
	global_load_lds_dwordx4 v156, s[12:13]
	s_add_i32 m0, s66, 0x2000
	s_add_i32 s66, s69, s31
	global_load_lds_dwordx4 v158, s[12:13]
	s_add_u32 s12, s12, 0x40000
	s_addc_u32 s13, s13, 0
	s_mov_b32 m0, s66
	s_nop 0
	global_load_lds_dwordx4 v156, s[12:13]
	s_add_i32 m0, s66, 0x2000
	s_nop 0
	global_load_lds_dwordx4 v158, s[12:13]
	s_mov_b32 m0, s0
	s_nop 0
	global_load_lds_dwordx4 v251, s[100:101]
	s_mov_b32 m0, s1
	s_nop 0
	global_load_lds_dwordx4 v252, s[100:101]
	s_waitcnt vmcnt(8)
	s_waitcnt lgkmcnt(0)
	s_barrier
	s_waitcnt lgkmcnt(0)
	v_mfma_f32_16x16x32_bf16 v[62:65], v[132:135], v[216:219], v[62:65]
	v_mfma_f32_16x16x32_bf16 v[58:61], v[140:143], v[216:219], v[58:61]
	v_mfma_f32_16x16x32_bf16 v[54:57], v[132:135], v[224:227], v[54:57]
	v_mfma_f32_16x16x32_bf16 v[50:53], v[140:143], v[224:227], v[50:53]
	v_mfma_f32_16x16x32_bf16 v[46:49], v[132:135], v[232:235], v[46:49]
	v_mfma_f32_16x16x32_bf16 v[42:45], v[140:143], v[232:235], v[42:45]
	v_mfma_f32_16x16x32_bf16 v[38:41], v[132:135], v[240:243], v[38:41]
	v_mfma_f32_16x16x32_bf16 v[34:37], v[140:143], v[240:243], v[34:37]
	v_mfma_f32_16x16x32_bf16 v[62:65], v[136:139], v[220:223], v[62:65]
	v_mfma_f32_16x16x32_bf16 v[58:61], v[144:147], v[220:223], v[58:61]
	v_mfma_f32_16x16x32_bf16 v[54:57], v[136:139], v[228:231], v[54:57]
	v_mfma_f32_16x16x32_bf16 v[50:53], v[144:147], v[228:231], v[50:53]
	v_mfma_f32_16x16x32_bf16 v[46:49], v[136:139], v[236:239], v[46:49]
	v_mfma_f32_16x16x32_bf16 v[42:45], v[144:147], v[236:239], v[42:45]
	v_mfma_f32_16x16x32_bf16 v[38:41], v[136:139], v[244:247], v[38:41]
	v_mfma_f32_16x16x32_bf16 v[34:37], v[144:147], v[244:247], v[34:37]
	v_mfma_f32_16x16x32_bf16 v[30:33], v[148:151], v[216:219], v[30:33]
	s_add_i32 s65, s65, 2
	v_mfma_f32_16x16x32_bf16 v[26:29], v[182:185], v[216:219], v[26:29]
	s_add_u32 s63, s63, 0x100
	v_mfma_f32_16x16x32_bf16 v[22:25], v[148:151], v[224:227], v[22:25]
	s_addc_u32 s64, s64, 0
	v_mfma_f32_16x16x32_bf16 v[18:21], v[182:185], v[224:227], v[18:21]
	s_add_u32 s10, s10, 0x10000
	v_mfma_f32_16x16x32_bf16 v[14:17], v[148:151], v[232:235], v[14:17]
	s_addc_u32 s11, s11, 0
	v_mfma_f32_16x16x32_bf16 v[10:13], v[182:185], v[232:235], v[10:13]
	s_mov_b64 s[12:13], 0x10000
	v_mfma_f32_16x16x32_bf16 v[6:9], v[148:151], v[240:243], v[6:9]
	s_cmp_gt_u32 s65, 13
	v_mfma_f32_16x16x32_bf16 v[2:5], v[182:185], v[240:243], v[2:5]
	v_mfma_f32_16x16x32_bf16 v[30:33], v[178:181], v[220:223], v[30:33]
	v_mfma_f32_16x16x32_bf16 v[26:29], v[212:215], v[220:223], v[26:29]
	v_mfma_f32_16x16x32_bf16 v[22:25], v[178:181], v[228:231], v[22:25]
	v_mfma_f32_16x16x32_bf16 v[18:21], v[212:215], v[228:231], v[18:21]
	v_mfma_f32_16x16x32_bf16 v[14:17], v[178:181], v[236:239], v[14:17]
	v_mfma_f32_16x16x32_bf16 v[10:13], v[212:215], v[236:239], v[10:13]
	v_mfma_f32_16x16x32_bf16 v[6:9], v[178:181], v[244:247], v[6:9]
	v_mfma_f32_16x16x32_bf16 v[2:5], v[212:215], v[244:247], v[2:5]
	s_barrier
	s_cbranch_scc0 .LBB0_818
	s_setprio 0
	s_and_b64 vcc, exec, s[52:53]
	s_cbranch_vccz .LBB0_821
	s_barrier

; #define PG8_STAGE(bufoff, gbase, voff) do { _Pragma("unroll") for (int _i = 0; _i < 2; ++_i) \
;         __builtin_amdgcn_global_load_lds((const unsigned*)((const char*)(gbase) + (voff)[_i]), (PG8_LAS unsigned*)(lds + (bufoff) + ldsw + _i * 8192), 16, 0, 0); } while (0)
; #define PG8_LDA(dst, b, h) do { _Pragma("unroll") for (int m = 0; m < 4; ++m) _Pragma("unroll") for (int k = 0; k < 2; ++k) dst[m][k] = *(const PG8_LAS bf16x8*)(lds + PG8_SA(b, h) + aoff + m * 2048 + k * 1024); } while (0)
; #define PG8_LDB(dst, b, h) do { _Pragma("unroll") for (int n = 0; n < 2; ++n) _Pragma("unroll") for (int k = 0; k < 2; ++k) dst[n][k] = *(const PG8_LAS bf16x8*)(lds + PG8_SB(b, h) + boff + n * 2048 + k * 1024); } while (0)
; #define PG8_WAIT_V(n) asm volatile("s_waitcnt vmcnt(" #n ")" ::: "memory")
; #define PG8_WAIT_L(n) asm volatile("s_waitcnt lgkmcnt(" #n ")" ::: "memory")
; #define PG8_BAR __builtin_amdgcn_s_barrier()
; template <class Epi, bool ALIGN_EPI, bool ABLK = false>
; __device__ __forceinline__ void gemm_phase(PG8_LAS unsigned char* lds, const Gemm g, const StaticOrder& S, const Epi& E) {
;     ...
;         const bool has_next = S.next(ui + 1, nxt);
;         const char* nA = has_next ? PG8_ABASE(nxt) : cA; const char* nB = has_next ? PG8_BBASE(nxt) : cB;
;         for (int t = 0; t < nt; t += 2) {
;             const bool last = (t == nt - 2);
;             const char* a1 = cA + (size_t)(t + 1) * kstepA;
;             const char* a2 = last ? nA : cA + (size_t)(t + 2) * kstepA; const char* b2 = last ? nB : cB + (size_t)(t + 2) * kstepB;
;             const char* a3 = a2 + kstepA; const char* b3 = b2 + kstepB;
;             PG8_LDB(B0, 0, 0); PG8_LDB(B1, 0, 1); PG8_SCHED; PG8_LDA(At, 0, 0); PG8_STAGE(PG8_SA(1, 1), a1 + hstepA, voffA);
;             PG8_WAIT_V(8); PG8_WAIT_L(0); PG8_BAR; PG8_MMA(0, 0, At, B0); PG8_MMA(0, 1, At, B1); PG8_BAR; PG8_SCHED;
;             PG8_LDA(At, 0, 1); PG8_STAGE(PG8_SB(0, 0), b2, voffB); PG8_STAGE(PG8_SB(0, 1), b2 + hstepB, voffB); PG8_STAGE(PG8_SA(0, 0), a2, voffA);
;             PG8_WAIT_V(8); PG8_WAIT_L(0); PG8_BAR; PG8_MMA(1, 0, At, B0); PG8_MMA(1, 1, At, B1); PG8_BAR; PG8_SCHED;
;             PG8_LDB(B0, 1, 0); PG8_LDB(B1, 1, 1); PG8_SCHED; PG8_LDA(At, 1, 0); PG8_STAGE(PG8_SA(0, 1), a2 + hstepA, voffA);
;             PG8_WAIT_V(8); PG8_WAIT_L(0); PG8_BAR; PG8_MMA(0, 0, At, B0); PG8_MMA(0, 1, At, B1); PG8_BAR; PG8_SCHED;
.LBB0_1982:
	s_ashr_i32 s55, s54, 31
	s_lshl_b64 s[56:57], s[54:55], 19
	s_add_u32 s56, s14, s56
	s_addc_u32 s57, s15, s57
	s_and_b64 s[58:59], s[6:7], exec
	s_cselect_b32 s55, s57, s27
	s_cselect_b32 s75, s56, s26
	s_ashr_i32 s53, s52, 31
	s_lshl_b64 s[58:59], s[52:53], 19
	s_add_u32 s58, s18, s58
	s_addc_u32 s59, s19, s59
	s_and_b64 s[60:61], s[6:7], exec
	s_cselect_b32 s53, s59, s25
	s_cselect_b32 s76, s58, s24
	s_add_u32 s77, s24, 0x100
	s_addc_u32 s78, s25, 0
	s_mov_b32 s79, -2
	s_mov_b64 s[60:61], 0x10000
	v_mov_b64_e32 v[130:131], v[138:139]
	s_setprio 0
	v_readfirstlane_b32 s101, v0
	s_nop 3
	s_bfe_u32 s101, s101, 0x40006
	s_cmp_ge_u32 s101, 4
	s_cbranch_scc0 .Lprio_1983
	s_setprio 1
.Lprio_1983:
.LBB0_1983:
	v_add_u32_e32 v136, s71, v179
	ds_read_b128 v[132:135], v136
	ds_read_b128 v[184:187], v136 offset:1024
	ds_read_b128 v[188:191], v136 offset:2048
	ds_read_b128 v[192:195], v136 offset:3072
	v_add_u32_e32 v136, s72, v179
	ds_read_b128 v[196:199], v136
	ds_read_b128 v[200:203], v136 offset:1024
	ds_read_b128 v[204:207], v136 offset:2048
	ds_read_b128 v[208:211], v136 offset:3072
	s_add_u32 s62, s26, s60
	s_addc_u32 s63, s27, s61
	s_cmp_eq_u32 s79, 12
	s_cselect_b32 s81, s55, s63
	s_cselect_b32 s80, s75, s62
	s_cselect_b32 s63, s53, s78
	s_cselect_b32 s62, s76, s77
	v_lshl_add_u64 v[136:137], s[26:27], 0, v[130:131]
	v_lshl_add_u64 v[244:245], v[136:137], 0, s[40:41]
	s_add_i32 m0, s23, 0xc000
	ds_read_b128 v[212:215], v182
	ds_read_b128 v[216:219], v182 offset:1024
	ds_read_b128 v[220:223], v182 offset:2048
	ds_read_b128 v[224:227], v182 offset:3072
	ds_read_b128 v[228:231], v182 offset:4096
	ds_read_b128 v[232:235], v182 offset:5120
	ds_read_b128 v[236:239], v182 offset:6144
	ds_read_b128 v[240:243], v182 offset:7168
	global_load_lds_dwordx4 v[244:245], off
	v_lshl_add_u64 v[136:137], v[136:137], 0, s[42:43]
	s_add_i32 m0, s23, 0xe000
	s_nop 0
	global_load_lds_dwordx4 v[136:137], off
	s_waitcnt vmcnt(8)
	s_waitcnt lgkmcnt(0)
	s_barrier
	s_waitcnt lgkmcnt(0)
	v_mfma_f32_16x16x32_bf16 v[126:129], v[132:135], v[212:215], v[126:129]
	v_mfma_f32_16x16x32_bf16 v[122:125], v[188:191], v[212:215], v[122:125]
	v_mfma_f32_16x16x32_bf16 v[118:121], v[132:135], v[220:223], v[118:121]
	v_mfma_f32_16x16x32_bf16 v[114:117], v[188:191], v[220:223], v[114:117]
	v_mfma_f32_16x16x32_bf16 v[110:113], v[132:135], v[228:231], v[110:113]
	v_mfma_f32_16x16x32_bf16 v[106:109], v[188:191], v[228:231], v[106:109]
	v_mfma_f32_16x16x32_bf16 v[102:105], v[132:135], v[236:239], v[102:105]
	v_mfma_f32_16x16x32_bf16 v[98:101], v[188:191], v[236:239], v[98:101]
	v_mfma_f32_16x16x32_bf16 v[126:129], v[184:187], v[216:219], v[126:129]
	v_mfma_f32_16x16x32_bf16 v[122:125], v[192:195], v[216:219], v[122:125]
	v_mfma_f32_16x16x32_bf16 v[118:121], v[184:187], v[224:227], v[118:121]
	v_mfma_f32_16x16x32_bf16 v[114:117], v[192:195], v[224:227], v[114:117]
	v_mfma_f32_16x16x32_bf16 v[110:113], v[184:187], v[232:235], v[110:113]
	v_mfma_f32_16x16x32_bf16 v[106:109], v[192:195], v[232:235], v[106:109]
	v_mfma_f32_16x16x32_bf16 v[102:105], v[184:187], v[240:243], v[102:105]
	v_mfma_f32_16x16x32_bf16 v[98:101], v[192:195], v[240:243], v[98:101]
	v_mfma_f32_16x16x32_bf16 v[94:97], v[196:199], v[212:215], v[94:97]
	s_add_i32 s82, s71, s21
	v_mfma_f32_16x16x32_bf16 v[90:93], v[204:207], v[212:215], v[90:93]
	s_mov_b32 m0, s82
	v_mfma_f32_16x16x32_bf16 v[86:89], v[196:199], v[220:223], v[86:89]
	v_mfma_f32_16x16x32_bf16 v[82:85], v[204:207], v[220:223], v[82:85]
	v_mfma_f32_16x16x32_bf16 v[78:81], v[196:199], v[228:231], v[78:81]
	v_mfma_f32_16x16x32_bf16 v[74:77], v[204:207], v[228:231], v[74:77]
	v_mfma_f32_16x16x32_bf16 v[70:73], v[196:199], v[236:239], v[70:73]
	v_mfma_f32_16x16x32_bf16 v[66:69], v[204:207], v[236:239], v[66:69]
	v_mfma_f32_16x16x32_bf16 v[94:97], v[200:203], v[216:219], v[94:97]
	v_mfma_f32_16x16x32_bf16 v[90:93], v[208:211], v[216:219], v[90:93]
	v_mfma_f32_16x16x32_bf16 v[86:89], v[200:203], v[224:227], v[86:89]
	v_mfma_f32_16x16x32_bf16 v[82:85], v[208:211], v[224:227], v[82:85]
	v_mfma_f32_16x16x32_bf16 v[78:81], v[200:203], v[232:235], v[78:81]
	v_mfma_f32_16x16x32_bf16 v[74:77], v[208:211], v[232:235], v[74:77]
	v_mfma_f32_16x16x32_bf16 v[70:73], v[200:203], v[240:243], v[70:73]
	v_mfma_f32_16x16x32_bf16 v[66:69], v[208:211], v[240:243], v[66:69]
	s_barrier
	v_lshl_add_u64 v[136:137], s[62:63], 0, v[140:141]
	ds_read_b128 v[212:215], v182 offset:16384
	ds_read_b128 v[216:219], v182 offset:17408
	ds_read_b128 v[220:223], v182 offset:18432
	ds_read_b128 v[224:227], v182 offset:19456
	ds_read_b128 v[228:231], v182 offset:20480
	ds_read_b128 v[232:235], v182 offset:21504
	ds_read_b128 v[236:239], v182 offset:22528
	ds_read_b128 v[240:243], v182 offset:23552
	global_load_lds_dwordx4 v[136:137], off
	s_add_i32 m0, s82, 0x2000
	s_add_u32 s82, s62, 0x40000
	v_lshl_add_u64 v[244:245], s[62:63], 0, v[142:143]
	s_addc_u32 s83, s63, 0
	s_add_i32 s84, s72, s21
	global_load_lds_dwordx4 v[244:245], off
	v_lshl_add_u64 v[246:247], s[82:83], 0, v[140:141]
	s_mov_b32 m0, s84
	s_nop 0
	global_load_lds_dwordx4 v[246:247], off
	v_lshl_add_u64 v[246:247], s[82:83], 0, v[142:143]
	s_add_i32 m0, s84, 0x2000
	s_nop 0
	global_load_lds_dwordx4 v[246:247], off
	v_lshl_add_u64 v[246:247], s[80:81], 0, v[138:139]
	s_mov_b32 m0, s23
	v_lshl_add_u64 v[248:249], v[246:247], 0, s[44:45]
	global_load_lds_dwordx4 v[246:247], off
	s_mov_b32 m0, s33
	s_nop 0
	global_load_lds_dwordx4 v[248:249], off
	s_waitcnt vmcnt(8)
	s_waitcnt lgkmcnt(0)
	s_barrier
; #define PG8_STAGE(bufoff, gbase, voff) do { _Pragma("unroll") for (int _i = 0; _i < 2; ++_i) \
;         __builtin_amdgcn_global_load_lds((const unsigned*)((const char*)(gbase) + (voff)[_i]), (PG8_LAS unsigned*)(lds + (bufoff) + ldsw + _i * 8192), 16, 0, 0); } while (0)
; #define PG8_LDA(dst, b, h) do { _Pragma("unroll") for (int m = 0; m < 4; ++m) _Pragma("unroll") for (int k = 0; k < 2; ++k) dst[m][k] = *(const PG8_LAS bf16x8*)(lds + PG8_SA(b, h) + aoff + m * 2048 + k * 1024); } while (0)
; #define PG8_LDB(dst, b, h) do { _Pragma("unroll") for (int n = 0; n < 2; ++n) _Pragma("unroll") for (int k = 0; k < 2; ++k) dst[n][k] = *(const PG8_LAS bf16x8*)(lds + PG8_SB(b, h) + boff + n * 2048 + k * 1024); } while (0)
; #define PG8_MMA(ai, bj, At, Bt) do { __builtin_amdgcn_s_setprio(1); _Pragma("unroll") for (int m = 0; m < 4; ++m) _Pragma("unroll") for (int n = 0; n < 2; ++n) _Pragma("unroll") for (int k = 0; k < 2; ++k) \
;         acc[ai][bj][m][n] = __builtin_amdgcn_mfma_f32_16x16x32_bf16(Bt[n][k], At[m][k], acc[ai][bj][m][n], 0, 0, 0); __builtin_amdgcn_s_setprio(0); } while (0)
; #define PG8_WAIT_V(n) asm volatile("s_waitcnt vmcnt(" #n ")" ::: "memory")
; #define PG8_WAIT_L(n) asm volatile("s_waitcnt lgkmcnt(" #n ")" ::: "memory")
; #define PG8_BAR __builtin_amdgcn_s_barrier()
; #define PG8_SCHED __builtin_amdgcn_sched_barrier(0)
; template <class Epi, bool ALIGN_EPI, bool ABLK = false>
; __device__ __forceinline__ void gemm_phase(PG8_LAS unsigned char* lds, const Gemm g, const StaticOrder& S, const Epi& E) {
;     ...
;             PG8_WAIT_V(8); PG8_WAIT_L(0); PG8_BAR; PG8_MMA(1, 0, At, B0); PG8_MMA(1, 1, At, B1); PG8_BAR; PG8_SCHED;
;             PG8_LDB(B0, 1, 0); PG8_LDB(B1, 1, 1); PG8_SCHED; PG8_LDA(At, 1, 0); PG8_STAGE(PG8_SA(0, 1), a2 + hstepA, voffA);
;             PG8_WAIT_V(8); PG8_WAIT_L(0); PG8_BAR; PG8_MMA(0, 0, At, B0); PG8_MMA(0, 1, At, B1); PG8_BAR; PG8_SCHED;
	s_waitcnt lgkmcnt(0)
	v_mfma_f32_16x16x32_bf16 v[62:65], v[132:135], v[212:215], v[62:65]
	v_mfma_f32_16x16x32_bf16 v[58:61], v[188:191], v[212:215], v[58:61]
	v_mfma_f32_16x16x32_bf16 v[54:57], v[132:135], v[220:223], v[54:57]
	v_mfma_f32_16x16x32_bf16 v[50:53], v[188:191], v[220:223], v[50:53]
	v_mfma_f32_16x16x32_bf16 v[46:49], v[132:135], v[228:231], v[46:49]
	v_mfma_f32_16x16x32_bf16 v[42:45], v[188:191], v[228:231], v[42:45]
	v_mfma_f32_16x16x32_bf16 v[38:41], v[132:135], v[236:239], v[38:41]
	v_mfma_f32_16x16x32_bf16 v[34:37], v[188:191], v[236:239], v[34:37]
	v_mfma_f32_16x16x32_bf16 v[62:65], v[184:187], v[216:219], v[62:65]
	v_mfma_f32_16x16x32_bf16 v[58:61], v[192:195], v[216:219], v[58:61]
	v_mfma_f32_16x16x32_bf16 v[54:57], v[184:187], v[224:227], v[54:57]
	v_mfma_f32_16x16x32_bf16 v[50:53], v[192:195], v[224:227], v[50:53]
	v_mfma_f32_16x16x32_bf16 v[46:49], v[184:187], v[232:235], v[46:49]
	v_mfma_f32_16x16x32_bf16 v[42:45], v[192:195], v[232:235], v[42:45]
	v_mfma_f32_16x16x32_bf16 v[38:41], v[184:187], v[240:243], v[38:41]
	v_mfma_f32_16x16x32_bf16 v[34:37], v[192:195], v[240:243], v[34:37]
	v_mfma_f32_16x16x32_bf16 v[30:33], v[196:199], v[212:215], v[30:33]
	s_add_i32 s80, 0, 0x18000
	v_mfma_f32_16x16x32_bf16 v[26:29], v[204:207], v[212:215], v[26:29]
	s_add_i32 s81, 0, 0x1c000
	v_mfma_f32_16x16x32_bf16 v[22:25], v[196:199], v[220:223], v[22:25]
	v_mfma_f32_16x16x32_bf16 v[18:21], v[204:207], v[220:223], v[18:21]
	v_mfma_f32_16x16x32_bf16 v[14:17], v[196:199], v[228:231], v[14:17]
	v_mfma_f32_16x16x32_bf16 v[10:13], v[204:207], v[228:231], v[10:13]
	v_mfma_f32_16x16x32_bf16 v[6:9], v[196:199], v[236:239], v[6:9]
	v_mfma_f32_16x16x32_bf16 v[2:5], v[204:207], v[236:239], v[2:5]
	v_mfma_f32_16x16x32_bf16 v[30:33], v[200:203], v[216:219], v[30:33]
	v_mfma_f32_16x16x32_bf16 v[26:29], v[208:211], v[216:219], v[26:29]
	v_mfma_f32_16x16x32_bf16 v[22:25], v[200:203], v[224:227], v[22:25]
	v_mfma_f32_16x16x32_bf16 v[18:21], v[208:211], v[224:227], v[18:21]
	v_mfma_f32_16x16x32_bf16 v[14:17], v[200:203], v[232:235], v[14:17]
	v_mfma_f32_16x16x32_bf16 v[10:13], v[208:211], v[232:235], v[10:13]
	v_mfma_f32_16x16x32_bf16 v[6:9], v[200:203], v[240:243], v[6:9]
	v_mfma_f32_16x16x32_bf16 v[2:5], v[208:211], v[240:243], v[2:5]
	s_barrier
	v_add_u32_e32 v192, s80, v179
	v_add_u32_e32 v208, s81, v179
	ds_read_b128 v[132:135], v192
	ds_read_b128 v[184:187], v192 offset:1024
	ds_read_b128 v[188:191], v192 offset:2048
	ds_read_b128 v[192:195], v192 offset:3072
	ds_read_b128 v[196:199], v208
	ds_read_b128 v[200:203], v208 offset:1024
	ds_read_b128 v[204:207], v208 offset:2048
	ds_read_b128 v[208:211], v208 offset:3072
	s_mov_b32 m0, s67
	v_lshl_add_u64 v[248:249], v[246:247], 0, s[46:47]
	ds_read_b128 v[212:215], v182 offset:32768
	ds_read_b128 v[216:219], v182 offset:33792
	ds_read_b128 v[220:223], v182 offset:34816
	ds_read_b128 v[224:227], v182 offset:35840
	ds_read_b128 v[228:231], v182 offset:36864
	ds_read_b128 v[232:235], v182 offset:37888
	ds_read_b128 v[236:239], v182 offset:38912
	ds_read_b128 v[240:243], v182 offset:39936
	global_load_lds_dwordx4 v[248:249], off
	v_lshl_add_u64 v[248:249], v[246:247], 0, s[48:49]
	s_mov_b32 m0, s68
	s_nop 0
	global_load_lds_dwordx4 v[248:249], off
	s_waitcnt vmcnt(8)
	s_waitcnt lgkmcnt(0)
	s_barrier
	s_waitcnt lgkmcnt(0)
	v_mfma_f32_16x16x32_bf16 v[126:129], v[132:135], v[212:215], v[126:129]
	v_mfma_f32_16x16x32_bf16 v[122:125], v[188:191], v[212:215], v[122:125]
	v_mfma_f32_16x16x32_bf16 v[118:121], v[132:135], v[220:223], v[118:121]
	v_mfma_f32_16x16x32_bf16 v[114:117], v[188:191], v[220:223], v[114:117]
	v_mfma_f32_16x16x32_bf16 v[110:113], v[132:135], v[228:231], v[110:113]
	v_mfma_f32_16x16x32_bf16 v[106:109], v[188:191], v[228:231], v[106:109]
	v_mfma_f32_16x16x32_bf16 v[102:105], v[132:135], v[236:239], v[102:105]
	v_mfma_f32_16x16x32_bf16 v[98:101], v[188:191], v[236:239], v[98:101]
	v_mfma_f32_16x16x32_bf16 v[126:129], v[184:187], v[216:219], v[126:129]
	v_mfma_f32_16x16x32_bf16 v[122:125], v[192:195], v[216:219], v[122:125]
	v_mfma_f32_16x16x32_bf16 v[118:121], v[184:187], v[224:227], v[118:121]
	v_mfma_f32_16x16x32_bf16 v[114:117], v[192:195], v[224:227], v[114:117]
	v_mfma_f32_16x16x32_bf16 v[110:113], v[184:187], v[232:235], v[110:113]
	v_mfma_f32_16x16x32_bf16 v[106:109], v[192:195], v[232:235], v[106:109]
	v_mfma_f32_16x16x32_bf16 v[102:105], v[184:187], v[240:243], v[102:105]
	v_mfma_f32_16x16x32_bf16 v[98:101], v[192:195], v[240:243], v[98:101]
	v_mfma_f32_16x16x32_bf16 v[94:97], v[196:199], v[212:215], v[94:97]
	s_add_i32 s80, s80, s21
	v_mfma_f32_16x16x32_bf16 v[90:93], v[204:207], v[212:215], v[90:93]
	s_mov_b32 m0, s80
	v_mfma_f32_16x16x32_bf16 v[86:89], v[196:199], v[220:223], v[86:89]
	v_mfma_f32_16x16x32_bf16 v[82:85], v[204:207], v[220:223], v[82:85]
	v_mfma_f32_16x16x32_bf16 v[78:81], v[196:199], v[228:231], v[78:81]
	v_mfma_f32_16x16x32_bf16 v[74:77], v[204:207], v[228:231], v[74:77]
	v_mfma_f32_16x16x32_bf16 v[70:73], v[196:199], v[236:239], v[70:73]
	v_mfma_f32_16x16x32_bf16 v[66:69], v[204:207], v[236:239], v[66:69]
	v_mfma_f32_16x16x32_bf16 v[94:97], v[200:203], v[216:219], v[94:97]
	v_mfma_f32_16x16x32_bf16 v[90:93], v[208:211], v[216:219], v[90:93]
	v_mfma_f32_16x16x32_bf16 v[86:89], v[200:203], v[224:227], v[86:89]
	v_mfma_f32_16x16x32_bf16 v[82:85], v[208:211], v[224:227], v[82:85]
	v_mfma_f32_16x16x32_bf16 v[78:81], v[200:203], v[232:235], v[78:81]
	v_mfma_f32_16x16x32_bf16 v[74:77], v[208:211], v[232:235], v[74:77]
	v_mfma_f32_16x16x32_bf16 v[70:73], v[200:203], v[240:243], v[70:73]
	v_mfma_f32_16x16x32_bf16 v[66:69], v[208:211], v[240:243], v[66:69]
	s_barrier
; #define PG8_STAGE(bufoff, gbase, voff) do { _Pragma("unroll") for (int _i = 0; _i < 2; ++_i) \
;         __builtin_amdgcn_global_load_lds((const unsigned*)((const char*)(gbase) + (voff)[_i]), (PG8_LAS unsigned*)(lds + (bufoff) + ldsw + _i * 8192), 16, 0, 0); } while (0)
; #define PG8_LDA(dst, b, h) do { _Pragma("unroll") for (int m = 0; m < 4; ++m) _Pragma("unroll") for (int k = 0; k < 2; ++k) dst[m][k] = *(const PG8_LAS bf16x8*)(lds + PG8_SA(b, h) + aoff + m * 2048 + k * 1024); } while (0)
; #define PG8_MMA(ai, bj, At, Bt) do { __builtin_amdgcn_s_setprio(1); _Pragma("unroll") for (int m = 0; m < 4; ++m) _Pragma("unroll") for (int n = 0; n < 2; ++n) _Pragma("unroll") for (int k = 0; k < 2; ++k) \
;         acc[ai][bj][m][n] = __builtin_amdgcn_mfma_f32_16x16x32_bf16(Bt[n][k], At[m][k], acc[ai][bj][m][n], 0, 0, 0); __builtin_amdgcn_s_setprio(0); } while (0)
; #define PG8_WAIT_V(n) asm volatile("s_waitcnt vmcnt(" #n ")" ::: "memory")
; #define PG8_WAIT_L(n) asm volatile("s_waitcnt lgkmcnt(" #n ")" ::: "memory")
; #define PG8_BAR __builtin_amdgcn_s_barrier()
; #define PG8_SCHED __builtin_amdgcn_sched_barrier(0)
; template <class Epi, bool ALIGN_EPI, bool ABLK = false>
; __device__ __forceinline__ void gemm_phase(PG8_LAS unsigned char* lds, const Gemm g, const StaticOrder& S, const Epi& E) {
;     ...
;             PG8_LDA(At, 1, 1); PG8_STAGE(PG8_SB(1, 0), b3, voffB); PG8_STAGE(PG8_SB(1, 1), b3 + hstepB, voffB); PG8_STAGE(PG8_SA(1, 0), a3, voffA);
;             PG8_WAIT_V(8); PG8_WAIT_L(0); PG8_BAR; PG8_MMA(1, 0, At, B0); PG8_MMA(1, 1, At, B1); PG8_BAR; PG8_SCHED;
;         }
;         if constexpr (ALIGN_EPI) { if (wr == 0) PG8_BAR; }
	v_lshl_add_u64 v[136:137], v[136:137], 0, s[30:31]
	ds_read_b128 v[212:215], v182 offset:49152
	ds_read_b128 v[216:219], v182 offset:50176
	ds_read_b128 v[220:223], v182 offset:51200
	ds_read_b128 v[224:227], v182 offset:52224
	ds_read_b128 v[228:231], v182 offset:53248
	ds_read_b128 v[232:235], v182 offset:54272
	ds_read_b128 v[236:239], v182 offset:55296
	ds_read_b128 v[240:243], v182 offset:56320
	global_load_lds_dwordx4 v[136:137], off
	s_add_i32 m0, s80, 0x2000
	s_add_u32 s62, s62, 0x40080
	v_lshl_add_u64 v[136:137], v[244:245], 0, s[30:31]
	s_addc_u32 s63, s63, 0
	s_add_i32 s80, s81, s21
	global_load_lds_dwordx4 v[136:137], off
	v_lshl_add_u64 v[136:137], s[62:63], 0, v[140:141]
	s_mov_b32 m0, s80
	s_nop 0
	global_load_lds_dwordx4 v[136:137], off
	v_lshl_add_u64 v[136:137], s[62:63], 0, v[142:143]
	s_add_i32 m0, s80, 0x2000
	s_nop 0
	global_load_lds_dwordx4 v[136:137], off
	v_lshl_add_u64 v[136:137], v[246:247], 0, s[34:35]
	s_mov_b32 m0, s9
	s_nop 0
	global_load_lds_dwordx4 v[136:137], off
	v_lshl_add_u64 v[136:137], v[246:247], 0, s[36:37]
	s_mov_b32 m0, s70
	s_nop 0
	global_load_lds_dwordx4 v[136:137], off
	s_waitcnt vmcnt(8)
	s_waitcnt lgkmcnt(0)
	s_barrier
	s_waitcnt lgkmcnt(0)
	v_mfma_f32_16x16x32_bf16 v[62:65], v[132:135], v[212:215], v[62:65]
	v_mfma_f32_16x16x32_bf16 v[58:61], v[188:191], v[212:215], v[58:61]
	v_mfma_f32_16x16x32_bf16 v[54:57], v[132:135], v[220:223], v[54:57]
	v_mfma_f32_16x16x32_bf16 v[50:53], v[188:191], v[220:223], v[50:53]
	v_mfma_f32_16x16x32_bf16 v[46:49], v[132:135], v[228:231], v[46:49]
	v_mfma_f32_16x16x32_bf16 v[42:45], v[188:191], v[228:231], v[42:45]
	v_mfma_f32_16x16x32_bf16 v[38:41], v[132:135], v[236:239], v[38:41]
	v_mfma_f32_16x16x32_bf16 v[34:37], v[188:191], v[236:239], v[34:37]
	v_mfma_f32_16x16x32_bf16 v[62:65], v[184:187], v[216:219], v[62:65]
	v_mfma_f32_16x16x32_bf16 v[58:61], v[192:195], v[216:219], v[58:61]
	v_mfma_f32_16x16x32_bf16 v[54:57], v[184:187], v[224:227], v[54:57]
	v_mfma_f32_16x16x32_bf16 v[50:53], v[192:195], v[224:227], v[50:53]
	v_mfma_f32_16x16x32_bf16 v[46:49], v[184:187], v[232:235], v[46:49]
	v_mfma_f32_16x16x32_bf16 v[42:45], v[192:195], v[232:235], v[42:45]
	v_mfma_f32_16x16x32_bf16 v[38:41], v[184:187], v[240:243], v[38:41]
	v_mfma_f32_16x16x32_bf16 v[34:37], v[192:195], v[240:243], v[34:37]
	v_mfma_f32_16x16x32_bf16 v[30:33], v[196:199], v[212:215], v[30:33]
	s_add_i32 s79, s79, 2
	v_mfma_f32_16x16x32_bf16 v[26:29], v[204:207], v[212:215], v[26:29]
	s_add_u32 s77, s77, 0x100
	v_mfma_f32_16x16x32_bf16 v[22:25], v[196:199], v[220:223], v[22:25]
	s_addc_u32 s78, s78, 0
	v_mfma_f32_16x16x32_bf16 v[18:21], v[204:207], v[220:223], v[18:21]
	s_add_u32 s60, s60, 0x10000
	v_mfma_f32_16x16x32_bf16 v[14:17], v[196:199], v[228:231], v[14:17]
	s_addc_u32 s61, s61, 0
	v_mfma_f32_16x16x32_bf16 v[10:13], v[204:207], v[228:231], v[10:13]
	s_cmp_gt_u32 s79, 13
	v_mfma_f32_16x16x32_bf16 v[6:9], v[196:199], v[236:239], v[6:9]
	v_mfma_f32_16x16x32_bf16 v[2:5], v[204:207], v[236:239], v[2:5]
	v_mfma_f32_16x16x32_bf16 v[30:33], v[200:203], v[216:219], v[30:33]
	v_mfma_f32_16x16x32_bf16 v[26:29], v[208:211], v[216:219], v[26:29]
	v_mfma_f32_16x16x32_bf16 v[22:25], v[200:203], v[224:227], v[22:25]
	v_mfma_f32_16x16x32_bf16 v[18:21], v[208:211], v[224:227], v[18:21]
	v_mfma_f32_16x16x32_bf16 v[14:17], v[200:203], v[232:235], v[14:17]
	v_mfma_f32_16x16x32_bf16 v[10:13], v[208:211], v[232:235], v[10:13]
	v_mfma_f32_16x16x32_bf16 v[6:9], v[200:203], v[240:243], v[6:9]
	v_mfma_f32_16x16x32_bf16 v[2:5], v[208:211], v[240:243], v[2:5]
	s_barrier
	v_lshl_add_u64 v[130:131], v[130:131], 0, s[50:51]
	s_cbranch_scc0 .LBB0_1983
	s_setprio 0
	s_and_b64 vcc, exec, s[38:39]
	s_cbranch_vccz .LBB0_1986
	s_barrier

; #define PG8_STAGE(bufoff, gbase, voff) do { _Pragma("unroll") for (int _i = 0; _i < 2; ++_i) \
;         __builtin_amdgcn_global_load_lds((const unsigned*)((const char*)(gbase) + (voff)[_i]), (PG8_LAS unsigned*)(lds + (bufoff) + ldsw + _i * 8192), 16, 0, 0); } while (0)
; #define PG8_LDA(dst, b, h) do { _Pragma("unroll") for (int m = 0; m < 4; ++m) _Pragma("unroll") for (int k = 0; k < 2; ++k) dst[m][k] = *(const PG8_LAS bf16x8*)(lds + PG8_SA(b, h) + aoff + m * 2048 + k * 1024); } while (0)
; #define PG8_LDB(dst, b, h) do { _Pragma("unroll") for (int n = 0; n < 2; ++n) _Pragma("unroll") for (int k = 0; k < 2; ++k) dst[n][k] = *(const PG8_LAS bf16x8*)(lds + PG8_SB(b, h) + boff + n * 2048 + k * 1024); } while (0)
; #define PG8_MMA(ai, bj, At, Bt) do { __builtin_amdgcn_s_setprio(1); _Pragma("unroll") for (int m = 0; m < 4; ++m) _Pragma("unroll") for (int n = 0; n < 2; ++n) _Pragma("unroll") for (int k = 0; k < 2; ++k) \
;         acc[ai][bj][m][n] = __builtin_amdgcn_mfma_f32_16x16x32_bf16(Bt[n][k], At[m][k], acc[ai][bj][m][n], 0, 0, 0); __builtin_amdgcn_s_setprio(0); } while (0)
; #define PG8_WAIT_V(n) asm volatile("s_waitcnt vmcnt(" #n ")" ::: "memory")
; #define PG8_WAIT_L(n) asm volatile("s_waitcnt lgkmcnt(" #n ")" ::: "memory")
; #define PG8_BAR __builtin_amdgcn_s_barrier()
; #define PG8_SCHED __builtin_amdgcn_sched_barrier(0)
; #define S xcd_barrier(bar);
; template <class Epi, bool ALIGN_EPI, bool ABLK = false>
; __device__ __forceinline__ void gemm_phase(PG8_LAS unsigned char* lds, const Gemm g, const StaticOrder& S, const Epi& E) {
;     ...
;         const bool has_next = S.next(ui + 1, nxt);
;         const char* nA = has_next ? PG8_ABASE(nxt) : cA; const char* nB = has_next ? PG8_BBASE(nxt) : cB;
;         for (int t = 0; t < nt; t += 2) {
;             const bool last = (t == nt - 2);
;             const char* a1 = cA + (size_t)(t + 1) * kstepA;
;             const char* a2 = last ? nA : cA + (size_t)(t + 2) * kstepA; const char* b2 = last ? nB : cB + (size_t)(t + 2) * kstepB;
;             const char* a3 = a2 + kstepA; const char* b3 = b2 + kstepB;
;             PG8_LDB(B0, 0, 0); PG8_LDB(B1, 0, 1); PG8_SCHED; PG8_LDA(At, 0, 0); PG8_STAGE(PG8_SA(1, 1), a1 + hstepA, voffA);
;             PG8_WAIT_V(8); PG8_WAIT_L(0); PG8_BAR; PG8_MMA(0, 0, At, B0); PG8_MMA(0, 1, At, B1); PG8_BAR; PG8_SCHED;
.LBB0_2104:
	s_and_b32 s67, s66, 1
	s_cmp_eq_u32 s67, 0
	s_cselect_b32 s41, s19, s58
	s_cselect_b32 s46, s18, s57
	s_ashr_i32 s43, s42, 31
	s_lshl_b64 s[44:45], s[42:43], 19
	s_add_u32 s44, s46, s44
	s_addc_u32 s45, s41, s45
	s_and_b64 s[46:47], s[4:5], exec
	s_cselect_b32 s43, s45, s7
	s_cselect_b32 s69, s44, s6
	s_ashr_i32 s41, s40, 31
	s_lshl_b64 s[46:47], s[40:41], 20
	s_add_u32 s41, s14, s46
	s_addc_u32 s47, s15, s47
	s_lshl_b32 s46, s67, 11
	s_add_u32 s46, s41, s46
	s_addc_u32 s47, s47, 0
	s_and_b64 s[50:51], s[4:5], exec
	s_cselect_b32 s41, s47, s49
	s_cselect_b32 s70, s46, s48
	s_add_u32 s6, s6, 0x40080
	s_addc_u32 s7, s7, 0
	s_add_u32 s71, s48, 0x100
	s_addc_u32 s72, s49, 0
	s_mov_b32 s73, -2
	s_setprio 0
	v_readfirstlane_b32 s101, v0
	s_nop 3
	s_bfe_u32 s101, s101, 0x40006
	s_cmp_ge_u32 s101, 4
	s_cbranch_scc0 .Lprio_2105
	s_setprio 1
.Lprio_2105:
.LBB0_2105:
	v_add_u32_e32 v3, s64, v239
	ds_read_b128 v[134:137], v3
	ds_read_b128 v[138:141], v3 offset:1024
	ds_read_b128 v[142:145], v3 offset:2048
	ds_read_b128 v[146:149], v3 offset:3072
	v_add_u32_e32 v3, s65, v239
	ds_read_b128 v[150:153], v3
	ds_read_b128 v[154:157], v3 offset:1024
	ds_read_b128 v[158:161], v3 offset:2048
	ds_read_b128 v[162:165], v3 offset:3072
	s_add_u32 s48, s6, 0xfffc0080
	s_addc_u32 s49, s7, -1
	s_cmp_eq_u32 s73, 12
	s_cselect_b32 s51, s43, s49
	s_cselect_b32 s50, s69, s48
	s_cselect_b32 s49, s41, s72
	s_cselect_b32 s48, s70, s71
	v_lshl_add_u64 v[4:5], s[6:7], 0, v[218:219]
	s_add_i32 m0, s37, 0xc000
	ds_read_b128 v[166:169], v240
	ds_read_b128 v[170:173], v240 offset:1024
	ds_read_b128 v[174:177], v240 offset:2048
	ds_read_b128 v[178:181], v240 offset:3072
	ds_read_b128 v[182:185], v240 offset:4096
	ds_read_b128 v[186:189], v240 offset:5120
	ds_read_b128 v[190:193], v240 offset:6144
	ds_read_b128 v[226:229], v240 offset:7168
	global_load_lds_dwordx4 v[4:5], off
	v_lshl_add_u64 v[4:5], s[6:7], 0, v[220:221]
	s_add_i32 m0, s37, 0xe000
	s_nop 0
	global_load_lds_dwordx4 v[4:5], off
	s_waitcnt vmcnt(8)
	s_waitcnt lgkmcnt(0)
	s_barrier
	s_waitcnt lgkmcnt(0)
	v_mfma_f32_16x16x32_bf16 v[130:133], v[134:137], v[166:169], v[130:133]
	v_mfma_f32_16x16x32_bf16 v[126:129], v[142:145], v[166:169], v[126:129]
	v_mfma_f32_16x16x32_bf16 v[122:125], v[134:137], v[174:177], v[122:125]
	v_mfma_f32_16x16x32_bf16 v[118:121], v[142:145], v[174:177], v[118:121]
	v_mfma_f32_16x16x32_bf16 v[114:117], v[134:137], v[182:185], v[114:117]
	v_mfma_f32_16x16x32_bf16 v[110:113], v[142:145], v[182:185], v[110:113]
	v_mfma_f32_16x16x32_bf16 v[106:109], v[134:137], v[190:193], v[106:109]
	v_mfma_f32_16x16x32_bf16 v[102:105], v[142:145], v[190:193], v[102:105]
	v_mfma_f32_16x16x32_bf16 v[130:133], v[138:141], v[170:173], v[130:133]
	v_mfma_f32_16x16x32_bf16 v[126:129], v[146:149], v[170:173], v[126:129]
	v_mfma_f32_16x16x32_bf16 v[122:125], v[138:141], v[178:181], v[122:125]
	v_mfma_f32_16x16x32_bf16 v[118:121], v[146:149], v[178:181], v[118:121]
	v_mfma_f32_16x16x32_bf16 v[114:117], v[138:141], v[186:189], v[114:117]
	v_mfma_f32_16x16x32_bf16 v[110:113], v[146:149], v[186:189], v[110:113]
	v_mfma_f32_16x16x32_bf16 v[106:109], v[138:141], v[226:229], v[106:109]
	v_mfma_f32_16x16x32_bf16 v[102:105], v[146:149], v[226:229], v[102:105]
	v_mfma_f32_16x16x32_bf16 v[98:101], v[150:153], v[166:169], v[98:101]
	s_add_i32 s74, s64, s54
	v_mfma_f32_16x16x32_bf16 v[94:97], v[158:161], v[166:169], v[94:97]
	s_mov_b32 m0, s74
	v_mfma_f32_16x16x32_bf16 v[90:93], v[150:153], v[174:177], v[90:93]
	v_mfma_f32_16x16x32_bf16 v[86:89], v[158:161], v[174:177], v[86:89]
	v_mfma_f32_16x16x32_bf16 v[82:85], v[150:153], v[182:185], v[82:85]
	v_mfma_f32_16x16x32_bf16 v[78:81], v[158:161], v[182:185], v[78:81]
	v_mfma_f32_16x16x32_bf16 v[74:77], v[150:153], v[190:193], v[74:77]
	v_mfma_f32_16x16x32_bf16 v[70:73], v[158:161], v[190:193], v[70:73]
	v_mfma_f32_16x16x32_bf16 v[98:101], v[154:157], v[170:173], v[98:101]
	v_mfma_f32_16x16x32_bf16 v[94:97], v[162:165], v[170:173], v[94:97]
	v_mfma_f32_16x16x32_bf16 v[90:93], v[154:157], v[178:181], v[90:93]
	v_mfma_f32_16x16x32_bf16 v[86:89], v[162:165], v[178:181], v[86:89]
	v_mfma_f32_16x16x32_bf16 v[82:85], v[154:157], v[186:189], v[82:85]
	v_mfma_f32_16x16x32_bf16 v[78:81], v[162:165], v[186:189], v[78:81]
	v_mfma_f32_16x16x32_bf16 v[74:77], v[154:157], v[226:229], v[74:77]
	v_mfma_f32_16x16x32_bf16 v[70:73], v[162:165], v[226:229], v[70:73]
	s_barrier
	v_lshl_add_u64 v[230:231], s[48:49], 0, v[196:197]
	ds_read_b128 v[166:169], v240 offset:16384
	ds_read_b128 v[170:173], v240 offset:17408
	ds_read_b128 v[174:177], v240 offset:18432
	ds_read_b128 v[178:181], v240 offset:19456
	ds_read_b128 v[182:185], v240 offset:20480
	ds_read_b128 v[186:189], v240 offset:21504
	ds_read_b128 v[190:193], v240 offset:22528
	ds_read_b128 v[226:229], v240 offset:23552
	global_load_lds_dwordx4 v[230:231], off
	s_add_i32 m0, s74, 0x2000
	s_add_u32 s74, s48, 0x80000
	v_lshl_add_u64 v[242:243], s[48:49], 0, v[200:201]
	s_addc_u32 s75, s49, 0
	s_add_i32 s76, s65, s54
	global_load_lds_dwordx4 v[242:243], off
	v_lshl_add_u64 v[4:5], s[74:75], 0, v[196:197]
	s_mov_b32 m0, s76
	v_lshl_add_u64 v[244:245], s[50:51], 0, v[194:195]
	global_load_lds_dwordx4 v[4:5], off
	v_lshl_add_u64 v[4:5], s[74:75], 0, v[200:201]
	s_add_i32 m0, s76, 0x2000
	v_lshl_add_u64 v[246:247], s[50:51], 0, v[198:199]
	global_load_lds_dwordx4 v[4:5], off
	s_mov_b32 m0, s37
	s_nop 0
	global_load_lds_dwordx4 v[244:245], off
	s_mov_b32 m0, s39
	s_nop 0
	global_load_lds_dwordx4 v[246:247], off
	s_waitcnt vmcnt(8)
	s_waitcnt lgkmcnt(0)
	s_barrier
; #define PG8_STAGE(bufoff, gbase, voff) do { _Pragma("unroll") for (int _i = 0; _i < 2; ++_i) \
;         __builtin_amdgcn_global_load_lds((const unsigned*)((const char*)(gbase) + (voff)[_i]), (PG8_LAS unsigned*)(lds + (bufoff) + ldsw + _i * 8192), 16, 0, 0); } while (0)
; #define PG8_LDA(dst, b, h) do { _Pragma("unroll") for (int m = 0; m < 4; ++m) _Pragma("unroll") for (int k = 0; k < 2; ++k) dst[m][k] = *(const PG8_LAS bf16x8*)(lds + PG8_SA(b, h) + aoff + m * 2048 + k * 1024); } while (0)
; #define PG8_LDB(dst, b, h) do { _Pragma("unroll") for (int n = 0; n < 2; ++n) _Pragma("unroll") for (int k = 0; k < 2; ++k) dst[n][k] = *(const PG8_LAS bf16x8*)(lds + PG8_SB(b, h) + boff + n * 2048 + k * 1024); } while (0)
; #define PG8_MMA(ai, bj, At, Bt) do { __builtin_amdgcn_s_setprio(1); _Pragma("unroll") for (int m = 0; m < 4; ++m) _Pragma("unroll") for (int n = 0; n < 2; ++n) _Pragma("unroll") for (int k = 0; k < 2; ++k) \
;         acc[ai][bj][m][n] = __builtin_amdgcn_mfma_f32_16x16x32_bf16(Bt[n][k], At[m][k], acc[ai][bj][m][n], 0, 0, 0); __builtin_amdgcn_s_setprio(0); } while (0)
; #define PG8_WAIT_V(n) asm volatile("s_waitcnt vmcnt(" #n ")" ::: "memory")
; #define PG8_WAIT_L(n) asm volatile("s_waitcnt lgkmcnt(" #n ")" ::: "memory")
; #define PG8_BAR __builtin_amdgcn_s_barrier()
; #define PG8_SCHED __builtin_amdgcn_sched_barrier(0)
; template <class Epi, bool ALIGN_EPI, bool ABLK = false>
; __device__ __forceinline__ void gemm_phase(PG8_LAS unsigned char* lds, const Gemm g, const StaticOrder& S, const Epi& E) {
;     ...
;             PG8_WAIT_V(8); PG8_WAIT_L(0); PG8_BAR; PG8_MMA(1, 0, At, B0); PG8_MMA(1, 1, At, B1); PG8_BAR; PG8_SCHED;
;             PG8_LDB(B0, 1, 0); PG8_LDB(B1, 1, 1); PG8_SCHED; PG8_LDA(At, 1, 0); PG8_STAGE(PG8_SA(0, 1), a2 + hstepA, voffA);
;             PG8_WAIT_V(8); PG8_WAIT_L(0); PG8_BAR; PG8_MMA(0, 0, At, B0); PG8_MMA(0, 1, At, B1); PG8_BAR; PG8_SCHED;
	s_waitcnt lgkmcnt(0)
	v_mfma_f32_16x16x32_bf16 v[66:69], v[134:137], v[166:169], v[66:69]
	v_mfma_f32_16x16x32_bf16 v[62:65], v[142:145], v[166:169], v[62:65]
	v_mfma_f32_16x16x32_bf16 v[58:61], v[134:137], v[174:177], v[58:61]
	v_mfma_f32_16x16x32_bf16 v[54:57], v[142:145], v[174:177], v[54:57]
	v_mfma_f32_16x16x32_bf16 v[50:53], v[134:137], v[182:185], v[50:53]
	v_mfma_f32_16x16x32_bf16 v[46:49], v[142:145], v[182:185], v[46:49]
	v_mfma_f32_16x16x32_bf16 v[42:45], v[134:137], v[190:193], v[42:45]
	v_mfma_f32_16x16x32_bf16 v[38:41], v[142:145], v[190:193], v[38:41]
	v_mfma_f32_16x16x32_bf16 v[66:69], v[138:141], v[170:173], v[66:69]
	v_mfma_f32_16x16x32_bf16 v[62:65], v[146:149], v[170:173], v[62:65]
	v_mfma_f32_16x16x32_bf16 v[58:61], v[138:141], v[178:181], v[58:61]
	v_mfma_f32_16x16x32_bf16 v[54:57], v[146:149], v[178:181], v[54:57]
	v_mfma_f32_16x16x32_bf16 v[50:53], v[138:141], v[186:189], v[50:53]
	v_mfma_f32_16x16x32_bf16 v[46:49], v[146:149], v[186:189], v[46:49]
	v_mfma_f32_16x16x32_bf16 v[42:45], v[138:141], v[226:229], v[42:45]
	v_mfma_f32_16x16x32_bf16 v[38:41], v[146:149], v[226:229], v[38:41]
	v_mfma_f32_16x16x32_bf16 v[34:37], v[150:153], v[166:169], v[34:37]
	s_add_i32 s74, 0, 0x18000
	v_mfma_f32_16x16x32_bf16 v[30:33], v[158:161], v[166:169], v[30:33]
	s_add_i32 s75, 0, 0x1c000
	v_mfma_f32_16x16x32_bf16 v[26:29], v[150:153], v[174:177], v[26:29]
	v_mfma_f32_16x16x32_bf16 v[22:25], v[158:161], v[174:177], v[22:25]
	v_mfma_f32_16x16x32_bf16 v[18:21], v[150:153], v[182:185], v[18:21]
	v_mfma_f32_16x16x32_bf16 v[14:17], v[158:161], v[182:185], v[14:17]
	v_mfma_f32_16x16x32_bf16 v[10:13], v[150:153], v[190:193], v[10:13]
	v_mfma_f32_16x16x32_bf16 v[4:7], v[158:161], v[190:193], v[6:9]
	v_mfma_f32_16x16x32_bf16 v[34:37], v[154:157], v[170:173], v[34:37]
	v_mfma_f32_16x16x32_bf16 v[30:33], v[162:165], v[170:173], v[30:33]
	v_mfma_f32_16x16x32_bf16 v[26:29], v[154:157], v[178:181], v[26:29]
	v_mfma_f32_16x16x32_bf16 v[22:25], v[162:165], v[178:181], v[22:25]
	v_mfma_f32_16x16x32_bf16 v[18:21], v[154:157], v[186:189], v[18:21]
	v_mfma_f32_16x16x32_bf16 v[14:17], v[162:165], v[186:189], v[14:17]
	v_mfma_f32_16x16x32_bf16 v[10:13], v[154:157], v[226:229], v[10:13]
	v_mfma_f32_16x16x32_bf16 v[4:7], v[162:165], v[226:229], v[4:7]
	s_barrier
	v_add_u32_e32 v3, s74, v239
	ds_read_b128 v[134:137], v3
	ds_read_b128 v[138:141], v3 offset:1024
	ds_read_b128 v[142:145], v3 offset:2048
	ds_read_b128 v[146:149], v3 offset:3072
	v_add_u32_e32 v3, s75, v239
	ds_read_b128 v[150:153], v3
	ds_read_b128 v[154:157], v3 offset:1024
	ds_read_b128 v[158:161], v3 offset:2048
	ds_read_b128 v[162:165], v3 offset:3072
	s_add_u32 s50, s50, 0x40000
	s_addc_u32 s51, s51, 0
	s_mov_b32 m0, s55
	v_lshl_add_u64 v[8:9], s[50:51], 0, v[194:195]
	ds_read_b128 v[166:169], v240 offset:32768
	ds_read_b128 v[170:173], v240 offset:33792
	ds_read_b128 v[174:177], v240 offset:34816
	ds_read_b128 v[178:181], v240 offset:35840
	ds_read_b128 v[182:185], v240 offset:36864
	ds_read_b128 v[186:189], v240 offset:37888
	ds_read_b128 v[190:193], v240 offset:38912
	ds_read_b128 v[226:229], v240 offset:39936
	global_load_lds_dwordx4 v[8:9], off
	v_lshl_add_u64 v[8:9], s[50:51], 0, v[198:199]
	s_mov_b32 m0, s56
	s_nop 0
	global_load_lds_dwordx4 v[8:9], off
	s_waitcnt vmcnt(8)
	s_waitcnt lgkmcnt(0)
	s_barrier
	s_waitcnt lgkmcnt(0)
	v_mfma_f32_16x16x32_bf16 v[130:133], v[134:137], v[166:169], v[130:133]
	v_mfma_f32_16x16x32_bf16 v[126:129], v[142:145], v[166:169], v[126:129]
	v_mfma_f32_16x16x32_bf16 v[122:125], v[134:137], v[174:177], v[122:125]
	v_mfma_f32_16x16x32_bf16 v[118:121], v[142:145], v[174:177], v[118:121]
	v_mfma_f32_16x16x32_bf16 v[114:117], v[134:137], v[182:185], v[114:117]
	v_mfma_f32_16x16x32_bf16 v[110:113], v[142:145], v[182:185], v[110:113]
	v_mfma_f32_16x16x32_bf16 v[106:109], v[134:137], v[190:193], v[106:109]
	v_mfma_f32_16x16x32_bf16 v[102:105], v[142:145], v[190:193], v[102:105]
	v_mfma_f32_16x16x32_bf16 v[130:133], v[138:141], v[170:173], v[130:133]
	v_mfma_f32_16x16x32_bf16 v[126:129], v[146:149], v[170:173], v[126:129]
	v_mfma_f32_16x16x32_bf16 v[122:125], v[138:141], v[178:181], v[122:125]
	v_mfma_f32_16x16x32_bf16 v[118:121], v[146:149], v[178:181], v[118:121]
	v_mfma_f32_16x16x32_bf16 v[114:117], v[138:141], v[186:189], v[114:117]
	v_mfma_f32_16x16x32_bf16 v[110:113], v[146:149], v[186:189], v[110:113]
	v_mfma_f32_16x16x32_bf16 v[106:109], v[138:141], v[226:229], v[106:109]
	v_mfma_f32_16x16x32_bf16 v[102:105], v[146:149], v[226:229], v[102:105]
	v_mfma_f32_16x16x32_bf16 v[98:101], v[150:153], v[166:169], v[98:101]
	s_add_i32 s50, s74, s54
	v_mfma_f32_16x16x32_bf16 v[94:97], v[158:161], v[166:169], v[94:97]
	s_mov_b32 m0, s50
	v_mfma_f32_16x16x32_bf16 v[90:93], v[150:153], v[174:177], v[90:93]
	v_mfma_f32_16x16x32_bf16 v[86:89], v[158:161], v[174:177], v[86:89]
	v_mfma_f32_16x16x32_bf16 v[82:85], v[150:153], v[182:185], v[82:85]
	v_mfma_f32_16x16x32_bf16 v[78:81], v[158:161], v[182:185], v[78:81]
	v_mfma_f32_16x16x32_bf16 v[74:77], v[150:153], v[190:193], v[74:77]
	v_mfma_f32_16x16x32_bf16 v[70:73], v[158:161], v[190:193], v[70:73]
	v_mfma_f32_16x16x32_bf16 v[98:101], v[154:157], v[170:173], v[98:101]
	v_mfma_f32_16x16x32_bf16 v[94:97], v[162:165], v[170:173], v[94:97]
	v_mfma_f32_16x16x32_bf16 v[90:93], v[154:157], v[178:181], v[90:93]
	v_mfma_f32_16x16x32_bf16 v[86:89], v[162:165], v[178:181], v[86:89]
	v_mfma_f32_16x16x32_bf16 v[82:85], v[154:157], v[186:189], v[82:85]
	v_mfma_f32_16x16x32_bf16 v[78:81], v[162:165], v[186:189], v[78:81]
	v_mfma_f32_16x16x32_bf16 v[74:77], v[154:157], v[226:229], v[74:77]
	v_mfma_f32_16x16x32_bf16 v[70:73], v[162:165], v[226:229], v[70:73]
	s_barrier
; #define PG8_STAGE(bufoff, gbase, voff) do { _Pragma("unroll") for (int _i = 0; _i < 2; ++_i) \
;         __builtin_amdgcn_global_load_lds((const unsigned*)((const char*)(gbase) + (voff)[_i]), (PG8_LAS unsigned*)(lds + (bufoff) + ldsw + _i * 8192), 16, 0, 0); } while (0)
; #define PG8_LDA(dst, b, h) do { _Pragma("unroll") for (int m = 0; m < 4; ++m) _Pragma("unroll") for (int k = 0; k < 2; ++k) dst[m][k] = *(const PG8_LAS bf16x8*)(lds + PG8_SA(b, h) + aoff + m * 2048 + k * 1024); } while (0)
; #define PG8_MMA(ai, bj, At, Bt) do { __builtin_amdgcn_s_setprio(1); _Pragma("unroll") for (int m = 0; m < 4; ++m) _Pragma("unroll") for (int n = 0; n < 2; ++n) _Pragma("unroll") for (int k = 0; k < 2; ++k) \
;         acc[ai][bj][m][n] = __builtin_amdgcn_mfma_f32_16x16x32_bf16(Bt[n][k], At[m][k], acc[ai][bj][m][n], 0, 0, 0); __builtin_amdgcn_s_setprio(0); } while (0)
; #define PG8_WAIT_V(n) asm volatile("s_waitcnt vmcnt(" #n ")" ::: "memory")
; #define PG8_WAIT_L(n) asm volatile("s_waitcnt lgkmcnt(" #n ")" ::: "memory")
; #define PG8_BAR __builtin_amdgcn_s_barrier()
; #define PG8_SCHED __builtin_amdgcn_sched_barrier(0)
; template <class Epi, bool ALIGN_EPI, bool ABLK = false>
; __device__ __forceinline__ void gemm_phase(PG8_LAS unsigned char* lds, const Gemm g, const StaticOrder& S, const Epi& E) {
;     ...
;             PG8_LDA(At, 1, 1); PG8_STAGE(PG8_SB(1, 0), b3, voffB); PG8_STAGE(PG8_SB(1, 1), b3 + hstepB, voffB); PG8_STAGE(PG8_SA(1, 0), a3, voffA);
;             PG8_WAIT_V(8); PG8_WAIT_L(0); PG8_BAR; PG8_MMA(1, 0, At, B0); PG8_MMA(1, 1, At, B1); PG8_BAR; PG8_SCHED;
;         }
;         if constexpr (ALIGN_EPI) { if (wr == 0) PG8_BAR; }
	v_lshl_add_u64 v[8:9], v[230:231], 0, s[22:23]
	ds_read_b128 v[166:169], v240 offset:49152
	ds_read_b128 v[170:173], v240 offset:50176
	ds_read_b128 v[174:177], v240 offset:51200
	ds_read_b128 v[178:181], v240 offset:52224
	ds_read_b128 v[182:185], v240 offset:53248
	ds_read_b128 v[186:189], v240 offset:54272
	ds_read_b128 v[190:193], v240 offset:55296
	ds_read_b128 v[226:229], v240 offset:56320
	global_load_lds_dwordx4 v[8:9], off
	s_add_i32 m0, s50, 0x2000
	s_add_u32 s48, s48, 0x80080
	v_lshl_add_u64 v[8:9], v[242:243], 0, s[22:23]
	s_addc_u32 s49, s49, 0
	s_add_i32 s50, s75, s54
	global_load_lds_dwordx4 v[8:9], off
	v_lshl_add_u64 v[8:9], s[48:49], 0, v[196:197]
	s_mov_b32 m0, s50
	s_nop 0
	global_load_lds_dwordx4 v[8:9], off
	v_lshl_add_u64 v[8:9], s[48:49], 0, v[200:201]
	s_add_i32 m0, s50, 0x2000
	s_nop 0
	global_load_lds_dwordx4 v[8:9], off
	v_lshl_add_u64 v[8:9], v[244:245], 0, s[22:23]
	s_mov_b32 m0, s59
	s_nop 0
	global_load_lds_dwordx4 v[8:9], off
	v_lshl_add_u64 v[8:9], v[246:247], 0, s[22:23]
	s_mov_b32 m0, s60
	s_nop 0
	global_load_lds_dwordx4 v[8:9], off
	s_waitcnt vmcnt(8)
	s_waitcnt lgkmcnt(0)
	s_barrier
	s_waitcnt lgkmcnt(0)
	v_mfma_f32_16x16x32_bf16 v[66:69], v[134:137], v[166:169], v[66:69]
	v_mfma_f32_16x16x32_bf16 v[62:65], v[142:145], v[166:169], v[62:65]
	v_mfma_f32_16x16x32_bf16 v[58:61], v[134:137], v[174:177], v[58:61]
	v_mfma_f32_16x16x32_bf16 v[54:57], v[142:145], v[174:177], v[54:57]
	v_mfma_f32_16x16x32_bf16 v[50:53], v[134:137], v[182:185], v[50:53]
	v_mfma_f32_16x16x32_bf16 v[46:49], v[142:145], v[182:185], v[46:49]
	v_mfma_f32_16x16x32_bf16 v[42:45], v[134:137], v[190:193], v[42:45]
	v_mfma_f32_16x16x32_bf16 v[38:41], v[142:145], v[190:193], v[38:41]
	v_mfma_f32_16x16x32_bf16 v[66:69], v[138:141], v[170:173], v[66:69]
	v_mfma_f32_16x16x32_bf16 v[62:65], v[146:149], v[170:173], v[62:65]
	v_mfma_f32_16x16x32_bf16 v[58:61], v[138:141], v[178:181], v[58:61]
	v_mfma_f32_16x16x32_bf16 v[54:57], v[146:149], v[178:181], v[54:57]
	v_mfma_f32_16x16x32_bf16 v[50:53], v[138:141], v[186:189], v[50:53]
	v_mfma_f32_16x16x32_bf16 v[46:49], v[146:149], v[186:189], v[46:49]
	v_mfma_f32_16x16x32_bf16 v[42:45], v[138:141], v[226:229], v[42:45]
	v_mfma_f32_16x16x32_bf16 v[38:41], v[146:149], v[226:229], v[38:41]
	v_mfma_f32_16x16x32_bf16 v[34:37], v[150:153], v[166:169], v[34:37]
	s_add_i32 s73, s73, 2
	v_mfma_f32_16x16x32_bf16 v[30:33], v[158:161], v[166:169], v[30:33]
	s_add_u32 s6, s6, 0x100
	v_mfma_f32_16x16x32_bf16 v[26:29], v[150:153], v[174:177], v[26:29]
	s_addc_u32 s7, s7, 0
	v_mfma_f32_16x16x32_bf16 v[22:25], v[158:161], v[174:177], v[22:25]
	s_add_u32 s71, s71, 0x100
	v_mfma_f32_16x16x32_bf16 v[18:21], v[150:153], v[182:185], v[18:21]
	s_addc_u32 s72, s72, 0
	v_mfma_f32_16x16x32_bf16 v[14:17], v[158:161], v[182:185], v[14:17]
	s_cmp_gt_u32 s73, 13
	v_mfma_f32_16x16x32_bf16 v[8:11], v[150:153], v[190:193], v[10:13]
	v_mfma_f32_16x16x32_bf16 v[4:7], v[158:161], v[190:193], v[4:7]
	v_mfma_f32_16x16x32_bf16 v[34:37], v[154:157], v[170:173], v[34:37]
	v_mfma_f32_16x16x32_bf16 v[30:33], v[162:165], v[170:173], v[30:33]
	v_mfma_f32_16x16x32_bf16 v[26:29], v[154:157], v[178:181], v[26:29]
	v_mfma_f32_16x16x32_bf16 v[22:25], v[162:165], v[178:181], v[22:25]
	v_mfma_f32_16x16x32_bf16 v[18:21], v[154:157], v[186:189], v[18:21]
	v_mfma_f32_16x16x32_bf16 v[14:17], v[162:165], v[186:189], v[14:17]
	v_mfma_f32_16x16x32_bf16 v[10:13], v[154:157], v[226:229], v[8:11]
	v_mfma_f32_16x16x32_bf16 v[6:9], v[162:165], v[226:229], v[4:7]
	s_barrier
	s_cbranch_scc0 .LBB0_2105
	s_setprio 0
	s_and_b64 vcc, exec, s[24:25]
	s_cbranch_vccz .LBB0_2108
	s_barrier

; #define PG8_STAGE(bufoff, gbase, voff) do { _Pragma("unroll") for (int _i = 0; _i < 2; ++_i) \
;         __builtin_amdgcn_global_load_lds((const unsigned*)((const char*)(gbase) + (voff)[_i]), (PG8_LAS unsigned*)(lds + (bufoff) + ldsw + _i * 8192), 16, 0, 0); } while (0)
; #define PG8_LDA(dst, b, h) do { _Pragma("unroll") for (int m = 0; m < 4; ++m) _Pragma("unroll") for (int k = 0; k < 2; ++k) dst[m][k] = *(const PG8_LAS bf16x8*)(lds + PG8_SA(b, h) + aoff + m * 2048 + k * 1024); } while (0)
; #define PG8_LDB(dst, b, h) do { _Pragma("unroll") for (int n = 0; n < 2; ++n) _Pragma("unroll") for (int k = 0; k < 2; ++k) dst[n][k] = *(const PG8_LAS bf16x8*)(lds + PG8_SB(b, h) + boff + n * 2048 + k * 1024); } while (0)
; #define PG8_WAIT_V(n) asm volatile("s_waitcnt vmcnt(" #n ")" ::: "memory")
; #define PG8_WAIT_L(n) asm volatile("s_waitcnt lgkmcnt(" #n ")" ::: "memory")
; template <class Epi, bool ALIGN_EPI, bool ABLK = false>
; __device__ __forceinline__ void gemm_phase(PG8_LAS unsigned char* lds, const Gemm g, const StaticOrder& S, const Epi& E) {
;     ...
;         const bool has_next = S.next(ui + 1, nxt);
;         const char* nA = has_next ? PG8_ABASE(nxt) : cA; const char* nB = has_next ? PG8_BBASE(nxt) : cB;
;         for (int t = 0; t < nt; t += 2) {
;             const bool last = (t == nt - 2);
;             const char* a1 = cA + (size_t)(t + 1) * kstepA;
;             const char* a2 = last ? nA : cA + (size_t)(t + 2) * kstepA; const char* b2 = last ? nB : cB + (size_t)(t + 2) * kstepB;
;             const char* a3 = a2 + kstepA; const char* b3 = b2 + kstepB;
;             PG8_LDB(B0, 0, 0); PG8_LDB(B1, 0, 1); PG8_SCHED; PG8_LDA(At, 0, 0); PG8_STAGE(PG8_SA(1, 1), a1 + hstepA, voffA);
;             PG8_WAIT_V(8); PG8_WAIT_L(0); PG8_BAR; PG8_MMA(0, 0, At, B0); PG8_MMA(0, 1, At, B1); PG8_BAR; PG8_SCHED;
;             PG8_LDA(At, 0, 1); PG8_STAGE(PG8_SB(0, 0), b2, voffB); PG8_STAGE(PG8_SB(0, 1), b2 + hstepB, voffB); PG8_STAGE(PG8_SA(0, 0), a2, voffA);
;     ...
;         if (!E.keep(cur)) {
; #pragma unroll
;             for (int a = 0; a < 2; ++a)
; #pragma unroll
;                 for (int b = 0; b < 2; ++b)
; #pragma unroll
;                     for (int m = 0; m < 4; ++m)
; #pragma unroll
;                         for (int n = 0; n < 2; ++n) acc[a][b][m][n] = (f32x4){0.f, 0.f, 0.f, 0.f};
;         }
;         cur = nxt; cA = nA; cB = nB; ++ui;
.LBB0_2288:
	s_ashr_i32 s51, s50, 31
	s_lshl_b64 s[52:53], s[50:51], 19
	s_add_u32 s52, s20, s52
	s_addc_u32 s53, s21, s53
	s_and_b64 s[54:55], s[6:7], exec
	s_cselect_b32 s51, s53, s59
	s_cselect_b32 s60, s52, s58
	s_ashr_i32 s49, s48, 31
	s_lshl_b64 s[54:55], s[48:49], 19
	s_add_u32 s54, s18, s54
	s_addc_u32 s55, s19, s55
	s_and_b64 s[80:81], s[6:7], exec
	s_cselect_b32 s49, s55, s57
	s_cselect_b32 s61, s54, s56
	s_add_u32 s80, s56, 0x100
	s_addc_u32 s81, s57, 0
	s_add_u32 s56, s58, 0x10000
	v_mov_b32_e32 v2, 0
	s_addc_u32 s57, s59, 0
	s_mov_b32 s82, -2
	s_waitcnt lgkmcnt(0)
	v_mov_b32_e32 v3, v2
	v_mov_b32_e32 v4, v2
	v_mov_b32_e32 v5, v2
	v_mov_b32_e32 v6, v2
	v_mov_b32_e32 v7, v2
	v_mov_b32_e32 v8, v2
	v_mov_b32_e32 v9, v2
	v_mov_b32_e32 v18, v2
	v_mov_b32_e32 v19, v2
	v_mov_b32_e32 v20, v2
	v_mov_b32_e32 v21, v2
	v_mov_b32_e32 v22, v2
	v_mov_b32_e32 v23, v2
	v_mov_b32_e32 v24, v2
	v_mov_b32_e32 v25, v2
	v_mov_b32_e32 v34, v2
	v_mov_b32_e32 v35, v2
	v_mov_b32_e32 v36, v2
	v_mov_b32_e32 v37, v2
	v_mov_b32_e32 v38, v2
	v_mov_b32_e32 v39, v2
	v_mov_b32_e32 v40, v2
	v_mov_b32_e32 v41, v2
	v_mov_b32_e32 v50, v2
	v_mov_b32_e32 v51, v2
	v_mov_b32_e32 v52, v2
	v_mov_b32_e32 v53, v2
	v_mov_b32_e32 v54, v2
	v_mov_b32_e32 v55, v2
	v_mov_b32_e32 v56, v2
	v_mov_b32_e32 v57, v2
	v_mov_b32_e32 v10, v2
	v_mov_b32_e32 v11, v2
	v_mov_b32_e32 v12, v2
	v_mov_b32_e32 v13, v2
	v_mov_b32_e32 v14, v2
	v_mov_b32_e32 v15, v2
	v_mov_b32_e32 v16, v2
	v_mov_b32_e32 v17, v2
	v_mov_b32_e32 v26, v2
	v_mov_b32_e32 v27, v2
	v_mov_b32_e32 v28, v2
	v_mov_b32_e32 v29, v2
	v_mov_b32_e32 v30, v2
	v_mov_b32_e32 v31, v2
	v_mov_b32_e32 v32, v2
	v_mov_b32_e32 v33, v2
	v_mov_b32_e32 v42, v2
	v_mov_b32_e32 v43, v2
	v_mov_b32_e32 v44, v2
	v_mov_b32_e32 v45, v2
	v_mov_b32_e32 v46, v2
	v_mov_b32_e32 v47, v2
	v_mov_b32_e32 v48, v2
	v_mov_b32_e32 v49, v2
	v_mov_b32_e32 v58, v2
	v_mov_b32_e32 v59, v2
	v_mov_b32_e32 v60, v2
	v_mov_b32_e32 v61, v2
	v_mov_b32_e32 v62, v2
	v_mov_b32_e32 v63, v2
	v_mov_b32_e32 v64, v2
	v_mov_b32_e32 v65, v2
	v_mov_b32_e32 v66, v2
	v_mov_b32_e32 v67, v2
	v_mov_b32_e32 v68, v2
	v_mov_b32_e32 v69, v2
	v_mov_b32_e32 v70, v2
	v_mov_b32_e32 v71, v2
	v_mov_b32_e32 v72, v2
	v_mov_b32_e32 v73, v2
	v_mov_b32_e32 v82, v2
	v_mov_b32_e32 v83, v2
	v_mov_b32_e32 v84, v2
	v_mov_b32_e32 v85, v2
	v_mov_b32_e32 v86, v2
	v_mov_b32_e32 v87, v2
	v_mov_b32_e32 v88, v2
	v_mov_b32_e32 v89, v2
	v_mov_b32_e32 v98, v2
	v_mov_b32_e32 v99, v2
	v_mov_b32_e32 v100, v2
	v_mov_b32_e32 v101, v2
	v_mov_b32_e32 v106, v2
	v_mov_b32_e32 v107, v2
	v_mov_b32_e32 v108, v2
	v_mov_b32_e32 v109, v2
	v_mov_b32_e32 v126, v2
	v_mov_b32_e32 v127, v2
	v_mov_b32_e32 v128, v2
	v_mov_b32_e32 v129, v2
	v_mov_b32_e32 v130, v2
	v_mov_b32_e32 v131, v2
	v_mov_b32_e32 v132, v2
	v_mov_b32_e32 v133, v2
	v_mov_b32_e32 v74, v2
	v_mov_b32_e32 v75, v2
	v_mov_b32_e32 v76, v2
	v_mov_b32_e32 v77, v2
	v_mov_b32_e32 v78, v2
	v_mov_b32_e32 v79, v2
	v_mov_b32_e32 v80, v2
	v_mov_b32_e32 v81, v2
	v_mov_b32_e32 v90, v2
	v_mov_b32_e32 v91, v2
	v_mov_b32_e32 v92, v2
	v_mov_b32_e32 v93, v2
	v_mov_b32_e32 v94, v2
	v_mov_b32_e32 v95, v2
	v_mov_b32_e32 v96, v2
	v_mov_b32_e32 v97, v2
	v_mov_b32_e32 v114, v2
	v_mov_b32_e32 v115, v2
	v_mov_b32_e32 v116, v2
	v_mov_b32_e32 v117, v2
	v_mov_b32_e32 v118, v2
	v_mov_b32_e32 v119, v2
	v_mov_b32_e32 v120, v2
	v_mov_b32_e32 v121, v2
	v_mov_b32_e32 v138, v2
	v_mov_b32_e32 v139, v2
	v_mov_b32_e32 v140, v2
	v_mov_b32_e32 v141, v2
	v_mov_b32_e32 v142, v2
	v_mov_b32_e32 v143, v2
	v_mov_b32_e32 v144, v2
	v_mov_b32_e32 v145, v2
	s_setprio 0
	v_readfirstlane_b32 s101, v0
	s_nop 3
	s_bfe_u32 s101, s101, 0x40006
	s_cmp_ge_u32 s101, 4
	s_cbranch_scc0 .Lprio_2289
	s_setprio 1
.Lprio_2289:
.LBB0_2289:
	ds_read_b128 v[102:105], v232
	ds_read_b128 v[110:113], v232 offset:1024
	ds_read_b128 v[122:125], v232 offset:2048
	ds_read_b128 v[134:137], v232 offset:3072
	ds_read_b128 v[146:149], v233
	ds_read_b128 v[150:153], v233 offset:1024
	ds_read_b128 v[154:157], v233 offset:2048
	ds_read_b128 v[158:161], v233 offset:3072
	s_cmp_eq_u32 s82, 12
	s_cselect_b32 s85, s51, s57
	s_cselect_b32 s84, s60, s56
	s_cselect_b32 s59, s49, s81
	s_cselect_b32 s58, s61, s80
	s_movk_i32 s86, 0xc000
	v_lshl_add_u64 v[212:213], s[56:57], 0, v[186:187]
	s_mov_b32 s87, -1
	v_lshl_add_u64 v[244:245], v[212:213], 0, s[86:87]
	s_movk_i32 s86, 0xe000
	s_add_i32 m0, s9, 0xc000
	s_mov_b32 s87, -1
	ds_read_b128 v[162:165], v234
	ds_read_b128 v[166:169], v234 offset:1024
	ds_read_b128 v[170:173], v234 offset:2048
	ds_read_b128 v[174:177], v234 offset:3072
	ds_read_b128 v[178:181], v234 offset:4096
	ds_read_b128 v[182:185], v234 offset:5120
	ds_read_b128 v[236:239], v234 offset:6144
	ds_read_b128 v[240:243], v234 offset:7168
	global_load_lds_dwordx4 v[244:245], off
	v_lshl_add_u64 v[212:213], v[212:213], 0, s[86:87]
	s_add_i32 m0, s9, 0xe000
	s_nop 0
	global_load_lds_dwordx4 v[212:213], off
	s_waitcnt vmcnt(8)
	s_waitcnt lgkmcnt(0)
	s_barrier
; #define PG8_STAGE(bufoff, gbase, voff) do { _Pragma("unroll") for (int _i = 0; _i < 2; ++_i) \
;         __builtin_amdgcn_global_load_lds((const unsigned*)((const char*)(gbase) + (voff)[_i]), (PG8_LAS unsigned*)(lds + (bufoff) + ldsw + _i * 8192), 16, 0, 0); } while (0)
; #define PG8_LDA(dst, b, h) do { _Pragma("unroll") for (int m = 0; m < 4; ++m) _Pragma("unroll") for (int k = 0; k < 2; ++k) dst[m][k] = *(const PG8_LAS bf16x8*)(lds + PG8_SA(b, h) + aoff + m * 2048 + k * 1024); } while (0)
; #define PG8_MMA(ai, bj, At, Bt) do { __builtin_amdgcn_s_setprio(1); _Pragma("unroll") for (int m = 0; m < 4; ++m) _Pragma("unroll") for (int n = 0; n < 2; ++n) _Pragma("unroll") for (int k = 0; k < 2; ++k) \
;         acc[ai][bj][m][n] = __builtin_amdgcn_mfma_f32_16x16x32_bf16(Bt[n][k], At[m][k], acc[ai][bj][m][n], 0, 0, 0); __builtin_amdgcn_s_setprio(0); } while (0)
; #define PG8_WAIT_V(n) asm volatile("s_waitcnt vmcnt(" #n ")" ::: "memory")
; #define PG8_WAIT_L(n) asm volatile("s_waitcnt lgkmcnt(" #n ")" ::: "memory")
; #define PG8_BAR __builtin_amdgcn_s_barrier()
; #define PG8_SCHED __builtin_amdgcn_sched_barrier(0)
; template <class Epi, bool ALIGN_EPI, bool ABLK = false>
; __device__ __forceinline__ void gemm_phase(PG8_LAS unsigned char* lds, const Gemm g, const StaticOrder& S, const Epi& E) {
;     ...
;             PG8_WAIT_V(8); PG8_WAIT_L(0); PG8_BAR; PG8_MMA(0, 0, At, B0); PG8_MMA(0, 1, At, B1); PG8_BAR; PG8_SCHED;
;             PG8_LDA(At, 0, 1); PG8_STAGE(PG8_SB(0, 0), b2, voffB); PG8_STAGE(PG8_SB(0, 1), b2 + hstepB, voffB); PG8_STAGE(PG8_SA(0, 0), a2, voffA);
;             PG8_WAIT_V(8); PG8_WAIT_L(0); PG8_BAR; PG8_MMA(1, 0, At, B0); PG8_MMA(1, 1, At, B1); PG8_BAR; PG8_SCHED;
	s_waitcnt lgkmcnt(0)
	v_mfma_f32_16x16x32_bf16 v[142:145], v[102:105], v[162:165], v[142:145]
	v_mfma_f32_16x16x32_bf16 v[138:141], v[122:125], v[162:165], v[138:141]
	v_mfma_f32_16x16x32_bf16 v[118:121], v[102:105], v[170:173], v[118:121]
	v_mfma_f32_16x16x32_bf16 v[114:117], v[122:125], v[170:173], v[114:117]
	v_mfma_f32_16x16x32_bf16 v[94:97], v[102:105], v[178:181], v[94:97]
	v_mfma_f32_16x16x32_bf16 v[90:93], v[122:125], v[178:181], v[90:93]
	v_mfma_f32_16x16x32_bf16 v[78:81], v[102:105], v[236:239], v[78:81]
	v_mfma_f32_16x16x32_bf16 v[74:77], v[122:125], v[236:239], v[74:77]
	v_mfma_f32_16x16x32_bf16 v[142:145], v[110:113], v[166:169], v[142:145]
	v_mfma_f32_16x16x32_bf16 v[138:141], v[134:137], v[166:169], v[138:141]
	v_mfma_f32_16x16x32_bf16 v[118:121], v[110:113], v[174:177], v[118:121]
	v_mfma_f32_16x16x32_bf16 v[114:117], v[134:137], v[174:177], v[114:117]
	v_mfma_f32_16x16x32_bf16 v[94:97], v[110:113], v[182:185], v[94:97]
	v_mfma_f32_16x16x32_bf16 v[90:93], v[134:137], v[182:185], v[90:93]
	v_mfma_f32_16x16x32_bf16 v[78:81], v[110:113], v[240:243], v[78:81]
	v_mfma_f32_16x16x32_bf16 v[74:77], v[134:137], v[240:243], v[74:77]
	v_mfma_f32_16x16x32_bf16 v[130:133], v[146:149], v[162:165], v[130:133]
	s_add_i32 s83, s77, s65
	v_mfma_f32_16x16x32_bf16 v[126:129], v[154:157], v[162:165], v[126:129]
	s_mov_b32 m0, s83
	v_mfma_f32_16x16x32_bf16 v[106:109], v[146:149], v[170:173], v[106:109]
	v_mfma_f32_16x16x32_bf16 v[98:101], v[154:157], v[170:173], v[98:101]
	v_mfma_f32_16x16x32_bf16 v[86:89], v[146:149], v[178:181], v[86:89]
	v_mfma_f32_16x16x32_bf16 v[82:85], v[154:157], v[178:181], v[82:85]
	v_mfma_f32_16x16x32_bf16 v[70:73], v[146:149], v[236:239], v[70:73]
	v_mfma_f32_16x16x32_bf16 v[66:69], v[154:157], v[236:239], v[66:69]
	v_mfma_f32_16x16x32_bf16 v[130:133], v[150:153], v[166:169], v[130:133]
	v_mfma_f32_16x16x32_bf16 v[126:129], v[158:161], v[166:169], v[126:129]
	v_mfma_f32_16x16x32_bf16 v[106:109], v[150:153], v[174:177], v[106:109]
	v_mfma_f32_16x16x32_bf16 v[98:101], v[158:161], v[174:177], v[98:101]
	v_mfma_f32_16x16x32_bf16 v[86:89], v[150:153], v[182:185], v[86:89]
	v_mfma_f32_16x16x32_bf16 v[82:85], v[158:161], v[182:185], v[82:85]
	v_mfma_f32_16x16x32_bf16 v[70:73], v[150:153], v[240:243], v[70:73]
	v_mfma_f32_16x16x32_bf16 v[66:69], v[158:161], v[240:243], v[66:69]
	s_barrier
	v_lshl_add_u64 v[212:213], s[58:59], 0, v[188:189]
	ds_read_b128 v[162:165], v234 offset:16384
	ds_read_b128 v[166:169], v234 offset:17408
	ds_read_b128 v[170:173], v234 offset:18432
	ds_read_b128 v[174:177], v234 offset:19456
	ds_read_b128 v[178:181], v234 offset:20480
	ds_read_b128 v[182:185], v234 offset:21504
	ds_read_b128 v[236:239], v234 offset:22528
	ds_read_b128 v[240:243], v234 offset:23552
	global_load_lds_dwordx4 v[212:213], off
	s_add_i32 m0, s83, 0x2000
	s_add_u32 s86, s58, 0x40000
	v_lshl_add_u64 v[244:245], s[58:59], 0, v[190:191]
	s_addc_u32 s87, s59, 0
	s_add_i32 s83, s78, s65
	global_load_lds_dwordx4 v[244:245], off
	v_lshl_add_u64 v[246:247], s[86:87], 0, v[188:189]
	s_mov_b32 m0, s83
	s_nop 0
	global_load_lds_dwordx4 v[246:247], off
	v_lshl_add_u64 v[246:247], s[86:87], 0, v[190:191]
	s_add_i32 m0, s83, 0x2000
	s_nop 0
	global_load_lds_dwordx4 v[246:247], off
	v_lshl_add_u64 v[246:247], s[84:85], 0, v[186:187]
	s_mov_b32 m0, s9
	v_lshl_add_u64 v[248:249], v[246:247], 0, s[10:11]
	global_load_lds_dwordx4 v[246:247], off
	s_mov_b32 m0, s66
	s_nop 0
	global_load_lds_dwordx4 v[248:249], off
	s_waitcnt vmcnt(8)
	s_waitcnt lgkmcnt(0)
	s_barrier
	s_waitcnt lgkmcnt(0)
	v_mfma_f32_16x16x32_bf16 v[62:65], v[102:105], v[162:165], v[62:65]
	v_mfma_f32_16x16x32_bf16 v[58:61], v[122:125], v[162:165], v[58:61]
	v_mfma_f32_16x16x32_bf16 v[46:49], v[102:105], v[170:173], v[46:49]
	v_mfma_f32_16x16x32_bf16 v[42:45], v[122:125], v[170:173], v[42:45]
	v_mfma_f32_16x16x32_bf16 v[30:33], v[102:105], v[178:181], v[30:33]
	v_mfma_f32_16x16x32_bf16 v[26:29], v[122:125], v[178:181], v[26:29]
	v_mfma_f32_16x16x32_bf16 v[14:17], v[102:105], v[236:239], v[14:17]
	v_mfma_f32_16x16x32_bf16 v[10:13], v[122:125], v[236:239], v[10:13]
	v_mfma_f32_16x16x32_bf16 v[62:65], v[110:113], v[166:169], v[62:65]
	v_mfma_f32_16x16x32_bf16 v[58:61], v[134:137], v[166:169], v[58:61]
	v_mfma_f32_16x16x32_bf16 v[46:49], v[110:113], v[174:177], v[46:49]
	v_mfma_f32_16x16x32_bf16 v[42:45], v[134:137], v[174:177], v[42:45]
	v_mfma_f32_16x16x32_bf16 v[30:33], v[110:113], v[182:185], v[30:33]
	v_mfma_f32_16x16x32_bf16 v[26:29], v[134:137], v[182:185], v[26:29]
	v_mfma_f32_16x16x32_bf16 v[14:17], v[110:113], v[240:243], v[14:17]
	v_mfma_f32_16x16x32_bf16 v[10:13], v[134:137], v[240:243], v[10:13]
	v_mfma_f32_16x16x32_bf16 v[54:57], v[146:149], v[162:165], v[54:57]
	s_add_i32 s83, 0, 0x18000
	v_mfma_f32_16x16x32_bf16 v[50:53], v[154:157], v[162:165], v[50:53]
	s_add_i32 s84, 0, 0x1c000
	v_mfma_f32_16x16x32_bf16 v[38:41], v[146:149], v[170:173], v[38:41]
	v_mfma_f32_16x16x32_bf16 v[34:37], v[154:157], v[170:173], v[34:37]
	v_mfma_f32_16x16x32_bf16 v[22:25], v[146:149], v[178:181], v[22:25]
	v_mfma_f32_16x16x32_bf16 v[18:21], v[154:157], v[178:181], v[18:21]
	v_mfma_f32_16x16x32_bf16 v[6:9], v[146:149], v[236:239], v[6:9]
	v_mfma_f32_16x16x32_bf16 v[2:5], v[154:157], v[236:239], v[2:5]
	v_mfma_f32_16x16x32_bf16 v[54:57], v[150:153], v[166:169], v[54:57]
	v_mfma_f32_16x16x32_bf16 v[50:53], v[158:161], v[166:169], v[50:53]
	v_mfma_f32_16x16x32_bf16 v[38:41], v[150:153], v[174:177], v[38:41]
	v_mfma_f32_16x16x32_bf16 v[34:37], v[158:161], v[174:177], v[34:37]
	v_mfma_f32_16x16x32_bf16 v[22:25], v[150:153], v[182:185], v[22:25]
	v_mfma_f32_16x16x32_bf16 v[18:21], v[158:161], v[182:185], v[18:21]
	v_mfma_f32_16x16x32_bf16 v[6:9], v[150:153], v[240:243], v[6:9]
	v_mfma_f32_16x16x32_bf16 v[2:5], v[158:161], v[240:243], v[2:5]
	s_barrier
; #define PG8_STAGE(bufoff, gbase, voff) do { _Pragma("unroll") for (int _i = 0; _i < 2; ++_i) \
;         __builtin_amdgcn_global_load_lds((const unsigned*)((const char*)(gbase) + (voff)[_i]), (PG8_LAS unsigned*)(lds + (bufoff) + ldsw + _i * 8192), 16, 0, 0); } while (0)
; #define PG8_LDA(dst, b, h) do { _Pragma("unroll") for (int m = 0; m < 4; ++m) _Pragma("unroll") for (int k = 0; k < 2; ++k) dst[m][k] = *(const PG8_LAS bf16x8*)(lds + PG8_SA(b, h) + aoff + m * 2048 + k * 1024); } while (0)
; #define PG8_LDB(dst, b, h) do { _Pragma("unroll") for (int n = 0; n < 2; ++n) _Pragma("unroll") for (int k = 0; k < 2; ++k) dst[n][k] = *(const PG8_LAS bf16x8*)(lds + PG8_SB(b, h) + boff + n * 2048 + k * 1024); } while (0)
; #define PG8_MMA(ai, bj, At, Bt) do { __builtin_amdgcn_s_setprio(1); _Pragma("unroll") for (int m = 0; m < 4; ++m) _Pragma("unroll") for (int n = 0; n < 2; ++n) _Pragma("unroll") for (int k = 0; k < 2; ++k) \
;         acc[ai][bj][m][n] = __builtin_amdgcn_mfma_f32_16x16x32_bf16(Bt[n][k], At[m][k], acc[ai][bj][m][n], 0, 0, 0); __builtin_amdgcn_s_setprio(0); } while (0)
; #define PG8_WAIT_V(n) asm volatile("s_waitcnt vmcnt(" #n ")" ::: "memory")
; #define PG8_WAIT_L(n) asm volatile("s_waitcnt lgkmcnt(" #n ")" ::: "memory")
; #define PG8_BAR __builtin_amdgcn_s_barrier()
; #define PG8_SCHED __builtin_amdgcn_sched_barrier(0)
; template <class Epi, bool ALIGN_EPI, bool ABLK = false>
; __device__ __forceinline__ void gemm_phase(PG8_LAS unsigned char* lds, const Gemm g, const StaticOrder& S, const Epi& E) {
;     ...
;             PG8_LDB(B0, 1, 0); PG8_LDB(B1, 1, 1); PG8_SCHED; PG8_LDA(At, 1, 0); PG8_STAGE(PG8_SA(0, 1), a2 + hstepA, voffA);
;             PG8_WAIT_V(8); PG8_WAIT_L(0); PG8_BAR; PG8_MMA(0, 0, At, B0); PG8_MMA(0, 1, At, B1); PG8_BAR; PG8_SCHED;
;             PG8_LDA(At, 1, 1); PG8_STAGE(PG8_SB(1, 0), b3, voffB); PG8_STAGE(PG8_SB(1, 1), b3 + hstepB, voffB); PG8_STAGE(PG8_SA(1, 0), a3, voffA);
;             PG8_WAIT_V(8); PG8_WAIT_L(0); PG8_BAR; PG8_MMA(1, 0, At, B0); PG8_MMA(1, 1, At, B1); PG8_BAR; PG8_SCHED;
	v_add_u32_e32 v134, s83, v224
	v_add_u32_e32 v158, s84, v224
	ds_read_b128 v[102:105], v134
	ds_read_b128 v[110:113], v134 offset:1024
	ds_read_b128 v[122:125], v134 offset:2048
	ds_read_b128 v[134:137], v134 offset:3072
	ds_read_b128 v[146:149], v158
	ds_read_b128 v[150:153], v158 offset:1024
	ds_read_b128 v[154:157], v158 offset:2048
	ds_read_b128 v[158:161], v158 offset:3072
	s_mov_b32 m0, s67
	v_lshl_add_u64 v[248:249], v[246:247], 0, s[12:13]
	ds_read_b128 v[162:165], v234 offset:32768
	ds_read_b128 v[166:169], v234 offset:33792
	ds_read_b128 v[170:173], v234 offset:34816
	ds_read_b128 v[174:177], v234 offset:35840
	ds_read_b128 v[178:181], v234 offset:36864
	ds_read_b128 v[182:185], v234 offset:37888
	ds_read_b128 v[236:239], v234 offset:38912
	ds_read_b128 v[240:243], v234 offset:39936
	global_load_lds_dwordx4 v[248:249], off
	v_lshl_add_u64 v[248:249], v[246:247], 0, s[24:25]
	s_mov_b32 m0, s68
	s_nop 0
	global_load_lds_dwordx4 v[248:249], off
	s_waitcnt vmcnt(8)
	s_waitcnt lgkmcnt(0)
	s_barrier
	s_waitcnt lgkmcnt(0)
	v_mfma_f32_16x16x32_bf16 v[142:145], v[102:105], v[162:165], v[142:145]
	v_mfma_f32_16x16x32_bf16 v[138:141], v[122:125], v[162:165], v[138:141]
	v_mfma_f32_16x16x32_bf16 v[118:121], v[102:105], v[170:173], v[118:121]
	v_mfma_f32_16x16x32_bf16 v[114:117], v[122:125], v[170:173], v[114:117]
	v_mfma_f32_16x16x32_bf16 v[94:97], v[102:105], v[178:181], v[94:97]
	v_mfma_f32_16x16x32_bf16 v[90:93], v[122:125], v[178:181], v[90:93]
	v_mfma_f32_16x16x32_bf16 v[78:81], v[102:105], v[236:239], v[78:81]
	v_mfma_f32_16x16x32_bf16 v[74:77], v[122:125], v[236:239], v[74:77]
	v_mfma_f32_16x16x32_bf16 v[142:145], v[110:113], v[166:169], v[142:145]
	v_mfma_f32_16x16x32_bf16 v[138:141], v[134:137], v[166:169], v[138:141]
	v_mfma_f32_16x16x32_bf16 v[118:121], v[110:113], v[174:177], v[118:121]
	v_mfma_f32_16x16x32_bf16 v[114:117], v[134:137], v[174:177], v[114:117]
	v_mfma_f32_16x16x32_bf16 v[94:97], v[110:113], v[182:185], v[94:97]
	v_mfma_f32_16x16x32_bf16 v[90:93], v[134:137], v[182:185], v[90:93]
	v_mfma_f32_16x16x32_bf16 v[78:81], v[110:113], v[240:243], v[78:81]
	v_mfma_f32_16x16x32_bf16 v[74:77], v[134:137], v[240:243], v[74:77]
	v_mfma_f32_16x16x32_bf16 v[130:133], v[146:149], v[162:165], v[130:133]
	s_add_i32 s83, s83, s65
	v_mfma_f32_16x16x32_bf16 v[126:129], v[154:157], v[162:165], v[126:129]
	s_mov_b32 m0, s83
	v_mfma_f32_16x16x32_bf16 v[106:109], v[146:149], v[170:173], v[106:109]
	v_mfma_f32_16x16x32_bf16 v[98:101], v[154:157], v[170:173], v[98:101]
	v_mfma_f32_16x16x32_bf16 v[86:89], v[146:149], v[178:181], v[86:89]
	v_mfma_f32_16x16x32_bf16 v[82:85], v[154:157], v[178:181], v[82:85]
	v_mfma_f32_16x16x32_bf16 v[70:73], v[146:149], v[236:239], v[70:73]
	v_mfma_f32_16x16x32_bf16 v[66:69], v[154:157], v[236:239], v[66:69]
	v_mfma_f32_16x16x32_bf16 v[130:133], v[150:153], v[166:169], v[130:133]
	v_mfma_f32_16x16x32_bf16 v[126:129], v[158:161], v[166:169], v[126:129]
	v_mfma_f32_16x16x32_bf16 v[106:109], v[150:153], v[174:177], v[106:109]
	v_mfma_f32_16x16x32_bf16 v[98:101], v[158:161], v[174:177], v[98:101]
	v_mfma_f32_16x16x32_bf16 v[86:89], v[150:153], v[182:185], v[86:89]
	v_mfma_f32_16x16x32_bf16 v[82:85], v[158:161], v[182:185], v[82:85]
	v_mfma_f32_16x16x32_bf16 v[70:73], v[150:153], v[240:243], v[70:73]
	v_mfma_f32_16x16x32_bf16 v[66:69], v[158:161], v[240:243], v[66:69]
	s_barrier
	v_lshl_add_u64 v[212:213], v[212:213], 0, s[34:35]
	ds_read_b128 v[162:165], v234 offset:49152
	ds_read_b128 v[166:169], v234 offset:50176
	ds_read_b128 v[170:173], v234 offset:51200
	ds_read_b128 v[174:177], v234 offset:52224
	ds_read_b128 v[178:181], v234 offset:53248
	ds_read_b128 v[182:185], v234 offset:54272
	ds_read_b128 v[236:239], v234 offset:55296
	ds_read_b128 v[240:243], v234 offset:56320
	global_load_lds_dwordx4 v[212:213], off
	s_add_i32 m0, s83, 0x2000
	s_add_u32 s58, s58, 0x40080
	v_lshl_add_u64 v[212:213], v[244:245], 0, s[34:35]
	s_addc_u32 s59, s59, 0
	s_add_i32 s83, s84, s65
	global_load_lds_dwordx4 v[212:213], off
	v_lshl_add_u64 v[212:213], s[58:59], 0, v[188:189]
	s_mov_b32 m0, s83
	s_nop 0
	global_load_lds_dwordx4 v[212:213], off
	v_lshl_add_u64 v[212:213], s[58:59], 0, v[190:191]
	s_add_i32 m0, s83, 0x2000
	s_nop 0
	global_load_lds_dwordx4 v[212:213], off
	v_lshl_add_u64 v[212:213], v[246:247], 0, s[36:37]
	s_mov_b32 m0, s71
	s_nop 0
	global_load_lds_dwordx4 v[212:213], off
	v_lshl_add_u64 v[212:213], v[246:247], 0, s[38:39]
	s_mov_b32 m0, s72
	s_nop 0
	global_load_lds_dwordx4 v[212:213], off
	s_waitcnt vmcnt(8)
	s_waitcnt lgkmcnt(0)
	s_barrier
	s_waitcnt lgkmcnt(0)
	v_mfma_f32_16x16x32_bf16 v[62:65], v[102:105], v[162:165], v[62:65]
	v_mfma_f32_16x16x32_bf16 v[58:61], v[122:125], v[162:165], v[58:61]
	v_mfma_f32_16x16x32_bf16 v[46:49], v[102:105], v[170:173], v[46:49]
	v_mfma_f32_16x16x32_bf16 v[42:45], v[122:125], v[170:173], v[42:45]
	v_mfma_f32_16x16x32_bf16 v[30:33], v[102:105], v[178:181], v[30:33]
	v_mfma_f32_16x16x32_bf16 v[26:29], v[122:125], v[178:181], v[26:29]
	v_mfma_f32_16x16x32_bf16 v[14:17], v[102:105], v[236:239], v[14:17]
	v_mfma_f32_16x16x32_bf16 v[10:13], v[122:125], v[236:239], v[10:13]
	v_mfma_f32_16x16x32_bf16 v[62:65], v[110:113], v[166:169], v[62:65]
	v_mfma_f32_16x16x32_bf16 v[58:61], v[134:137], v[166:169], v[58:61]
	v_mfma_f32_16x16x32_bf16 v[46:49], v[110:113], v[174:177], v[46:49]
	v_mfma_f32_16x16x32_bf16 v[42:45], v[134:137], v[174:177], v[42:45]
	v_mfma_f32_16x16x32_bf16 v[30:33], v[110:113], v[182:185], v[30:33]
	v_mfma_f32_16x16x32_bf16 v[26:29], v[134:137], v[182:185], v[26:29]
	v_mfma_f32_16x16x32_bf16 v[14:17], v[110:113], v[240:243], v[14:17]
	v_mfma_f32_16x16x32_bf16 v[10:13], v[134:137], v[240:243], v[10:13]
	v_mfma_f32_16x16x32_bf16 v[54:57], v[146:149], v[162:165], v[54:57]
	s_add_i32 s82, s82, 2
	v_mfma_f32_16x16x32_bf16 v[50:53], v[154:157], v[162:165], v[50:53]
	s_add_u32 s80, s80, 0x100
	v_mfma_f32_16x16x32_bf16 v[38:41], v[146:149], v[170:173], v[38:41]
	s_addc_u32 s81, s81, 0
	v_mfma_f32_16x16x32_bf16 v[34:37], v[154:157], v[170:173], v[34:37]
	s_add_u32 s56, s56, 0x10000
	v_mfma_f32_16x16x32_bf16 v[22:25], v[146:149], v[178:181], v[22:25]
	s_addc_u32 s57, s57, 0
	v_mfma_f32_16x16x32_bf16 v[18:21], v[154:157], v[178:181], v[18:21]
	s_cmp_gt_u32 s82, 13
	v_mfma_f32_16x16x32_bf16 v[6:9], v[146:149], v[236:239], v[6:9]
	v_mfma_f32_16x16x32_bf16 v[2:5], v[154:157], v[236:239], v[2:5]
	v_mfma_f32_16x16x32_bf16 v[54:57], v[150:153], v[166:169], v[54:57]
	v_mfma_f32_16x16x32_bf16 v[50:53], v[158:161], v[166:169], v[50:53]
	v_mfma_f32_16x16x32_bf16 v[38:41], v[150:153], v[174:177], v[38:41]
	v_mfma_f32_16x16x32_bf16 v[34:37], v[158:161], v[174:177], v[34:37]
	v_mfma_f32_16x16x32_bf16 v[22:25], v[150:153], v[182:185], v[22:25]
	v_mfma_f32_16x16x32_bf16 v[18:21], v[158:161], v[182:185], v[18:21]
	v_mfma_f32_16x16x32_bf16 v[6:9], v[150:153], v[240:243], v[6:9]
	v_mfma_f32_16x16x32_bf16 v[2:5], v[158:161], v[240:243], v[2:5]
	s_barrier
	s_cbranch_scc0 .LBB0_2289
	s_setprio 0
	s_and_b64 vcc, exec, s[40:41]
	s_cbranch_vccz .LBB0_2292
	s_barrier

; #define PG8_STAGE(bufoff, gbase, voff) do { _Pragma("unroll") for (int _i = 0; _i < 2; ++_i) \
;         __builtin_amdgcn_global_load_lds((const unsigned*)((const char*)(gbase) + (voff)[_i]), (PG8_LAS unsigned*)(lds + (bufoff) + ldsw + _i * 8192), 16, 0, 0); } while (0)
; #define PG8_LDA(dst, b, h) do { _Pragma("unroll") for (int m = 0; m < 4; ++m) _Pragma("unroll") for (int k = 0; k < 2; ++k) dst[m][k] = *(const PG8_LAS bf16x8*)(lds + PG8_SA(b, h) + aoff + m * 2048 + k * 1024); } while (0)
; #define PG8_LDB(dst, b, h) do { _Pragma("unroll") for (int n = 0; n < 2; ++n) _Pragma("unroll") for (int k = 0; k < 2; ++k) dst[n][k] = *(const PG8_LAS bf16x8*)(lds + PG8_SB(b, h) + boff + n * 2048 + k * 1024); } while (0)
; #define PG8_MMA(ai, bj, At, Bt) do { __builtin_amdgcn_s_setprio(1); _Pragma("unroll") for (int m = 0; m < 4; ++m) _Pragma("unroll") for (int n = 0; n < 2; ++n) _Pragma("unroll") for (int k = 0; k < 2; ++k) \
;         acc[ai][bj][m][n] = __builtin_amdgcn_mfma_f32_16x16x32_bf16(Bt[n][k], At[m][k], acc[ai][bj][m][n], 0, 0, 0); __builtin_amdgcn_s_setprio(0); } while (0)
; #define PG8_WAIT_V(n) asm volatile("s_waitcnt vmcnt(" #n ")" ::: "memory")
; #define PG8_WAIT_L(n) asm volatile("s_waitcnt lgkmcnt(" #n ")" ::: "memory")
; #define PG8_BAR __builtin_amdgcn_s_barrier()
; template <class Epi, bool ALIGN_EPI, bool ABLK = false>
; __device__ __forceinline__ void gemm_phase(PG8_LAS unsigned char* lds, const Gemm g, const StaticOrder& S, const Epi& E) {
;     ...
;         const bool has_next = S.next(ui + 1, nxt);
;         const char* nA = has_next ? PG8_ABASE(nxt) : cA; const char* nB = has_next ? PG8_BBASE(nxt) : cB;
;         for (int t = 0; t < nt; t += 2) {
;             const bool last = (t == nt - 2);
;             const char* a1 = cA + (size_t)(t + 1) * kstepA;
;             const char* a2 = last ? nA : cA + (size_t)(t + 2) * kstepA; const char* b2 = last ? nB : cB + (size_t)(t + 2) * kstepB;
;             const char* a3 = a2 + kstepA; const char* b3 = b2 + kstepB;
;             PG8_LDB(B0, 0, 0); PG8_LDB(B1, 0, 1); PG8_SCHED; PG8_LDA(At, 0, 0); PG8_STAGE(PG8_SA(1, 1), a1 + hstepA, voffA);
;             PG8_WAIT_V(8); PG8_WAIT_L(0); PG8_BAR; PG8_MMA(0, 0, At, B0); PG8_MMA(0, 1, At, B1); PG8_BAR; PG8_SCHED;
;             PG8_LDA(At, 0, 1); PG8_STAGE(PG8_SB(0, 0), b2, voffB); PG8_STAGE(PG8_SB(0, 1), b2 + hstepB, voffB); PG8_STAGE(PG8_SA(0, 0), a2, voffA);
.LBB0_2494:
	s_ashr_i32 s53, s52, 31
	s_lshl_b64 s[54:55], s[52:53], 19
	s_add_u32 s54, s11, s54
	s_addc_u32 s55, s33, s55
	s_and_b64 s[56:57], s[6:7], exec
	s_cselect_b32 s53, s55, s25
	s_cselect_b32 s79, s54, s24
	s_ashr_i32 s51, s50, 31
	s_lshl_b64 s[56:57], s[50:51], 19
	s_add_u32 s56, s12, s56
	s_addc_u32 s57, s13, s57
	s_and_b64 s[58:59], s[6:7], exec
	s_cselect_b32 s51, s57, s23
	s_cselect_b32 s80, s56, s22
	s_add_u32 s81, s22, 0x100
	s_addc_u32 s82, s23, 0
	s_mov_b32 s83, -2
	s_mov_b64 s[58:59], 0x10000
	s_setprio 0
	v_readfirstlane_b32 s101, v0
	s_nop 3
	s_bfe_u32 s101, s101, 0x40006
	s_cmp_ge_u32 s101, 4
	s_cbranch_scc0 .Lprio_2495
	s_setprio 1
.Lprio_2495:
.LBB0_2495:
	ds_read_b128 v[132:135], v251
	ds_read_b128 v[178:181], v251 offset:1024
	ds_read_b128 v[182:185], v251 offset:2048
	ds_read_b128 v[186:189], v251 offset:3072
	ds_read_b128 v[190:193], v251 offset:16384
	ds_read_b128 v[194:197], v251 offset:17408
	ds_read_b128 v[198:201], v251 offset:18432
	ds_read_b128 v[202:205], v251 offset:19456
	s_add_u32 s60, s24, s58
	s_addc_u32 s61, s25, s59
	s_sub_u32 s98, s60, 0x10000
	s_subb_u32 s99, s61, 0
	s_cmp_eq_u32 s83, 12
	s_cselect_b32 s101, s53, s61
	s_cselect_b32 s100, s79, s60
	s_cselect_b32 s61, s51, s82
	s_cselect_b32 s60, s80, s81
	s_add_i32 m0, s66, 0xc000
	ds_read_b128 v[206:209], v176
	ds_read_b128 v[210:213], v176 offset:1024
	ds_read_b128 v[214:217], v176 offset:2048
	ds_read_b128 v[218:221], v176 offset:3072
	ds_read_b128 v[222:225], v176 offset:4096
	ds_read_b128 v[226:229], v176 offset:5120
	ds_read_b128 v[230:233], v176 offset:6144
	ds_read_b128 v[234:237], v176 offset:7168
	global_load_lds_dwordx4 v249, s[98:99]
	s_add_i32 m0, s66, 0xe000
	s_nop 0
	global_load_lds_dwordx4 v250, s[98:99]
	s_waitcnt vmcnt(8)
	s_waitcnt lgkmcnt(0)
	s_barrier
	s_waitcnt lgkmcnt(0)
	v_mfma_f32_16x16x32_bf16 v[126:129], v[132:135], v[206:209], v[126:129]
	v_mfma_f32_16x16x32_bf16 v[122:125], v[182:185], v[206:209], v[122:125]
	v_mfma_f32_16x16x32_bf16 v[118:121], v[132:135], v[214:217], v[118:121]
	v_mfma_f32_16x16x32_bf16 v[114:117], v[182:185], v[214:217], v[114:117]
	v_mfma_f32_16x16x32_bf16 v[110:113], v[132:135], v[222:225], v[110:113]
	v_mfma_f32_16x16x32_bf16 v[106:109], v[182:185], v[222:225], v[106:109]
	v_mfma_f32_16x16x32_bf16 v[102:105], v[132:135], v[230:233], v[102:105]
	v_mfma_f32_16x16x32_bf16 v[98:101], v[182:185], v[230:233], v[98:101]
	v_mfma_f32_16x16x32_bf16 v[126:129], v[178:181], v[210:213], v[126:129]
	v_mfma_f32_16x16x32_bf16 v[122:125], v[186:189], v[210:213], v[122:125]
	v_mfma_f32_16x16x32_bf16 v[118:121], v[178:181], v[218:221], v[118:121]
	v_mfma_f32_16x16x32_bf16 v[114:117], v[186:189], v[218:221], v[114:117]
	v_mfma_f32_16x16x32_bf16 v[110:113], v[178:181], v[226:229], v[110:113]
	v_mfma_f32_16x16x32_bf16 v[106:109], v[186:189], v[226:229], v[106:109]
	v_mfma_f32_16x16x32_bf16 v[102:105], v[178:181], v[234:237], v[102:105]
	v_mfma_f32_16x16x32_bf16 v[98:101], v[186:189], v[234:237], v[98:101]
	v_mfma_f32_16x16x32_bf16 v[94:97], v[190:193], v[206:209], v[94:97]
	s_add_i32 s86, s75, s9
	v_mfma_f32_16x16x32_bf16 v[90:93], v[198:201], v[206:209], v[90:93]
	s_mov_b32 m0, s86
	v_mfma_f32_16x16x32_bf16 v[86:89], v[190:193], v[214:217], v[86:89]
	v_mfma_f32_16x16x32_bf16 v[82:85], v[198:201], v[214:217], v[82:85]
	v_mfma_f32_16x16x32_bf16 v[78:81], v[190:193], v[222:225], v[78:81]
	v_mfma_f32_16x16x32_bf16 v[74:77], v[198:201], v[222:225], v[74:77]
	v_mfma_f32_16x16x32_bf16 v[70:73], v[190:193], v[230:233], v[70:73]
	v_mfma_f32_16x16x32_bf16 v[66:69], v[198:201], v[230:233], v[66:69]
	v_mfma_f32_16x16x32_bf16 v[94:97], v[194:197], v[210:213], v[94:97]
	v_mfma_f32_16x16x32_bf16 v[90:93], v[202:205], v[210:213], v[90:93]
	v_mfma_f32_16x16x32_bf16 v[86:89], v[194:197], v[218:221], v[86:89]
	v_mfma_f32_16x16x32_bf16 v[82:85], v[202:205], v[218:221], v[82:85]
	v_mfma_f32_16x16x32_bf16 v[78:81], v[194:197], v[226:229], v[78:81]
	v_mfma_f32_16x16x32_bf16 v[74:77], v[202:205], v[226:229], v[74:77]
	v_mfma_f32_16x16x32_bf16 v[70:73], v[194:197], v[234:237], v[70:73]
	v_mfma_f32_16x16x32_bf16 v[66:69], v[202:205], v[234:237], v[66:69]
	s_barrier
	ds_read_b128 v[206:209], v176 offset:16384
	ds_read_b128 v[210:213], v176 offset:17408
	ds_read_b128 v[214:217], v176 offset:18432
	ds_read_b128 v[218:221], v176 offset:19456
	ds_read_b128 v[222:225], v176 offset:20480
	ds_read_b128 v[226:229], v176 offset:21504
	ds_read_b128 v[230:233], v176 offset:22528
	ds_read_b128 v[234:237], v176 offset:23552
	global_load_lds_dwordx4 v140, s[60:61]
	s_add_i32 m0, s86, 0x2000
	s_add_u32 s86, s60, 0x40000
	s_addc_u32 s87, s61, 0
	s_add_i32 s88, s76, s9
	global_load_lds_dwordx4 v142, s[60:61]
	s_mov_b32 m0, s88
	s_nop 0
	global_load_lds_dwordx4 v140, s[86:87]
	s_add_i32 m0, s88, 0x2000
	s_nop 0
	global_load_lds_dwordx4 v142, s[86:87]
	s_mov_b32 m0, s66
	s_nop 0
	global_load_lds_dwordx4 v138, s[100:101]
	s_mov_b32 m0, s67
	s_nop 0
	global_load_lds_dwordx4 v244, s[100:101]
	s_waitcnt vmcnt(8)
	s_waitcnt lgkmcnt(0)
	s_barrier
; #define PG8_STAGE(bufoff, gbase, voff) do { _Pragma("unroll") for (int _i = 0; _i < 2; ++_i) \
;         __builtin_amdgcn_global_load_lds((const unsigned*)((const char*)(gbase) + (voff)[_i]), (PG8_LAS unsigned*)(lds + (bufoff) + ldsw + _i * 8192), 16, 0, 0); } while (0)
; #define PG8_LDA(dst, b, h) do { _Pragma("unroll") for (int m = 0; m < 4; ++m) _Pragma("unroll") for (int k = 0; k < 2; ++k) dst[m][k] = *(const PG8_LAS bf16x8*)(lds + PG8_SA(b, h) + aoff + m * 2048 + k * 1024); } while (0)
; #define PG8_LDB(dst, b, h) do { _Pragma("unroll") for (int n = 0; n < 2; ++n) _Pragma("unroll") for (int k = 0; k < 2; ++k) dst[n][k] = *(const PG8_LAS bf16x8*)(lds + PG8_SB(b, h) + boff + n * 2048 + k * 1024); } while (0)
; #define PG8_MMA(ai, bj, At, Bt) do { __builtin_amdgcn_s_setprio(1); _Pragma("unroll") for (int m = 0; m < 4; ++m) _Pragma("unroll") for (int n = 0; n < 2; ++n) _Pragma("unroll") for (int k = 0; k < 2; ++k) \
;         acc[ai][bj][m][n] = __builtin_amdgcn_mfma_f32_16x16x32_bf16(Bt[n][k], At[m][k], acc[ai][bj][m][n], 0, 0, 0); __builtin_amdgcn_s_setprio(0); } while (0)
; #define PG8_WAIT_V(n) asm volatile("s_waitcnt vmcnt(" #n ")" ::: "memory")
; #define PG8_WAIT_L(n) asm volatile("s_waitcnt lgkmcnt(" #n ")" ::: "memory")
; #define PG8_BAR __builtin_amdgcn_s_barrier()
; #define PG8_SCHED __builtin_amdgcn_sched_barrier(0)
; template <class Epi, bool ALIGN_EPI, bool ABLK = false>
; __device__ __forceinline__ void gemm_phase(PG8_LAS unsigned char* lds, const Gemm g, const StaticOrder& S, const Epi& E) {
;     ...
;             PG8_WAIT_V(8); PG8_WAIT_L(0); PG8_BAR; PG8_MMA(1, 0, At, B0); PG8_MMA(1, 1, At, B1); PG8_BAR; PG8_SCHED;
;             PG8_LDB(B0, 1, 0); PG8_LDB(B1, 1, 1); PG8_SCHED; PG8_LDA(At, 1, 0); PG8_STAGE(PG8_SA(0, 1), a2 + hstepA, voffA);
;             PG8_WAIT_V(8); PG8_WAIT_L(0); PG8_BAR; PG8_MMA(0, 0, At, B0); PG8_MMA(0, 1, At, B1); PG8_BAR; PG8_SCHED;
	s_waitcnt lgkmcnt(0)
	v_mfma_f32_16x16x32_bf16 v[62:65], v[132:135], v[206:209], v[62:65]
	v_mfma_f32_16x16x32_bf16 v[58:61], v[182:185], v[206:209], v[58:61]
	v_mfma_f32_16x16x32_bf16 v[54:57], v[132:135], v[214:217], v[54:57]
	v_mfma_f32_16x16x32_bf16 v[50:53], v[182:185], v[214:217], v[50:53]
	v_mfma_f32_16x16x32_bf16 v[46:49], v[132:135], v[222:225], v[46:49]
	v_mfma_f32_16x16x32_bf16 v[42:45], v[182:185], v[222:225], v[42:45]
	v_mfma_f32_16x16x32_bf16 v[38:41], v[132:135], v[230:233], v[38:41]
	v_mfma_f32_16x16x32_bf16 v[34:37], v[182:185], v[230:233], v[34:37]
	v_mfma_f32_16x16x32_bf16 v[62:65], v[178:181], v[210:213], v[62:65]
	v_mfma_f32_16x16x32_bf16 v[58:61], v[186:189], v[210:213], v[58:61]
	v_mfma_f32_16x16x32_bf16 v[54:57], v[178:181], v[218:221], v[54:57]
	v_mfma_f32_16x16x32_bf16 v[50:53], v[186:189], v[218:221], v[50:53]
	v_mfma_f32_16x16x32_bf16 v[46:49], v[178:181], v[226:229], v[46:49]
	v_mfma_f32_16x16x32_bf16 v[42:45], v[186:189], v[226:229], v[42:45]
	v_mfma_f32_16x16x32_bf16 v[38:41], v[178:181], v[234:237], v[38:41]
	v_mfma_f32_16x16x32_bf16 v[34:37], v[186:189], v[234:237], v[34:37]
	v_mfma_f32_16x16x32_bf16 v[30:33], v[190:193], v[206:209], v[30:33]
	s_add_i32 s84, 0, 0x18000
	v_mfma_f32_16x16x32_bf16 v[26:29], v[198:201], v[206:209], v[26:29]
	s_add_i32 s85, 0, 0x1c000
	v_mfma_f32_16x16x32_bf16 v[22:25], v[190:193], v[214:217], v[22:25]
	v_mfma_f32_16x16x32_bf16 v[18:21], v[198:201], v[214:217], v[18:21]
	v_mfma_f32_16x16x32_bf16 v[14:17], v[190:193], v[222:225], v[14:17]
	v_mfma_f32_16x16x32_bf16 v[10:13], v[198:201], v[222:225], v[10:13]
	v_mfma_f32_16x16x32_bf16 v[6:9], v[190:193], v[230:233], v[6:9]
	v_mfma_f32_16x16x32_bf16 v[2:5], v[198:201], v[230:233], v[2:5]
	v_mfma_f32_16x16x32_bf16 v[30:33], v[194:197], v[210:213], v[30:33]
	v_mfma_f32_16x16x32_bf16 v[26:29], v[202:205], v[210:213], v[26:29]
	v_mfma_f32_16x16x32_bf16 v[22:25], v[194:197], v[218:221], v[22:25]
	v_mfma_f32_16x16x32_bf16 v[18:21], v[202:205], v[218:221], v[18:21]
	v_mfma_f32_16x16x32_bf16 v[14:17], v[194:197], v[226:229], v[14:17]
	v_mfma_f32_16x16x32_bf16 v[10:13], v[202:205], v[226:229], v[10:13]
	v_mfma_f32_16x16x32_bf16 v[6:9], v[194:197], v[234:237], v[6:9]
	v_mfma_f32_16x16x32_bf16 v[2:5], v[202:205], v[234:237], v[2:5]
	s_barrier
	ds_read_b128 v[132:135], v251 offset:32768
	ds_read_b128 v[178:181], v251 offset:33792
	ds_read_b128 v[182:185], v251 offset:34816
	ds_read_b128 v[186:189], v251 offset:35840
	ds_read_b128 v[190:193], v251 offset:49152
	ds_read_b128 v[194:197], v251 offset:50176
	ds_read_b128 v[198:201], v251 offset:51200
	ds_read_b128 v[202:205], v251 offset:52224
	s_mov_b32 m0, s68
	ds_read_b128 v[206:209], v176 offset:32768
	ds_read_b128 v[210:213], v176 offset:33792
	ds_read_b128 v[214:217], v176 offset:34816
	ds_read_b128 v[218:221], v176 offset:35840
	ds_read_b128 v[222:225], v176 offset:36864
	ds_read_b128 v[226:229], v176 offset:37888
	ds_read_b128 v[230:233], v176 offset:38912
	ds_read_b128 v[234:237], v176 offset:39936
	global_load_lds_dwordx4 v245, s[100:101]
	s_mov_b32 m0, s69
	s_nop 0
	global_load_lds_dwordx4 v246, s[100:101]
	s_waitcnt vmcnt(8)
	s_waitcnt lgkmcnt(0)
	s_barrier
	s_waitcnt lgkmcnt(0)
	v_mfma_f32_16x16x32_bf16 v[126:129], v[132:135], v[206:209], v[126:129]
	v_mfma_f32_16x16x32_bf16 v[122:125], v[182:185], v[206:209], v[122:125]
	v_mfma_f32_16x16x32_bf16 v[118:121], v[132:135], v[214:217], v[118:121]
	v_mfma_f32_16x16x32_bf16 v[114:117], v[182:185], v[214:217], v[114:117]
	v_mfma_f32_16x16x32_bf16 v[110:113], v[132:135], v[222:225], v[110:113]
	v_mfma_f32_16x16x32_bf16 v[106:109], v[182:185], v[222:225], v[106:109]
	v_mfma_f32_16x16x32_bf16 v[102:105], v[132:135], v[230:233], v[102:105]
	v_mfma_f32_16x16x32_bf16 v[98:101], v[182:185], v[230:233], v[98:101]
	v_mfma_f32_16x16x32_bf16 v[126:129], v[178:181], v[210:213], v[126:129]
	v_mfma_f32_16x16x32_bf16 v[122:125], v[186:189], v[210:213], v[122:125]
	v_mfma_f32_16x16x32_bf16 v[118:121], v[178:181], v[218:221], v[118:121]
	v_mfma_f32_16x16x32_bf16 v[114:117], v[186:189], v[218:221], v[114:117]
	v_mfma_f32_16x16x32_bf16 v[110:113], v[178:181], v[226:229], v[110:113]
	v_mfma_f32_16x16x32_bf16 v[106:109], v[186:189], v[226:229], v[106:109]
	v_mfma_f32_16x16x32_bf16 v[102:105], v[178:181], v[234:237], v[102:105]
	v_mfma_f32_16x16x32_bf16 v[98:101], v[186:189], v[234:237], v[98:101]
	v_mfma_f32_16x16x32_bf16 v[94:97], v[190:193], v[206:209], v[94:97]
	s_add_i32 s84, s84, s9
	v_mfma_f32_16x16x32_bf16 v[90:93], v[198:201], v[206:209], v[90:93]
	s_add_u32 s60, s60, s28
	v_mfma_f32_16x16x32_bf16 v[86:89], v[190:193], v[214:217], v[86:89]
	s_addc_u32 s61, s61, s29
	v_mfma_f32_16x16x32_bf16 v[82:85], v[198:201], v[214:217], v[82:85]
	s_mov_b32 m0, s84
	v_mfma_f32_16x16x32_bf16 v[78:81], v[190:193], v[222:225], v[78:81]
	v_mfma_f32_16x16x32_bf16 v[74:77], v[198:201], v[222:225], v[74:77]
	v_mfma_f32_16x16x32_bf16 v[70:73], v[190:193], v[230:233], v[70:73]
	v_mfma_f32_16x16x32_bf16 v[66:69], v[198:201], v[230:233], v[66:69]
	v_mfma_f32_16x16x32_bf16 v[94:97], v[194:197], v[210:213], v[94:97]
	v_mfma_f32_16x16x32_bf16 v[90:93], v[202:205], v[210:213], v[90:93]
	v_mfma_f32_16x16x32_bf16 v[86:89], v[194:197], v[218:221], v[86:89]
	v_mfma_f32_16x16x32_bf16 v[82:85], v[202:205], v[218:221], v[82:85]
	v_mfma_f32_16x16x32_bf16 v[78:81], v[194:197], v[226:229], v[78:81]
	v_mfma_f32_16x16x32_bf16 v[74:77], v[202:205], v[226:229], v[74:77]
	v_mfma_f32_16x16x32_bf16 v[70:73], v[194:197], v[234:237], v[70:73]
	v_mfma_f32_16x16x32_bf16 v[66:69], v[202:205], v[234:237], v[66:69]
	s_barrier
; #define PG8_STAGE(bufoff, gbase, voff) do { _Pragma("unroll") for (int _i = 0; _i < 2; ++_i) \
;         __builtin_amdgcn_global_load_lds((const unsigned*)((const char*)(gbase) + (voff)[_i]), (PG8_LAS unsigned*)(lds + (bufoff) + ldsw + _i * 8192), 16, 0, 0); } while (0)
; #define PG8_LDA(dst, b, h) do { _Pragma("unroll") for (int m = 0; m < 4; ++m) _Pragma("unroll") for (int k = 0; k < 2; ++k) dst[m][k] = *(const PG8_LAS bf16x8*)(lds + PG8_SA(b, h) + aoff + m * 2048 + k * 1024); } while (0)
; #define PG8_MMA(ai, bj, At, Bt) do { __builtin_amdgcn_s_setprio(1); _Pragma("unroll") for (int m = 0; m < 4; ++m) _Pragma("unroll") for (int n = 0; n < 2; ++n) _Pragma("unroll") for (int k = 0; k < 2; ++k) \
;         acc[ai][bj][m][n] = __builtin_amdgcn_mfma_f32_16x16x32_bf16(Bt[n][k], At[m][k], acc[ai][bj][m][n], 0, 0, 0); __builtin_amdgcn_s_setprio(0); } while (0)
; #define PG8_WAIT_V(n) asm volatile("s_waitcnt vmcnt(" #n ")" ::: "memory")
; #define PG8_WAIT_L(n) asm volatile("s_waitcnt lgkmcnt(" #n ")" ::: "memory")
; #define PG8_BAR __builtin_amdgcn_s_barrier()
; #define PG8_SCHED __builtin_amdgcn_sched_barrier(0)
; template <class Epi, bool ALIGN_EPI, bool ABLK = false>
; __device__ __forceinline__ void gemm_phase(PG8_LAS unsigned char* lds, const Gemm g, const StaticOrder& S, const Epi& E) {
;     ...
;             PG8_LDA(At, 1, 1); PG8_STAGE(PG8_SB(1, 0), b3, voffB); PG8_STAGE(PG8_SB(1, 1), b3 + hstepB, voffB); PG8_STAGE(PG8_SA(1, 0), a3, voffA);
;             PG8_WAIT_V(8); PG8_WAIT_L(0); PG8_BAR; PG8_MMA(1, 0, At, B0); PG8_MMA(1, 1, At, B1); PG8_BAR; PG8_SCHED;
	ds_read_b128 v[206:209], v176 offset:49152
	ds_read_b128 v[210:213], v176 offset:50176
	ds_read_b128 v[214:217], v176 offset:51200
	ds_read_b128 v[218:221], v176 offset:52224
	ds_read_b128 v[222:225], v176 offset:53248
	ds_read_b128 v[226:229], v176 offset:54272
	ds_read_b128 v[230:233], v176 offset:55296
	ds_read_b128 v[234:237], v176 offset:56320
	global_load_lds_dwordx4 v140, s[60:61]
	s_add_i32 m0, s84, 0x2000
	s_add_i32 s84, s85, s9
	global_load_lds_dwordx4 v142, s[60:61]
	s_add_u32 s60, s60, 0x40000
	s_addc_u32 s61, s61, 0
	s_mov_b32 m0, s84
	s_nop 0
	global_load_lds_dwordx4 v140, s[60:61]
	s_add_i32 m0, s84, 0x2000
	s_nop 0
	global_load_lds_dwordx4 v142, s[60:61]
	s_mov_b32 m0, s70
	s_nop 0
	global_load_lds_dwordx4 v247, s[100:101]
	s_mov_b32 m0, s72
	s_nop 0
	global_load_lds_dwordx4 v248, s[100:101]
	s_waitcnt vmcnt(8)
	s_waitcnt lgkmcnt(0)
	s_barrier
	s_waitcnt lgkmcnt(0)
	v_mfma_f32_16x16x32_bf16 v[62:65], v[132:135], v[206:209], v[62:65]
	v_mfma_f32_16x16x32_bf16 v[58:61], v[182:185], v[206:209], v[58:61]
	v_mfma_f32_16x16x32_bf16 v[54:57], v[132:135], v[214:217], v[54:57]
	v_mfma_f32_16x16x32_bf16 v[50:53], v[182:185], v[214:217], v[50:53]
	v_mfma_f32_16x16x32_bf16 v[46:49], v[132:135], v[222:225], v[46:49]
	v_mfma_f32_16x16x32_bf16 v[42:45], v[182:185], v[222:225], v[42:45]
	v_mfma_f32_16x16x32_bf16 v[38:41], v[132:135], v[230:233], v[38:41]
	v_mfma_f32_16x16x32_bf16 v[34:37], v[182:185], v[230:233], v[34:37]
	v_mfma_f32_16x16x32_bf16 v[62:65], v[178:181], v[210:213], v[62:65]
	v_mfma_f32_16x16x32_bf16 v[58:61], v[186:189], v[210:213], v[58:61]
	v_mfma_f32_16x16x32_bf16 v[54:57], v[178:181], v[218:221], v[54:57]
	v_mfma_f32_16x16x32_bf16 v[50:53], v[186:189], v[218:221], v[50:53]
	v_mfma_f32_16x16x32_bf16 v[46:49], v[178:181], v[226:229], v[46:49]
	v_mfma_f32_16x16x32_bf16 v[42:45], v[186:189], v[226:229], v[42:45]
	v_mfma_f32_16x16x32_bf16 v[38:41], v[178:181], v[234:237], v[38:41]
	v_mfma_f32_16x16x32_bf16 v[34:37], v[186:189], v[234:237], v[34:37]
	v_mfma_f32_16x16x32_bf16 v[30:33], v[190:193], v[206:209], v[30:33]
	s_add_i32 s83, s83, 2
	v_mfma_f32_16x16x32_bf16 v[26:29], v[198:201], v[206:209], v[26:29]
	s_add_u32 s81, s81, 0x100
	v_mfma_f32_16x16x32_bf16 v[22:25], v[190:193], v[214:217], v[22:25]
	s_addc_u32 s82, s82, 0
	v_mfma_f32_16x16x32_bf16 v[18:21], v[198:201], v[214:217], v[18:21]
	s_add_u32 s58, s58, 0x10000
	v_mfma_f32_16x16x32_bf16 v[14:17], v[190:193], v[222:225], v[14:17]
	s_addc_u32 s59, s59, 0
	v_mfma_f32_16x16x32_bf16 v[10:13], v[198:201], v[222:225], v[10:13]
	s_cmp_gt_u32 s83, 13
	v_mfma_f32_16x16x32_bf16 v[6:9], v[190:193], v[230:233], v[6:9]
	v_mfma_f32_16x16x32_bf16 v[2:5], v[198:201], v[230:233], v[2:5]
	v_mfma_f32_16x16x32_bf16 v[30:33], v[194:197], v[210:213], v[30:33]
	v_mfma_f32_16x16x32_bf16 v[26:29], v[202:205], v[210:213], v[26:29]
	v_mfma_f32_16x16x32_bf16 v[22:25], v[194:197], v[218:221], v[22:25]
	v_mfma_f32_16x16x32_bf16 v[18:21], v[202:205], v[218:221], v[18:21]
	v_mfma_f32_16x16x32_bf16 v[14:17], v[194:197], v[226:229], v[14:17]
	v_mfma_f32_16x16x32_bf16 v[10:13], v[202:205], v[226:229], v[10:13]
	v_mfma_f32_16x16x32_bf16 v[6:9], v[194:197], v[234:237], v[6:9]
	v_mfma_f32_16x16x32_bf16 v[2:5], v[202:205], v[234:237], v[2:5]
	s_barrier
	s_cbranch_scc0 .LBB0_2495
	s_setprio 0
	s_and_b64 vcc, exec, s[36:37]
	s_cbranch_vccz .LBB0_2498
	s_barrier

; #define PG8_STAGE(bufoff, gbase, voff) do { _Pragma("unroll") for (int _i = 0; _i < 2; ++_i) \
;         __builtin_amdgcn_global_load_lds((const unsigned*)((const char*)(gbase) + (voff)[_i]), (PG8_LAS unsigned*)(lds + (bufoff) + ldsw + _i * 8192), 16, 0, 0); } while (0)
; #define PG8_LDA(dst, b, h) do { _Pragma("unroll") for (int m = 0; m < 4; ++m) _Pragma("unroll") for (int k = 0; k < 2; ++k) dst[m][k] = *(const PG8_LAS bf16x8*)(lds + PG8_SA(b, h) + aoff + m * 2048 + k * 1024); } while (0)
; #define PG8_LDB(dst, b, h) do { _Pragma("unroll") for (int n = 0; n < 2; ++n) _Pragma("unroll") for (int k = 0; k < 2; ++k) dst[n][k] = *(const PG8_LAS bf16x8*)(lds + PG8_SB(b, h) + boff + n * 2048 + k * 1024); } while (0)
; #define PG8_WAIT_V(n) asm volatile("s_waitcnt vmcnt(" #n ")" ::: "memory")
; #define PG8_WAIT_L(n) asm volatile("s_waitcnt lgkmcnt(" #n ")" ::: "memory")
; template <class Epi, bool ALIGN_EPI, bool ABLK = false>
; __device__ __forceinline__ void gemm_phase(PG8_LAS unsigned char* lds, const Gemm g, const StaticOrder& S, const Epi& E) {
;     ...
;         const bool has_next = S.next(ui + 1, nxt);
;         const char* nA = has_next ? PG8_ABASE(nxt) : cA; const char* nB = has_next ? PG8_BBASE(nxt) : cB;
;         for (int t = 0; t < nt; t += 2) {
;             const bool last = (t == nt - 2);
;             const char* a1 = cA + (size_t)(t + 1) * kstepA;
;             const char* a2 = last ? nA : cA + (size_t)(t + 2) * kstepA; const char* b2 = last ? nB : cB + (size_t)(t + 2) * kstepB;
;             const char* a3 = a2 + kstepA; const char* b3 = b2 + kstepB;
;             PG8_LDB(B0, 0, 0); PG8_LDB(B1, 0, 1); PG8_SCHED; PG8_LDA(At, 0, 0); PG8_STAGE(PG8_SA(1, 1), a1 + hstepA, voffA);
;             PG8_WAIT_V(8); PG8_WAIT_L(0); PG8_BAR; PG8_MMA(0, 0, At, B0); PG8_MMA(0, 1, At, B1); PG8_BAR; PG8_SCHED;
;             PG8_LDA(At, 0, 1); PG8_STAGE(PG8_SB(0, 0), b2, voffB); PG8_STAGE(PG8_SB(0, 1), b2 + hstepB, voffB); PG8_STAGE(PG8_SA(0, 0), a2, voffA);
;     ...
;         if (!E.keep(cur)) {
; #pragma unroll
;             for (int a = 0; a < 2; ++a)
; #pragma unroll
;                 for (int b = 0; b < 2; ++b)
; #pragma unroll
;                     for (int m = 0; m < 4; ++m)
; #pragma unroll
;                         for (int n = 0; n < 2; ++n) acc[a][b][m][n] = (f32x4){0.f, 0.f, 0.f, 0.f};
;         }
;         cur = nxt; cA = nA; cB = nB; ++ui;
.LBB0_2630:
	s_add_u32 s51, s52, 0x100
	s_addc_u32 s56, s53, 0
	s_add_u32 s52, s54, 0x10000
	v_mov_b32_e32 v2, 0
	s_addc_u32 s53, s55, 0
	s_mov_b32 s57, -2
	v_mov_b32_e32 v3, v2
	v_mov_b32_e32 v4, v2
	v_mov_b32_e32 v5, v2
	v_mov_b32_e32 v6, v2
	v_mov_b32_e32 v7, v2
	v_mov_b32_e32 v8, v2
	v_mov_b32_e32 v9, v2
	v_mov_b32_e32 v18, v2
	v_mov_b32_e32 v19, v2
	v_mov_b32_e32 v20, v2
	v_mov_b32_e32 v21, v2
	v_mov_b32_e32 v22, v2
	v_mov_b32_e32 v23, v2
	v_mov_b32_e32 v24, v2
	v_mov_b32_e32 v25, v2
	v_mov_b32_e32 v34, v2
	v_mov_b32_e32 v35, v2
	v_mov_b32_e32 v36, v2
	v_mov_b32_e32 v37, v2
	v_mov_b32_e32 v38, v2
	v_mov_b32_e32 v39, v2
	v_mov_b32_e32 v40, v2
	v_mov_b32_e32 v41, v2
	v_mov_b32_e32 v50, v2
	v_mov_b32_e32 v51, v2
	v_mov_b32_e32 v52, v2
	v_mov_b32_e32 v53, v2
	v_mov_b32_e32 v54, v2
	v_mov_b32_e32 v55, v2
	v_mov_b32_e32 v56, v2
	v_mov_b32_e32 v57, v2
	v_mov_b32_e32 v10, v2
	v_mov_b32_e32 v11, v2
	v_mov_b32_e32 v12, v2
	v_mov_b32_e32 v13, v2
	v_mov_b32_e32 v14, v2
	v_mov_b32_e32 v15, v2
	v_mov_b32_e32 v16, v2
	v_mov_b32_e32 v17, v2
	v_mov_b32_e32 v26, v2
	v_mov_b32_e32 v27, v2
	v_mov_b32_e32 v28, v2
	v_mov_b32_e32 v29, v2
	v_mov_b32_e32 v30, v2
	v_mov_b32_e32 v31, v2
	v_mov_b32_e32 v32, v2
	v_mov_b32_e32 v33, v2
	v_mov_b32_e32 v42, v2
	v_mov_b32_e32 v43, v2
	v_mov_b32_e32 v44, v2
	v_mov_b32_e32 v45, v2
	v_mov_b32_e32 v46, v2
	v_mov_b32_e32 v47, v2
	v_mov_b32_e32 v48, v2
	v_mov_b32_e32 v49, v2
	v_mov_b32_e32 v58, v2
	v_mov_b32_e32 v59, v2
	v_mov_b32_e32 v60, v2
	v_mov_b32_e32 v61, v2
	v_mov_b32_e32 v62, v2
	v_mov_b32_e32 v63, v2
	v_mov_b32_e32 v64, v2
	v_mov_b32_e32 v65, v2
	v_mov_b32_e32 v66, v2
	v_mov_b32_e32 v67, v2
	v_mov_b32_e32 v68, v2
	v_mov_b32_e32 v69, v2
	v_mov_b32_e32 v70, v2
	v_mov_b32_e32 v71, v2
	v_mov_b32_e32 v72, v2
	v_mov_b32_e32 v73, v2
	v_mov_b32_e32 v82, v2
	v_mov_b32_e32 v83, v2
	v_mov_b32_e32 v84, v2
	v_mov_b32_e32 v85, v2
	v_mov_b32_e32 v86, v2
	v_mov_b32_e32 v87, v2
	v_mov_b32_e32 v88, v2
	v_mov_b32_e32 v89, v2
	v_mov_b32_e32 v98, v2
	v_mov_b32_e32 v99, v2
	v_mov_b32_e32 v100, v2
	v_mov_b32_e32 v101, v2
	v_mov_b32_e32 v102, v2
	v_mov_b32_e32 v103, v2
	v_mov_b32_e32 v104, v2
	v_mov_b32_e32 v105, v2
	v_mov_b32_e32 v114, v2
	v_mov_b32_e32 v115, v2
	v_mov_b32_e32 v116, v2
	v_mov_b32_e32 v117, v2
	v_mov_b32_e32 v118, v2
	v_mov_b32_e32 v119, v2
	v_mov_b32_e32 v120, v2
	v_mov_b32_e32 v121, v2
	v_mov_b32_e32 v74, v2
	v_mov_b32_e32 v75, v2
	v_mov_b32_e32 v76, v2
	v_mov_b32_e32 v77, v2
	v_mov_b32_e32 v78, v2
	v_mov_b32_e32 v79, v2
	v_mov_b32_e32 v80, v2
	v_mov_b32_e32 v81, v2
	v_mov_b32_e32 v90, v2
	v_mov_b32_e32 v91, v2
	v_mov_b32_e32 v92, v2
	v_mov_b32_e32 v93, v2
	v_mov_b32_e32 v94, v2
	v_mov_b32_e32 v95, v2
	v_mov_b32_e32 v96, v2
	v_mov_b32_e32 v97, v2
	v_mov_b32_e32 v106, v2
	v_mov_b32_e32 v107, v2
	v_mov_b32_e32 v108, v2
	v_mov_b32_e32 v109, v2
	v_mov_b32_e32 v110, v2
	v_mov_b32_e32 v111, v2
	v_mov_b32_e32 v112, v2
	v_mov_b32_e32 v113, v2
	v_mov_b32_e32 v122, v2
	v_mov_b32_e32 v123, v2
	v_mov_b32_e32 v124, v2
	v_mov_b32_e32 v125, v2
	v_mov_b32_e32 v126, v2
	v_mov_b32_e32 v127, v2
	v_mov_b32_e32 v128, v2
	v_mov_b32_e32 v129, v2
	s_setprio 0
	v_readfirstlane_b32 s101, v0
	s_nop 3
	s_bfe_u32 s101, s101, 0x40006
	s_cmp_ge_u32 s101, 4
	s_cbranch_scc0 .Lprio_2631
	s_setprio 1
.Lprio_2631:
.LBB0_2631:
	ds_read_b128 v[130:133], v234
	ds_read_b128 v[134:137], v234 offset:1024
	ds_read_b128 v[138:141], v234 offset:2048
	ds_read_b128 v[142:145], v234 offset:3072
	ds_read_b128 v[146:149], v235
	ds_read_b128 v[150:153], v235 offset:1024
	ds_read_b128 v[154:157], v235 offset:2048
	ds_read_b128 v[158:161], v235 offset:3072
	s_cmp_eq_u32 s57, 40
	s_cselect_b32 s81, s13, s53
	s_cselect_b32 s80, s12, s52
	s_cselect_b32 s55, s49, s56
	s_cselect_b32 s54, s48, s51
	v_lshl_add_u64 v[248:249], s[52:53], 0, v[186:187]
	v_lshl_add_u64 v[250:251], v[248:249], 0, s[44:45]
	s_add_i32 m0, s62, 0xc000
	ds_read_b128 v[162:165], v236
	ds_read_b128 v[166:169], v236 offset:1024
	ds_read_b128 v[170:173], v236 offset:2048
	ds_read_b128 v[174:177], v236 offset:3072
	ds_read_b128 v[178:181], v236 offset:4096
	ds_read_b128 v[182:185], v236 offset:5120
	ds_read_b128 v[240:243], v236 offset:6144
	ds_read_b128 v[244:247], v236 offset:7168
	global_load_lds_dwordx4 v[250:251], off
	v_lshl_add_u64 v[248:249], v[248:249], 0, s[46:47]
	s_add_i32 m0, s62, 0xe000
	s_nop 0
	global_load_lds_dwordx4 v[248:249], off
	s_waitcnt vmcnt(8)
	s_waitcnt lgkmcnt(0)
	s_barrier
	s_waitcnt lgkmcnt(0)
	v_mfma_f32_16x16x32_bf16 v[126:129], v[130:133], v[162:165], v[126:129]
	v_mfma_f32_16x16x32_bf16 v[122:125], v[138:141], v[162:165], v[122:125]
	v_mfma_f32_16x16x32_bf16 v[110:113], v[130:133], v[170:173], v[110:113]
	v_mfma_f32_16x16x32_bf16 v[106:109], v[138:141], v[170:173], v[106:109]
	v_mfma_f32_16x16x32_bf16 v[94:97], v[130:133], v[178:181], v[94:97]
	v_mfma_f32_16x16x32_bf16 v[90:93], v[138:141], v[178:181], v[90:93]
	v_mfma_f32_16x16x32_bf16 v[78:81], v[130:133], v[240:243], v[78:81]
	v_mfma_f32_16x16x32_bf16 v[74:77], v[138:141], v[240:243], v[74:77]
	v_mfma_f32_16x16x32_bf16 v[126:129], v[134:137], v[166:169], v[126:129]
	v_mfma_f32_16x16x32_bf16 v[122:125], v[142:145], v[166:169], v[122:125]
	v_mfma_f32_16x16x32_bf16 v[110:113], v[134:137], v[174:177], v[110:113]
	v_mfma_f32_16x16x32_bf16 v[106:109], v[142:145], v[174:177], v[106:109]
	v_mfma_f32_16x16x32_bf16 v[94:97], v[134:137], v[182:185], v[94:97]
	v_mfma_f32_16x16x32_bf16 v[90:93], v[142:145], v[182:185], v[90:93]
	v_mfma_f32_16x16x32_bf16 v[78:81], v[134:137], v[244:247], v[78:81]
	v_mfma_f32_16x16x32_bf16 v[74:77], v[142:145], v[244:247], v[74:77]
	v_mfma_f32_16x16x32_bf16 v[118:121], v[146:149], v[162:165], v[118:121]
	s_add_i32 s79, s74, s61
	v_mfma_f32_16x16x32_bf16 v[114:117], v[154:157], v[162:165], v[114:117]
	s_mov_b32 m0, s79
	v_mfma_f32_16x16x32_bf16 v[102:105], v[146:149], v[170:173], v[102:105]
	v_mfma_f32_16x16x32_bf16 v[98:101], v[154:157], v[170:173], v[98:101]
	v_mfma_f32_16x16x32_bf16 v[86:89], v[146:149], v[178:181], v[86:89]
	v_mfma_f32_16x16x32_bf16 v[82:85], v[154:157], v[178:181], v[82:85]
	v_mfma_f32_16x16x32_bf16 v[70:73], v[146:149], v[240:243], v[70:73]
	v_mfma_f32_16x16x32_bf16 v[66:69], v[154:157], v[240:243], v[66:69]
	v_mfma_f32_16x16x32_bf16 v[118:121], v[150:153], v[166:169], v[118:121]
	v_mfma_f32_16x16x32_bf16 v[114:117], v[158:161], v[166:169], v[114:117]
	v_mfma_f32_16x16x32_bf16 v[102:105], v[150:153], v[174:177], v[102:105]
	v_mfma_f32_16x16x32_bf16 v[98:101], v[158:161], v[174:177], v[98:101]
	v_mfma_f32_16x16x32_bf16 v[86:89], v[150:153], v[182:185], v[86:89]
	v_mfma_f32_16x16x32_bf16 v[82:85], v[158:161], v[182:185], v[82:85]
	v_mfma_f32_16x16x32_bf16 v[70:73], v[150:153], v[244:247], v[70:73]
	v_mfma_f32_16x16x32_bf16 v[66:69], v[158:161], v[244:247], v[66:69]
	s_barrier
; #define PG8_STAGE(bufoff, gbase, voff) do { _Pragma("unroll") for (int _i = 0; _i < 2; ++_i) \
;         __builtin_amdgcn_global_load_lds((const unsigned*)((const char*)(gbase) + (voff)[_i]), (PG8_LAS unsigned*)(lds + (bufoff) + ldsw + _i * 8192), 16, 0, 0); } while (0)
; #define PG8_LDA(dst, b, h) do { _Pragma("unroll") for (int m = 0; m < 4; ++m) _Pragma("unroll") for (int k = 0; k < 2; ++k) dst[m][k] = *(const PG8_LAS bf16x8*)(lds + PG8_SA(b, h) + aoff + m * 2048 + k * 1024); } while (0)
; #define PG8_LDB(dst, b, h) do { _Pragma("unroll") for (int n = 0; n < 2; ++n) _Pragma("unroll") for (int k = 0; k < 2; ++k) dst[n][k] = *(const PG8_LAS bf16x8*)(lds + PG8_SB(b, h) + boff + n * 2048 + k * 1024); } while (0)
; #define PG8_MMA(ai, bj, At, Bt) do { __builtin_amdgcn_s_setprio(1); _Pragma("unroll") for (int m = 0; m < 4; ++m) _Pragma("unroll") for (int n = 0; n < 2; ++n) _Pragma("unroll") for (int k = 0; k < 2; ++k) \
;         acc[ai][bj][m][n] = __builtin_amdgcn_mfma_f32_16x16x32_bf16(Bt[n][k], At[m][k], acc[ai][bj][m][n], 0, 0, 0); __builtin_amdgcn_s_setprio(0); } while (0)
; #define PG8_WAIT_V(n) asm volatile("s_waitcnt vmcnt(" #n ")" ::: "memory")
; #define PG8_WAIT_L(n) asm volatile("s_waitcnt lgkmcnt(" #n ")" ::: "memory")
; #define PG8_BAR __builtin_amdgcn_s_barrier()
; #define PG8_SCHED __builtin_amdgcn_sched_barrier(0)
; template <class Epi, bool ALIGN_EPI, bool ABLK = false>
; __device__ __forceinline__ void gemm_phase(PG8_LAS unsigned char* lds, const Gemm g, const StaticOrder& S, const Epi& E) {
;     ...
;             PG8_LDA(At, 0, 1); PG8_STAGE(PG8_SB(0, 0), b2, voffB); PG8_STAGE(PG8_SB(0, 1), b2 + hstepB, voffB); PG8_STAGE(PG8_SA(0, 0), a2, voffA);
;             PG8_WAIT_V(8); PG8_WAIT_L(0); PG8_BAR; PG8_MMA(1, 0, At, B0); PG8_MMA(1, 1, At, B1); PG8_BAR; PG8_SCHED;
;             PG8_LDB(B0, 1, 0); PG8_LDB(B1, 1, 1); PG8_SCHED; PG8_LDA(At, 1, 0); PG8_STAGE(PG8_SA(0, 1), a2 + hstepA, voffA);
	v_lshl_add_u64 v[248:249], s[54:55], 0, v[188:189]
	ds_read_b128 v[162:165], v236 offset:16384
	ds_read_b128 v[166:169], v236 offset:17408
	ds_read_b128 v[170:173], v236 offset:18432
	ds_read_b128 v[174:177], v236 offset:19456
	ds_read_b128 v[178:181], v236 offset:20480
	ds_read_b128 v[182:185], v236 offset:21504
	ds_read_b128 v[240:243], v236 offset:22528
	ds_read_b128 v[244:247], v236 offset:23552
	global_load_lds_dwordx4 v[248:249], off
	s_add_i32 m0, s79, 0x2000
	s_add_u32 s82, s54, 0xb0000
	v_lshl_add_u64 v[250:251], s[54:55], 0, v[190:191]
	s_addc_u32 s83, s55, 0
	s_add_i32 s79, s75, s61
	global_load_lds_dwordx4 v[250:251], off
	v_lshl_add_u64 v[252:253], s[82:83], 0, v[188:189]
	s_mov_b32 m0, s79
	s_nop 0
	global_load_lds_dwordx4 v[252:253], off
	v_lshl_add_u64 v[252:253], s[82:83], 0, v[190:191]
	s_add_i32 m0, s79, 0x2000
	s_nop 0
	global_load_lds_dwordx4 v[252:253], off
	v_lshl_add_u64 v[252:253], s[80:81], 0, v[186:187]
	s_mov_b32 m0, s62
	v_lshl_add_u64 v[208:209], v[252:253], 0, s[22:23]
	global_load_lds_dwordx4 v[252:253], off
	s_mov_b32 m0, s63
	s_nop 0
	global_load_lds_dwordx4 v[208:209], off
	s_waitcnt vmcnt(8)
	s_waitcnt lgkmcnt(0)
	s_barrier
	s_waitcnt lgkmcnt(0)
	v_mfma_f32_16x16x32_bf16 v[62:65], v[130:133], v[162:165], v[62:65]
	v_mfma_f32_16x16x32_bf16 v[58:61], v[138:141], v[162:165], v[58:61]
	v_mfma_f32_16x16x32_bf16 v[46:49], v[130:133], v[170:173], v[46:49]
	v_mfma_f32_16x16x32_bf16 v[42:45], v[138:141], v[170:173], v[42:45]
	v_mfma_f32_16x16x32_bf16 v[30:33], v[130:133], v[178:181], v[30:33]
	v_mfma_f32_16x16x32_bf16 v[26:29], v[138:141], v[178:181], v[26:29]
	v_mfma_f32_16x16x32_bf16 v[14:17], v[130:133], v[240:243], v[14:17]
	v_mfma_f32_16x16x32_bf16 v[10:13], v[138:141], v[240:243], v[10:13]
	v_mfma_f32_16x16x32_bf16 v[62:65], v[134:137], v[166:169], v[62:65]
	v_mfma_f32_16x16x32_bf16 v[58:61], v[142:145], v[166:169], v[58:61]
	v_mfma_f32_16x16x32_bf16 v[46:49], v[134:137], v[174:177], v[46:49]
	v_mfma_f32_16x16x32_bf16 v[42:45], v[142:145], v[174:177], v[42:45]
	v_mfma_f32_16x16x32_bf16 v[30:33], v[134:137], v[182:185], v[30:33]
	v_mfma_f32_16x16x32_bf16 v[26:29], v[142:145], v[182:185], v[26:29]
	v_mfma_f32_16x16x32_bf16 v[14:17], v[134:137], v[244:247], v[14:17]
	v_mfma_f32_16x16x32_bf16 v[10:13], v[142:145], v[244:247], v[10:13]
	v_mfma_f32_16x16x32_bf16 v[54:57], v[146:149], v[162:165], v[54:57]
	s_add_i32 s79, 0, 0x18000
	v_mfma_f32_16x16x32_bf16 v[50:53], v[154:157], v[162:165], v[50:53]
	s_add_i32 s80, 0, 0x1c000
	v_mfma_f32_16x16x32_bf16 v[38:41], v[146:149], v[170:173], v[38:41]
	v_mfma_f32_16x16x32_bf16 v[34:37], v[154:157], v[170:173], v[34:37]
	v_mfma_f32_16x16x32_bf16 v[22:25], v[146:149], v[178:181], v[22:25]
	v_mfma_f32_16x16x32_bf16 v[18:21], v[154:157], v[178:181], v[18:21]
	v_mfma_f32_16x16x32_bf16 v[6:9], v[146:149], v[240:243], v[6:9]
	v_mfma_f32_16x16x32_bf16 v[2:5], v[154:157], v[240:243], v[2:5]
	v_mfma_f32_16x16x32_bf16 v[54:57], v[150:153], v[166:169], v[54:57]
	v_mfma_f32_16x16x32_bf16 v[50:53], v[158:161], v[166:169], v[50:53]
	v_mfma_f32_16x16x32_bf16 v[38:41], v[150:153], v[174:177], v[38:41]
	v_mfma_f32_16x16x32_bf16 v[34:37], v[158:161], v[174:177], v[34:37]
	v_mfma_f32_16x16x32_bf16 v[22:25], v[150:153], v[182:185], v[22:25]
	v_mfma_f32_16x16x32_bf16 v[18:21], v[158:161], v[182:185], v[18:21]
	v_mfma_f32_16x16x32_bf16 v[6:9], v[150:153], v[244:247], v[6:9]
	v_mfma_f32_16x16x32_bf16 v[2:5], v[158:161], v[244:247], v[2:5]
	s_barrier
	v_add_u32_e32 v142, s79, v215
	v_add_u32_e32 v158, s80, v215
	ds_read_b128 v[130:133], v142
	ds_read_b128 v[134:137], v142 offset:1024
	ds_read_b128 v[138:141], v142 offset:2048
	ds_read_b128 v[142:145], v142 offset:3072
	ds_read_b128 v[146:149], v158
	ds_read_b128 v[150:153], v158 offset:1024
	ds_read_b128 v[154:157], v158 offset:2048
	ds_read_b128 v[158:161], v158 offset:3072
	s_mov_b32 m0, s64
	v_lshl_add_u64 v[208:209], v[252:253], 0, s[24:25]
	ds_read_b128 v[162:165], v236 offset:32768
	ds_read_b128 v[166:169], v236 offset:33792
	ds_read_b128 v[170:173], v236 offset:34816
	ds_read_b128 v[174:177], v236 offset:35840
	ds_read_b128 v[178:181], v236 offset:36864
	ds_read_b128 v[182:185], v236 offset:37888
	ds_read_b128 v[240:243], v236 offset:38912
	ds_read_b128 v[244:247], v236 offset:39936
	global_load_lds_dwordx4 v[208:209], off
	v_lshl_add_u64 v[208:209], v[252:253], 0, s[26:27]
	s_mov_b32 m0, s65
	s_nop 0
	global_load_lds_dwordx4 v[208:209], off
	s_waitcnt vmcnt(8)
	s_waitcnt lgkmcnt(0)
	s_barrier
; #define PG8_STAGE(bufoff, gbase, voff) do { _Pragma("unroll") for (int _i = 0; _i < 2; ++_i) \
;         __builtin_amdgcn_global_load_lds((const unsigned*)((const char*)(gbase) + (voff)[_i]), (PG8_LAS unsigned*)(lds + (bufoff) + ldsw + _i * 8192), 16, 0, 0); } while (0)
; #define PG8_LDA(dst, b, h) do { _Pragma("unroll") for (int m = 0; m < 4; ++m) _Pragma("unroll") for (int k = 0; k < 2; ++k) dst[m][k] = *(const PG8_LAS bf16x8*)(lds + PG8_SA(b, h) + aoff + m * 2048 + k * 1024); } while (0)
; #define PG8_LDB(dst, b, h) do { _Pragma("unroll") for (int n = 0; n < 2; ++n) _Pragma("unroll") for (int k = 0; k < 2; ++k) dst[n][k] = *(const PG8_LAS bf16x8*)(lds + PG8_SB(b, h) + boff + n * 2048 + k * 1024); } while (0)
; #define PG8_MMA(ai, bj, At, Bt) do { __builtin_amdgcn_s_setprio(1); _Pragma("unroll") for (int m = 0; m < 4; ++m) _Pragma("unroll") for (int n = 0; n < 2; ++n) _Pragma("unroll") for (int k = 0; k < 2; ++k) \
;         acc[ai][bj][m][n] = __builtin_amdgcn_mfma_f32_16x16x32_bf16(Bt[n][k], At[m][k], acc[ai][bj][m][n], 0, 0, 0); __builtin_amdgcn_s_setprio(0); } while (0)
; #define PG8_WAIT_V(n) asm volatile("s_waitcnt vmcnt(" #n ")" ::: "memory")
; #define PG8_WAIT_L(n) asm volatile("s_waitcnt lgkmcnt(" #n ")" ::: "memory")
; #define PG8_BAR __builtin_amdgcn_s_barrier()
; #define PG8_SCHED __builtin_amdgcn_sched_barrier(0)
; template <class Epi, bool ALIGN_EPI, bool ABLK = false>
; __device__ __forceinline__ void gemm_phase(PG8_LAS unsigned char* lds, const Gemm g, const StaticOrder& S, const Epi& E) {
;     ...
;             PG8_LDB(B0, 1, 0); PG8_LDB(B1, 1, 1); PG8_SCHED; PG8_LDA(At, 1, 0); PG8_STAGE(PG8_SA(0, 1), a2 + hstepA, voffA);
;             PG8_WAIT_V(8); PG8_WAIT_L(0); PG8_BAR; PG8_MMA(0, 0, At, B0); PG8_MMA(0, 1, At, B1); PG8_BAR; PG8_SCHED;
;             PG8_LDA(At, 1, 1); PG8_STAGE(PG8_SB(1, 0), b3, voffB); PG8_STAGE(PG8_SB(1, 1), b3 + hstepB, voffB); PG8_STAGE(PG8_SA(1, 0), a3, voffA);
;             PG8_WAIT_V(8); PG8_WAIT_L(0); PG8_BAR; PG8_MMA(1, 0, At, B0); PG8_MMA(1, 1, At, B1); PG8_BAR; PG8_SCHED;
	s_waitcnt lgkmcnt(0)
	v_mfma_f32_16x16x32_bf16 v[126:129], v[130:133], v[162:165], v[126:129]
	v_mfma_f32_16x16x32_bf16 v[122:125], v[138:141], v[162:165], v[122:125]
	v_mfma_f32_16x16x32_bf16 v[110:113], v[130:133], v[170:173], v[110:113]
	v_mfma_f32_16x16x32_bf16 v[106:109], v[138:141], v[170:173], v[106:109]
	v_mfma_f32_16x16x32_bf16 v[94:97], v[130:133], v[178:181], v[94:97]
	v_mfma_f32_16x16x32_bf16 v[90:93], v[138:141], v[178:181], v[90:93]
	v_mfma_f32_16x16x32_bf16 v[78:81], v[130:133], v[240:243], v[78:81]
	v_mfma_f32_16x16x32_bf16 v[74:77], v[138:141], v[240:243], v[74:77]
	v_mfma_f32_16x16x32_bf16 v[126:129], v[134:137], v[166:169], v[126:129]
	v_mfma_f32_16x16x32_bf16 v[122:125], v[142:145], v[166:169], v[122:125]
	v_mfma_f32_16x16x32_bf16 v[110:113], v[134:137], v[174:177], v[110:113]
	v_mfma_f32_16x16x32_bf16 v[106:109], v[142:145], v[174:177], v[106:109]
	v_mfma_f32_16x16x32_bf16 v[94:97], v[134:137], v[182:185], v[94:97]
	v_mfma_f32_16x16x32_bf16 v[90:93], v[142:145], v[182:185], v[90:93]
	v_mfma_f32_16x16x32_bf16 v[78:81], v[134:137], v[244:247], v[78:81]
	v_mfma_f32_16x16x32_bf16 v[74:77], v[142:145], v[244:247], v[74:77]
	v_mfma_f32_16x16x32_bf16 v[118:121], v[146:149], v[162:165], v[118:121]
	s_add_i32 s79, s79, s61
	v_mfma_f32_16x16x32_bf16 v[114:117], v[154:157], v[162:165], v[114:117]
	s_mov_b32 m0, s79
	v_mfma_f32_16x16x32_bf16 v[102:105], v[146:149], v[170:173], v[102:105]
	v_mfma_f32_16x16x32_bf16 v[98:101], v[154:157], v[170:173], v[98:101]
	v_mfma_f32_16x16x32_bf16 v[86:89], v[146:149], v[178:181], v[86:89]
	v_mfma_f32_16x16x32_bf16 v[82:85], v[154:157], v[178:181], v[82:85]
	v_mfma_f32_16x16x32_bf16 v[70:73], v[146:149], v[240:243], v[70:73]
	v_mfma_f32_16x16x32_bf16 v[66:69], v[154:157], v[240:243], v[66:69]
	v_mfma_f32_16x16x32_bf16 v[118:121], v[150:153], v[166:169], v[118:121]
	v_mfma_f32_16x16x32_bf16 v[114:117], v[158:161], v[166:169], v[114:117]
	v_mfma_f32_16x16x32_bf16 v[102:105], v[150:153], v[174:177], v[102:105]
	v_mfma_f32_16x16x32_bf16 v[98:101], v[158:161], v[174:177], v[98:101]
	v_mfma_f32_16x16x32_bf16 v[86:89], v[150:153], v[182:185], v[86:89]
	v_mfma_f32_16x16x32_bf16 v[82:85], v[158:161], v[182:185], v[82:85]
	v_mfma_f32_16x16x32_bf16 v[70:73], v[150:153], v[244:247], v[70:73]
	v_mfma_f32_16x16x32_bf16 v[66:69], v[158:161], v[244:247], v[66:69]
	s_barrier
	v_lshl_add_u64 v[208:209], v[248:249], 0, s[34:35]
	ds_read_b128 v[162:165], v236 offset:49152
	ds_read_b128 v[166:169], v236 offset:50176
	ds_read_b128 v[170:173], v236 offset:51200
	ds_read_b128 v[174:177], v236 offset:52224
	ds_read_b128 v[178:181], v236 offset:53248
	ds_read_b128 v[182:185], v236 offset:54272
	ds_read_b128 v[240:243], v236 offset:55296
	ds_read_b128 v[244:247], v236 offset:56320
	global_load_lds_dwordx4 v[208:209], off
	s_add_i32 m0, s79, 0x2000
	s_add_u32 s54, s54, 0xb0080
	v_lshl_add_u64 v[208:209], v[250:251], 0, s[34:35]
	s_addc_u32 s55, s55, 0
	s_add_i32 s79, s80, s61
	global_load_lds_dwordx4 v[208:209], off
	v_lshl_add_u64 v[208:209], s[54:55], 0, v[188:189]
	s_mov_b32 m0, s79
	s_nop 0
	global_load_lds_dwordx4 v[208:209], off
	v_lshl_add_u64 v[208:209], s[54:55], 0, v[190:191]
	s_add_i32 m0, s79, 0x2000
	s_nop 0
	global_load_lds_dwordx4 v[208:209], off
	v_lshl_add_u64 v[208:209], v[252:253], 0, s[36:37]
	s_mov_b32 m0, s69
	s_nop 0
	global_load_lds_dwordx4 v[208:209], off
	v_lshl_add_u64 v[208:209], v[252:253], 0, s[38:39]
	s_mov_b32 m0, s70
	s_nop 0
	global_load_lds_dwordx4 v[208:209], off
	s_waitcnt vmcnt(8)
	s_waitcnt lgkmcnt(0)
	s_barrier
	s_waitcnt lgkmcnt(0)
	v_mfma_f32_16x16x32_bf16 v[62:65], v[130:133], v[162:165], v[62:65]
	v_mfma_f32_16x16x32_bf16 v[58:61], v[138:141], v[162:165], v[58:61]
	v_mfma_f32_16x16x32_bf16 v[46:49], v[130:133], v[170:173], v[46:49]
	v_mfma_f32_16x16x32_bf16 v[42:45], v[138:141], v[170:173], v[42:45]
	v_mfma_f32_16x16x32_bf16 v[30:33], v[130:133], v[178:181], v[30:33]
	v_mfma_f32_16x16x32_bf16 v[26:29], v[138:141], v[178:181], v[26:29]
	v_mfma_f32_16x16x32_bf16 v[14:17], v[130:133], v[240:243], v[14:17]
	v_mfma_f32_16x16x32_bf16 v[10:13], v[138:141], v[240:243], v[10:13]
	v_mfma_f32_16x16x32_bf16 v[62:65], v[134:137], v[166:169], v[62:65]
	v_mfma_f32_16x16x32_bf16 v[58:61], v[142:145], v[166:169], v[58:61]
	v_mfma_f32_16x16x32_bf16 v[46:49], v[134:137], v[174:177], v[46:49]
	v_mfma_f32_16x16x32_bf16 v[42:45], v[142:145], v[174:177], v[42:45]
	v_mfma_f32_16x16x32_bf16 v[30:33], v[134:137], v[182:185], v[30:33]
	v_mfma_f32_16x16x32_bf16 v[26:29], v[142:145], v[182:185], v[26:29]
	v_mfma_f32_16x16x32_bf16 v[14:17], v[134:137], v[244:247], v[14:17]
	v_mfma_f32_16x16x32_bf16 v[10:13], v[142:145], v[244:247], v[10:13]
	v_mfma_f32_16x16x32_bf16 v[54:57], v[146:149], v[162:165], v[54:57]
	s_add_i32 s57, s57, 2
	v_mfma_f32_16x16x32_bf16 v[50:53], v[154:157], v[162:165], v[50:53]
	s_add_u32 s51, s51, 0x100
	v_mfma_f32_16x16x32_bf16 v[38:41], v[146:149], v[170:173], v[38:41]
	s_addc_u32 s56, s56, 0
	v_mfma_f32_16x16x32_bf16 v[34:37], v[154:157], v[170:173], v[34:37]
	s_add_u32 s52, s52, 0x10000
	v_mfma_f32_16x16x32_bf16 v[22:25], v[146:149], v[178:181], v[22:25]
	s_addc_u32 s53, s53, 0
	v_mfma_f32_16x16x32_bf16 v[18:21], v[154:157], v[178:181], v[18:21]
	s_cmp_gt_u32 s57, 41
	v_mfma_f32_16x16x32_bf16 v[6:9], v[146:149], v[240:243], v[6:9]
	v_mfma_f32_16x16x32_bf16 v[2:5], v[154:157], v[240:243], v[2:5]
	v_mfma_f32_16x16x32_bf16 v[54:57], v[150:153], v[166:169], v[54:57]
	v_mfma_f32_16x16x32_bf16 v[50:53], v[158:161], v[166:169], v[50:53]
	v_mfma_f32_16x16x32_bf16 v[38:41], v[150:153], v[174:177], v[38:41]
	v_mfma_f32_16x16x32_bf16 v[34:37], v[158:161], v[174:177], v[34:37]
	v_mfma_f32_16x16x32_bf16 v[22:25], v[150:153], v[182:185], v[22:25]
	v_mfma_f32_16x16x32_bf16 v[18:21], v[158:161], v[182:185], v[18:21]
	v_mfma_f32_16x16x32_bf16 v[6:9], v[150:153], v[244:247], v[6:9]
	v_mfma_f32_16x16x32_bf16 v[2:5], v[158:161], v[244:247], v[2:5]
	s_barrier
	s_cbranch_scc0 .LBB0_2631
	s_setprio 0
	s_and_b64 vcc, exec, s[40:41]
	s_cbranch_vccz .LBB0_2634
	s_barrier
